# attention x6 loops: LDS-DMA issue blocks without m0 pads (direct m0 immediates; address adds, row-sum adds and first LDS reads fill the m0 wait state)
# baseline (speedup 1.0000x reference)
.Lst0_u6_loop:
	s_mov_b32 m0, s58
	ds_read_b128 v[96:99], v205 offset:16384
	global_load_lds_dwordx4 v198, s[98:99]
	s_add_i32 m0, s58, 0x400
	ds_read_b128 v[100:103], v205 offset:24576
	global_load_lds_dwordx4 v194, s[98:99]
	s_add_i32 m0, s58, 0x14000
	s_nop 0
	global_load_lds_dwordx4 v196, s[100:101]
	s_add_i32 m0, s58, 0x14400
	s_nop 0
	global_load_lds_dwordx4 v192, s[100:101]
	s_waitcnt lgkmcnt(0)
	v_mfma_f32_32x32x16_bf16 v[112:127], v[96:99], v[160:163], 0
	ds_read_b128 v[128:131], v211 offset:16384
	ds_read_b128 v[132:135], v211 offset:24576
	ds_read_b128 v[136:139], v212 offset:16384
	v_exp_f32_e32 v140, v48
	v_exp_f32_e32 v141, v49
	v_exp_f32_e32 v142, v50
	v_exp_f32_e32 v143, v51
	ds_read_b128 v[48:51], v212 offset:24576
	v_mfma_f32_32x32x16_bf16 v[96:111], v[100:103], v[160:163], 0
	v_exp_f32_e32 v144, v52
	v_exp_f32_e32 v145, v53
	v_exp_f32_e32 v146, v54
	v_exp_f32_e32 v147, v55
	s_waitcnt lgkmcnt(0)
	v_mfma_f32_32x32x16_bf16 v[112:127], v[128:131], v[164:167], v[112:127]
	ds_read_b128 v[52:55], v213 offset:16384
	v_exp_f32_e32 v148, v56
	v_exp_f32_e32 v149, v57
	v_exp_f32_e32 v150, v58
	v_exp_f32_e32 v151, v59
	v_mfma_f32_32x32x16_bf16 v[96:111], v[132:135], v[164:167], v[96:111]
	ds_read_b128 v[56:59], v213 offset:24576
	v_exp_f32_e32 v128, v60
	v_exp_f32_e32 v129, v61
	v_exp_f32_e32 v130, v62
	v_exp_f32_e32 v131, v63
	v_mfma_f32_32x32x16_bf16 v[112:127], v[136:139], v[168:171], v[112:127]
	ds_read_b128 v[60:63], v206 offset:49152
	v_exp_f32_e32 v132, v32
	v_exp_f32_e32 v133, v33
	v_exp_f32_e32 v134, v34
	v_exp_f32_e32 v135, v35
	v_mfma_f32_32x32x16_bf16 v[96:111], v[48:51], v[168:171], v[96:111]
	ds_read_b128 v[32:35], v206 offset:53248
	v_exp_f32_e32 v136, v36
	v_exp_f32_e32 v137, v37
	v_exp_f32_e32 v138, v38
	v_exp_f32_e32 v139, v39
	s_waitcnt lgkmcnt(0)
	v_mfma_f32_32x32x16_bf16 v[112:127], v[52:55], v[172:175], v[112:127]
	ds_read_b128 v[36:39], v206 offset:57344
	v_exp_f32_e32 v152, v40
	v_exp_f32_e32 v153, v41
	v_exp_f32_e32 v154, v42
	v_exp_f32_e32 v155, v43
	v_mfma_f32_32x32x16_bf16 v[96:111], v[56:59], v[172:175], v[96:111]
	ds_read_b128 v[40:43], v206 offset:61440
	v_exp_f32_e32 v156, v44
	v_exp_f32_e32 v157, v45
	v_exp_f32_e32 v158, v46
	v_exp_f32_e32 v159, v47
	v_cvt_pk_bf16_f32 v44, v140, v141
	v_cvt_pk_bf16_f32 v45, v142, v143
	v_cvt_pk_bf16_f32 v46, v144, v145
	v_cvt_pk_bf16_f32 v47, v146, v147
	s_nop 1
	v_mfma_f32_32x32x16_bf16 v[80:95], v[60:63], v[44:47], v[80:95]
	ds_read_b128 v[48:51], v207 offset:49152
	v_cvt_pk_bf16_f32 v52, v148, v149
	v_cvt_pk_bf16_f32 v53, v150, v151
	v_cvt_pk_bf16_f32 v54, v128, v129
	v_cvt_pk_bf16_f32 v55, v130, v131
	v_mfma_f32_32x32x16_bf16 v[64:79], v[32:35], v[44:47], v[64:79]
	ds_read_b128 v[56:59], v207 offset:53248
	v_pk_add_f32 v[62:63], v[146:147], v[142:143]
	v_pk_add_f32 v[60:61], v[144:145], v[140:141]
	s_waitcnt lgkmcnt(0)
	v_mfma_f32_32x32x16_bf16 v[16:31], v[36:39], v[44:47], v[16:31]
	ds_read_b128 v[32:35], v207 offset:57344
	v_add_f32_e64 v62, v150, v62
	v_add_f32_e64 v63, v151, v63
	v_add_f32_e64 v60, v148, v60
	v_add_f32_e64 v61, v149, v61
	v_pk_add_f32 v[62:63], v[130:131], v[62:63]
	v_pk_add_f32 v[60:61], v[128:129], v[60:61]
	v_mfma_f32_32x32x16_bf16 v[0:15], v[40:43], v[44:47], v[0:15]
	ds_read_b128 v[36:39], v207 offset:61440
	v_mfma_f32_32x32x16_bf16 v[80:95], v[48:51], v[52:55], v[80:95]
	ds_read_b128 v[40:43], v208 offset:49152
	v_cvt_pk_bf16_f32 v44, v132, v133
	v_cvt_pk_bf16_f32 v45, v134, v135
	v_cvt_pk_bf16_f32 v46, v136, v137
	v_cvt_pk_bf16_f32 v47, v138, v139
	v_mfma_f32_32x32x16_bf16 v[64:79], v[56:59], v[52:55], v[64:79]
	ds_read_b128 v[48:51], v208 offset:53248
	v_add_f32_e64 v62, v134, v62
	v_add_f32_e64 v63, v135, v63
	v_add_f32_e64 v60, v132, v60
	v_add_f32_e64 v61, v133, v61
	v_pk_add_f32 v[62:63], v[138:139], v[62:63]
	v_pk_add_f32 v[60:61], v[136:137], v[60:61]
	s_waitcnt lgkmcnt(0)
	v_mfma_f32_32x32x16_bf16 v[16:31], v[32:35], v[52:55], v[16:31]
	ds_read_b128 v[56:59], v208 offset:57344
	v_add_f32_e64 v62, v154, v62
	v_add_f32_e64 v63, v155, v63
	v_add_f32_e64 v60, v152, v60
	v_add_f32_e64 v61, v153, v61
	v_pk_add_f32 v[130:131], v[158:159], v[62:63]
	v_pk_add_f32 v[128:129], v[156:157], v[60:61]
	v_mfma_f32_32x32x16_bf16 v[0:15], v[36:39], v[52:55], v[0:15]
	ds_read_b128 v[32:35], v208 offset:61440
	v_mfma_f32_32x32x16_bf16 v[80:95], v[40:43], v[44:47], v[80:95]
	ds_read_b128 v[36:39], v209 offset:49152
	v_cvt_pk_bf16_f32 v52, v152, v153
	v_cvt_pk_bf16_f32 v53, v154, v155
	v_cvt_pk_bf16_f32 v54, v156, v157
	v_cvt_pk_bf16_f32 v55, v158, v159
	v_mfma_f32_32x32x16_bf16 v[64:79], v[48:51], v[44:47], v[64:79]
	ds_read_b128 v[40:43], v209 offset:53248
	s_waitcnt lgkmcnt(0)
	v_mfma_f32_32x32x16_bf16 v[16:31], v[56:59], v[44:47], v[16:31]
	ds_read_b128 v[48:51], v209 offset:57344
	v_mfma_f32_32x32x16_bf16 v[0:15], v[32:35], v[44:47], v[0:15]
	ds_read_b128 v[56:59], v209 offset:61440
	v_mfma_f32_32x32x16_bf16 v[80:95], v[36:39], v[52:55], v[80:95]
	v_mfma_f32_32x32x16_bf16 v[64:79], v[40:43], v[52:55], v[64:79]
	s_waitcnt lgkmcnt(0)
	v_mfma_f32_32x32x16_bf16 v[16:31], v[48:51], v[52:55], v[16:31]
	v_mfma_f32_32x32x16_bf16 v[0:15], v[56:59], v[52:55], v[0:15]
	s_waitcnt vmcnt(4) lgkmcnt(0)
	s_barrier
	s_add_u32 s68, s98, 0x18000
	s_addc_u32 s69, s99, 0
	s_add_i32 m0, s57, 0x4000
	s_add_u32 s44, s100, 0x80
	global_load_lds_dwordx4 v198, s[68:69]
	s_addc_u32 s45, s101, 0
	s_add_i32 m0, s57, 0x4400
	s_nop 0
	global_load_lds_dwordx4 v194, s[68:69]
	s_add_i32 m0, s58, 0x18000
	s_nop 0
	global_load_lds_dwordx4 v196, s[44:45]
	s_add_i32 m0, s58, 0x18400
	s_nop 0
	global_load_lds_dwordx4 v192, s[44:45]
	v_exp_f32_e32 v144, v112
	ds_read_b128 v[32:35], v205 offset:32768
	ds_read_b128 v[36:39], v205 offset:40960
	s_waitcnt lgkmcnt(0)
	v_mfma_f32_32x32x16_bf16 v[48:63], v[32:35], v[160:163], 0
	ds_read_b128 v[132:135], v211 offset:32768
	ds_read_b128 v[136:139], v211 offset:40960
	ds_read_b128 v[140:143], v212 offset:32768
	v_exp_f32_e32 v145, v113
	v_exp_f32_e32 v146, v114
	v_exp_f32_e32 v147, v115
	ds_read_b128 v[112:115], v212 offset:40960
	v_mfma_f32_32x32x16_bf16 v[32:47], v[36:39], v[160:163], 0
	v_exp_f32_e32 v148, v116
	v_exp_f32_e32 v149, v117
	v_exp_f32_e32 v150, v118
	v_exp_f32_e32 v151, v119
	s_waitcnt lgkmcnt(0)
	v_mfma_f32_32x32x16_bf16 v[48:63], v[132:135], v[164:167], v[48:63]
	ds_read_b128 v[116:119], v213 offset:32768
	v_exp_f32_e32 v152, v120
	v_exp_f32_e32 v153, v121
	v_exp_f32_e32 v154, v122
	v_exp_f32_e32 v155, v123
	v_mfma_f32_32x32x16_bf16 v[32:47], v[136:139], v[164:167], v[32:47]
	ds_read_b128 v[120:123], v213 offset:40960
	v_exp_f32_e32 v156, v124
	v_exp_f32_e32 v157, v125
	v_exp_f32_e32 v158, v126
	v_exp_f32_e32 v159, v127
	v_mfma_f32_32x32x16_bf16 v[48:63], v[140:143], v[168:171], v[48:63]
	ds_read_b128 v[124:127], v236
	v_exp_f32_e32 v136, v96
	v_exp_f32_e32 v137, v97
	v_exp_f32_e32 v138, v98
	v_exp_f32_e32 v139, v99
	v_mfma_f32_32x32x16_bf16 v[32:47], v[112:115], v[168:171], v[32:47]
	ds_read_b128 v[96:99], v236 offset:4096
	v_exp_f32_e32 v140, v100
	v_exp_f32_e32 v141, v101
	v_exp_f32_e32 v142, v102
	v_exp_f32_e32 v143, v103
	s_waitcnt lgkmcnt(0)
	v_mfma_f32_32x32x16_bf16 v[48:63], v[116:119], v[172:175], v[48:63]
	ds_read_b128 v[100:103], v236 offset:8192
	v_exp_f32_e32 v178, v104
	v_exp_f32_e32 v179, v105
	v_exp_f32_e32 v180, v106
	v_exp_f32_e32 v181, v107
	v_mfma_f32_32x32x16_bf16 v[32:47], v[120:123], v[172:175], v[32:47]
	ds_read_b128 v[104:107], v236 offset:12288
	v_exp_f32_e32 v182, v108
	v_exp_f32_e32 v183, v109
	v_exp_f32_e32 v184, v110
	v_exp_f32_e32 v185, v111
	v_cvt_pk_bf16_f32 v108, v144, v145
	v_cvt_pk_bf16_f32 v109, v146, v147
	v_cvt_pk_bf16_f32 v110, v148, v149
	v_cvt_pk_bf16_f32 v111, v150, v151
	s_nop 1
	v_mfma_f32_32x32x16_bf16 v[80:95], v[124:127], v[108:111], v[80:95]
	ds_read_b128 v[112:115], v237
	v_cvt_pk_bf16_f32 v116, v152, v153
	v_cvt_pk_bf16_f32 v117, v154, v155
	v_cvt_pk_bf16_f32 v118, v156, v157
	v_cvt_pk_bf16_f32 v119, v158, v159
	v_mfma_f32_32x32x16_bf16 v[64:79], v[96:99], v[108:111], v[64:79]
	ds_read_b128 v[120:123], v237 offset:4096
	v_pk_add_f32 v[126:127], v[150:151], v[146:147]
	v_pk_add_f32 v[124:125], v[148:149], v[144:145]
	s_waitcnt lgkmcnt(0)
	v_mfma_f32_32x32x16_bf16 v[16:31], v[100:103], v[108:111], v[16:31]
	ds_read_b128 v[132:135], v237 offset:8192
	v_add_f32_e64 v98, v154, v126
	v_add_f32_e64 v99, v155, v127
	v_add_f32_e64 v96, v152, v124
	v_add_f32_e64 v97, v153, v125
	v_pk_add_f32 v[98:99], v[158:159], v[98:99]
	v_pk_add_f32 v[96:97], v[156:157], v[96:97]
	v_mfma_f32_32x32x16_bf16 v[0:15], v[104:107], v[108:111], v[0:15]
	ds_read_b128 v[100:103], v237 offset:12288
	v_mfma_f32_32x32x16_bf16 v[80:95], v[112:115], v[116:119], v[80:95]
	ds_read_b128 v[104:107], v238
	v_cvt_pk_bf16_f32 v108, v136, v137
	v_cvt_pk_bf16_f32 v109, v138, v139
	v_cvt_pk_bf16_f32 v110, v140, v141
	v_cvt_pk_bf16_f32 v111, v142, v143
	v_mfma_f32_32x32x16_bf16 v[64:79], v[120:123], v[116:119], v[64:79]
	ds_read_b128 v[112:115], v238 offset:4096
	v_add_f32_e64 v98, v138, v98
	v_add_f32_e64 v99, v139, v99
	v_add_f32_e64 v96, v136, v96
	v_add_f32_e64 v97, v137, v97
	v_pk_add_f32 v[98:99], v[142:143], v[98:99]
	v_pk_add_f32 v[96:97], v[140:141], v[96:97]
	s_waitcnt lgkmcnt(0)
	v_mfma_f32_32x32x16_bf16 v[16:31], v[132:135], v[116:119], v[16:31]
	ds_read_b128 v[120:123], v238 offset:8192
	v_add_f32_e64 v98, v180, v98
	v_add_f32_e64 v99, v181, v99
	v_add_f32_e64 v96, v178, v96
	v_add_f32_e64 v97, v179, v97
	v_pk_add_f32 v[98:99], v[184:185], v[98:99]
	v_pk_add_f32 v[96:97], v[182:183], v[96:97]
	v_mfma_f32_32x32x16_bf16 v[0:15], v[100:103], v[116:119], v[0:15]
	ds_read_b128 v[124:127], v238 offset:12288
	v_mfma_f32_32x32x16_bf16 v[80:95], v[104:107], v[108:111], v[80:95]
	ds_read_b128 v[100:103], v239
	v_cvt_pk_bf16_f32 v116, v178, v179
	v_cvt_pk_bf16_f32 v117, v180, v181
	v_cvt_pk_bf16_f32 v118, v182, v183
	v_cvt_pk_bf16_f32 v119, v184, v185
	v_mfma_f32_32x32x16_bf16 v[64:79], v[112:115], v[108:111], v[64:79]
	ds_read_b128 v[104:107], v239 offset:4096
	s_waitcnt lgkmcnt(0)
	v_mfma_f32_32x32x16_bf16 v[16:31], v[120:123], v[108:111], v[16:31]
	ds_read_b128 v[112:115], v239 offset:8192
	v_mfma_f32_32x32x16_bf16 v[0:15], v[124:127], v[108:111], v[0:15]
	ds_read_b128 v[120:123], v239 offset:12288
	v_mfma_f32_32x32x16_bf16 v[80:95], v[100:103], v[116:119], v[80:95]
	v_mfma_f32_32x32x16_bf16 v[64:79], v[104:107], v[116:119], v[64:79]
	s_waitcnt lgkmcnt(0)
	v_mfma_f32_32x32x16_bf16 v[16:31], v[112:115], v[116:119], v[16:31]
	v_mfma_f32_32x32x16_bf16 v[0:15], v[120:123], v[116:119], v[0:15]
	s_waitcnt vmcnt(4) lgkmcnt(0)
	v_add_f32_e32 v100, v128, v129
	v_add_f32_e32 v101, v130, v131
	v_add_f32_e32 v100, v100, v101
	v_add_f32_e32 v96, v96, v97
	v_add_f32_e32 v97, v98, v99
	s_barrier
	s_add_u32 s98, s98, 0x30000
	s_addc_u32 s99, s99, 0
	s_add_i32 m0, s58, 0x8000
	s_add_u32 s100, s100, 0x100
	global_load_lds_dwordx4 v198, s[98:99]
	s_addc_u32 s101, s101, 0
	s_add_i32 m0, s58, 0x8400
	v_add_f32_e32 v100, v177, v100
	global_load_lds_dwordx4 v194, s[98:99]
	s_add_i32 m0, s58, 0xc000
	v_add_f32_e32 v96, v96, v97
	global_load_lds_dwordx4 v196, s[100:101]
	s_add_i32 m0, s58, 0xc400
	v_add_f32_e32 v177, v100, v96
	global_load_lds_dwordx4 v192, s[100:101]
	ds_read_b128 v[96:99], v205
	ds_read_b128 v[100:103], v205 offset:8192
	s_waitcnt lgkmcnt(0)
	v_mfma_f32_32x32x16_bf16 v[112:127], v[96:99], v[160:163], 0
	ds_read_b128 v[128:131], v211
	ds_read_b128 v[132:135], v211 offset:8192
	ds_read_b128 v[136:139], v212
	v_exp_f32_e32 v140, v48
	v_exp_f32_e32 v141, v49
	v_exp_f32_e32 v142, v50
	v_exp_f32_e32 v143, v51
	ds_read_b128 v[48:51], v212 offset:8192
	v_mfma_f32_32x32x16_bf16 v[96:111], v[100:103], v[160:163], 0
	v_exp_f32_e32 v144, v52
	v_exp_f32_e32 v145, v53
	v_exp_f32_e32 v146, v54
	v_exp_f32_e32 v147, v55
	s_waitcnt lgkmcnt(0)
	v_mfma_f32_32x32x16_bf16 v[112:127], v[128:131], v[164:167], v[112:127]
	ds_read_b128 v[52:55], v213
	v_exp_f32_e32 v148, v56
	v_exp_f32_e32 v149, v57
	v_exp_f32_e32 v150, v58
	v_exp_f32_e32 v151, v59
	v_mfma_f32_32x32x16_bf16 v[96:111], v[132:135], v[164:167], v[96:111]
	ds_read_b128 v[56:59], v213 offset:8192
	v_exp_f32_e32 v128, v60
	v_exp_f32_e32 v129, v61
	v_exp_f32_e32 v130, v62
	v_exp_f32_e32 v131, v63
	v_mfma_f32_32x32x16_bf16 v[112:127], v[136:139], v[168:171], v[112:127]
	ds_read_b128 v[60:63], v236 offset:16384
	v_exp_f32_e32 v132, v32
	v_exp_f32_e32 v133, v33
	v_exp_f32_e32 v134, v34
	v_exp_f32_e32 v135, v35
	v_mfma_f32_32x32x16_bf16 v[96:111], v[48:51], v[168:171], v[96:111]
	ds_read_b128 v[32:35], v236 offset:20480
	v_exp_f32_e32 v136, v36
	v_exp_f32_e32 v137, v37
	v_exp_f32_e32 v138, v38
	v_exp_f32_e32 v139, v39
	s_waitcnt lgkmcnt(0)
	v_mfma_f32_32x32x16_bf16 v[112:127], v[52:55], v[172:175], v[112:127]
	ds_read_b128 v[36:39], v236 offset:24576
	v_exp_f32_e32 v152, v40
	v_exp_f32_e32 v153, v41
	v_exp_f32_e32 v154, v42
	v_exp_f32_e32 v155, v43
	v_mfma_f32_32x32x16_bf16 v[96:111], v[56:59], v[172:175], v[96:111]
	ds_read_b128 v[40:43], v236 offset:28672
	v_exp_f32_e32 v156, v44
	v_exp_f32_e32 v157, v45
	v_exp_f32_e32 v158, v46
	v_exp_f32_e32 v159, v47
	v_cvt_pk_bf16_f32 v44, v140, v141
	v_cvt_pk_bf16_f32 v45, v142, v143
	v_cvt_pk_bf16_f32 v46, v144, v145
	v_cvt_pk_bf16_f32 v47, v146, v147
	s_nop 1
	v_mfma_f32_32x32x16_bf16 v[80:95], v[60:63], v[44:47], v[80:95]
	ds_read_b128 v[48:51], v237 offset:16384
	v_cvt_pk_bf16_f32 v52, v148, v149
	v_cvt_pk_bf16_f32 v53, v150, v151
	v_cvt_pk_bf16_f32 v54, v128, v129
	v_cvt_pk_bf16_f32 v55, v130, v131
	v_mfma_f32_32x32x16_bf16 v[64:79], v[32:35], v[44:47], v[64:79]
	ds_read_b128 v[56:59], v237 offset:20480
	v_pk_add_f32 v[62:63], v[146:147], v[142:143]
	v_pk_add_f32 v[60:61], v[144:145], v[140:141]
	s_waitcnt lgkmcnt(0)
	v_mfma_f32_32x32x16_bf16 v[16:31], v[36:39], v[44:47], v[16:31]
	ds_read_b128 v[32:35], v237 offset:24576
	v_add_f32_e64 v62, v150, v62
	v_add_f32_e64 v63, v151, v63
	v_add_f32_e64 v60, v148, v60
	v_add_f32_e64 v61, v149, v61
	v_pk_add_f32 v[62:63], v[130:131], v[62:63]
	v_pk_add_f32 v[60:61], v[128:129], v[60:61]
	v_mfma_f32_32x32x16_bf16 v[0:15], v[40:43], v[44:47], v[0:15]
	ds_read_b128 v[36:39], v237 offset:28672
	v_mfma_f32_32x32x16_bf16 v[80:95], v[48:51], v[52:55], v[80:95]
	ds_read_b128 v[40:43], v238 offset:16384
	v_cvt_pk_bf16_f32 v44, v132, v133
	v_cvt_pk_bf16_f32 v45, v134, v135
	v_cvt_pk_bf16_f32 v46, v136, v137
	v_cvt_pk_bf16_f32 v47, v138, v139
	v_mfma_f32_32x32x16_bf16 v[64:79], v[56:59], v[52:55], v[64:79]
	ds_read_b128 v[48:51], v238 offset:20480
	v_add_f32_e64 v62, v134, v62
	v_add_f32_e64 v63, v135, v63
	v_add_f32_e64 v60, v132, v60
	v_add_f32_e64 v61, v133, v61
	v_pk_add_f32 v[62:63], v[138:139], v[62:63]
	v_pk_add_f32 v[60:61], v[136:137], v[60:61]
	s_waitcnt lgkmcnt(0)
	v_mfma_f32_32x32x16_bf16 v[16:31], v[32:35], v[52:55], v[16:31]
	ds_read_b128 v[56:59], v238 offset:24576
	v_add_f32_e64 v62, v154, v62
	v_add_f32_e64 v63, v155, v63
	v_add_f32_e64 v60, v152, v60
	v_add_f32_e64 v61, v153, v61
	v_pk_add_f32 v[130:131], v[158:159], v[62:63]
	v_pk_add_f32 v[128:129], v[156:157], v[60:61]
	v_mfma_f32_32x32x16_bf16 v[0:15], v[36:39], v[52:55], v[0:15]
	ds_read_b128 v[32:35], v238 offset:28672
	v_mfma_f32_32x32x16_bf16 v[80:95], v[40:43], v[44:47], v[80:95]
	ds_read_b128 v[36:39], v239 offset:16384
	v_cvt_pk_bf16_f32 v52, v152, v153
	v_cvt_pk_bf16_f32 v53, v154, v155
	v_cvt_pk_bf16_f32 v54, v156, v157
	v_cvt_pk_bf16_f32 v55, v158, v159
	v_mfma_f32_32x32x16_bf16 v[64:79], v[48:51], v[44:47], v[64:79]
	ds_read_b128 v[40:43], v239 offset:20480
	s_waitcnt lgkmcnt(0)
	v_mfma_f32_32x32x16_bf16 v[16:31], v[56:59], v[44:47], v[16:31]
	ds_read_b128 v[48:51], v239 offset:24576
	v_mfma_f32_32x32x16_bf16 v[0:15], v[32:35], v[44:47], v[0:15]
	ds_read_b128 v[56:59], v239 offset:28672
	v_mfma_f32_32x32x16_bf16 v[80:95], v[36:39], v[52:55], v[80:95]
	v_mfma_f32_32x32x16_bf16 v[64:79], v[40:43], v[52:55], v[64:79]
	s_waitcnt lgkmcnt(0)
	v_mfma_f32_32x32x16_bf16 v[16:31], v[48:51], v[52:55], v[16:31]
	v_mfma_f32_32x32x16_bf16 v[0:15], v[56:59], v[52:55], v[0:15]
	s_waitcnt vmcnt(4) lgkmcnt(0)
	s_barrier
	s_add_u32 s68, s98, 0x18000
	s_addc_u32 s69, s99, 0
	s_mov_b32 m0, s57
	s_add_u32 s44, s100, 0x80
	global_load_lds_dwordx4 v198, s[68:69]
	s_addc_u32 s45, s101, 0
	s_add_i32 m0, s57, 0x400
	s_nop 0
	global_load_lds_dwordx4 v194, s[68:69]
	s_add_i32 m0, s58, 0x10000
	s_nop 0
	global_load_lds_dwordx4 v196, s[44:45]
	s_add_i32 m0, s58, 0x10400
	s_nop 0
	global_load_lds_dwordx4 v192, s[44:45]
	v_exp_f32_e32 v144, v112
	ds_read_b128 v[32:35], v205 offset:16384
	ds_read_b128 v[36:39], v205 offset:24576
	s_waitcnt lgkmcnt(0)
	v_mfma_f32_32x32x16_bf16 v[48:63], v[32:35], v[160:163], 0
	ds_read_b128 v[132:135], v211 offset:16384
	ds_read_b128 v[136:139], v211 offset:24576
	ds_read_b128 v[140:143], v212 offset:16384
	v_exp_f32_e32 v145, v113
	v_exp_f32_e32 v146, v114
	v_exp_f32_e32 v147, v115
	ds_read_b128 v[112:115], v212 offset:24576
	v_mfma_f32_32x32x16_bf16 v[32:47], v[36:39], v[160:163], 0
	v_exp_f32_e32 v148, v116
	v_exp_f32_e32 v149, v117
	v_exp_f32_e32 v150, v118
	v_exp_f32_e32 v151, v119
	s_waitcnt lgkmcnt(0)
	v_mfma_f32_32x32x16_bf16 v[48:63], v[132:135], v[164:167], v[48:63]
	ds_read_b128 v[116:119], v213 offset:16384
	v_exp_f32_e32 v152, v120
	v_exp_f32_e32 v153, v121
	v_exp_f32_e32 v154, v122
	v_exp_f32_e32 v155, v123
	v_mfma_f32_32x32x16_bf16 v[32:47], v[136:139], v[164:167], v[32:47]
	ds_read_b128 v[120:123], v213 offset:24576
	v_exp_f32_e32 v156, v124
	v_exp_f32_e32 v157, v125
	v_exp_f32_e32 v158, v126
	v_exp_f32_e32 v159, v127
	v_mfma_f32_32x32x16_bf16 v[48:63], v[140:143], v[168:171], v[48:63]
	ds_read_b128 v[124:127], v236 offset:32768
	v_exp_f32_e32 v136, v96
	v_exp_f32_e32 v137, v97
	v_exp_f32_e32 v138, v98
	v_exp_f32_e32 v139, v99
	v_mfma_f32_32x32x16_bf16 v[32:47], v[112:115], v[168:171], v[32:47]
	ds_read_b128 v[96:99], v236 offset:36864
	v_exp_f32_e32 v140, v100
	v_exp_f32_e32 v141, v101
	v_exp_f32_e32 v142, v102
	v_exp_f32_e32 v143, v103
	s_waitcnt lgkmcnt(0)
	v_mfma_f32_32x32x16_bf16 v[48:63], v[116:119], v[172:175], v[48:63]
	ds_read_b128 v[100:103], v236 offset:40960
	v_exp_f32_e32 v178, v104
	v_exp_f32_e32 v179, v105
	v_exp_f32_e32 v180, v106
	v_exp_f32_e32 v181, v107
	v_mfma_f32_32x32x16_bf16 v[32:47], v[120:123], v[172:175], v[32:47]
	ds_read_b128 v[104:107], v236 offset:45056
	v_exp_f32_e32 v182, v108
	v_exp_f32_e32 v183, v109
	v_exp_f32_e32 v184, v110
	v_exp_f32_e32 v185, v111
	v_cvt_pk_bf16_f32 v108, v144, v145
	v_cvt_pk_bf16_f32 v109, v146, v147
	v_cvt_pk_bf16_f32 v110, v148, v149
	v_cvt_pk_bf16_f32 v111, v150, v151
	s_nop 1
	v_mfma_f32_32x32x16_bf16 v[80:95], v[124:127], v[108:111], v[80:95]
	ds_read_b128 v[112:115], v237 offset:32768
	v_cvt_pk_bf16_f32 v116, v152, v153
	v_cvt_pk_bf16_f32 v117, v154, v155
	v_cvt_pk_bf16_f32 v118, v156, v157
	v_cvt_pk_bf16_f32 v119, v158, v159
	v_mfma_f32_32x32x16_bf16 v[64:79], v[96:99], v[108:111], v[64:79]
	ds_read_b128 v[120:123], v237 offset:36864
	v_pk_add_f32 v[126:127], v[150:151], v[146:147]
	v_pk_add_f32 v[124:125], v[148:149], v[144:145]
	s_waitcnt lgkmcnt(0)
	v_mfma_f32_32x32x16_bf16 v[16:31], v[100:103], v[108:111], v[16:31]
	ds_read_b128 v[132:135], v237 offset:40960
	v_add_f32_e64 v98, v154, v126
	v_add_f32_e64 v99, v155, v127
	v_add_f32_e64 v96, v152, v124
	v_add_f32_e64 v97, v153, v125
	v_pk_add_f32 v[98:99], v[158:159], v[98:99]
	v_pk_add_f32 v[96:97], v[156:157], v[96:97]
	v_mfma_f32_32x32x16_bf16 v[0:15], v[104:107], v[108:111], v[0:15]
	ds_read_b128 v[100:103], v237 offset:45056
	v_mfma_f32_32x32x16_bf16 v[80:95], v[112:115], v[116:119], v[80:95]
	ds_read_b128 v[104:107], v238 offset:32768
	v_cvt_pk_bf16_f32 v108, v136, v137
	v_cvt_pk_bf16_f32 v109, v138, v139
	v_cvt_pk_bf16_f32 v110, v140, v141
	v_cvt_pk_bf16_f32 v111, v142, v143
	v_mfma_f32_32x32x16_bf16 v[64:79], v[120:123], v[116:119], v[64:79]
	ds_read_b128 v[112:115], v238 offset:36864
	v_add_f32_e64 v98, v138, v98
	v_add_f32_e64 v99, v139, v99
	v_add_f32_e64 v96, v136, v96
	v_add_f32_e64 v97, v137, v97
	v_pk_add_f32 v[98:99], v[142:143], v[98:99]
	v_pk_add_f32 v[96:97], v[140:141], v[96:97]
	s_waitcnt lgkmcnt(0)
	v_mfma_f32_32x32x16_bf16 v[16:31], v[132:135], v[116:119], v[16:31]
	ds_read_b128 v[120:123], v238 offset:40960
	v_add_f32_e64 v98, v180, v98
	v_add_f32_e64 v99, v181, v99
	v_add_f32_e64 v96, v178, v96
	v_add_f32_e64 v97, v179, v97
	v_pk_add_f32 v[98:99], v[184:185], v[98:99]
	v_pk_add_f32 v[96:97], v[182:183], v[96:97]
	v_mfma_f32_32x32x16_bf16 v[0:15], v[100:103], v[116:119], v[0:15]
	ds_read_b128 v[124:127], v238 offset:45056
	v_mfma_f32_32x32x16_bf16 v[80:95], v[104:107], v[108:111], v[80:95]
	ds_read_b128 v[100:103], v239 offset:32768
	v_cvt_pk_bf16_f32 v116, v178, v179
	v_cvt_pk_bf16_f32 v117, v180, v181
	v_cvt_pk_bf16_f32 v118, v182, v183
	v_cvt_pk_bf16_f32 v119, v184, v185
	v_mfma_f32_32x32x16_bf16 v[64:79], v[112:115], v[108:111], v[64:79]
	ds_read_b128 v[104:107], v239 offset:36864
	s_waitcnt lgkmcnt(0)
	v_mfma_f32_32x32x16_bf16 v[16:31], v[120:123], v[108:111], v[16:31]
	ds_read_b128 v[112:115], v239 offset:40960
	v_mfma_f32_32x32x16_bf16 v[0:15], v[124:127], v[108:111], v[0:15]
	ds_read_b128 v[120:123], v239 offset:45056
	v_mfma_f32_32x32x16_bf16 v[80:95], v[100:103], v[116:119], v[80:95]
	v_mfma_f32_32x32x16_bf16 v[64:79], v[104:107], v[116:119], v[64:79]
	s_waitcnt lgkmcnt(0)
	v_mfma_f32_32x32x16_bf16 v[16:31], v[112:115], v[116:119], v[16:31]
	v_mfma_f32_32x32x16_bf16 v[0:15], v[120:123], v[116:119], v[0:15]
	s_waitcnt vmcnt(4) lgkmcnt(0)
	v_add_f32_e32 v100, v128, v129
	v_add_f32_e32 v101, v130, v131
	v_add_f32_e32 v100, v100, v101
	v_add_f32_e32 v96, v96, v97
	v_add_f32_e32 v97, v98, v99
	s_barrier
	s_add_u32 s98, s98, 0x30000
	s_addc_u32 s99, s99, 0
	s_add_i32 m0, s58, 0x4000
	s_add_u32 s100, s100, 0x100
	global_load_lds_dwordx4 v198, s[98:99]
	s_addc_u32 s101, s101, 0
	s_add_i32 m0, s58, 0x4400
	v_add_f32_e32 v100, v177, v100
	global_load_lds_dwordx4 v194, s[98:99]
	s_add_i32 m0, s58, 0x14000
	v_add_f32_e32 v96, v96, v97
	global_load_lds_dwordx4 v196, s[100:101]
	s_add_i32 m0, s58, 0x14400
	v_add_f32_e32 v177, v100, v96
	global_load_lds_dwordx4 v192, s[100:101]
	ds_read_b128 v[96:99], v205 offset:32768
	ds_read_b128 v[100:103], v205 offset:40960
	s_waitcnt lgkmcnt(0)
	v_mfma_f32_32x32x16_bf16 v[112:127], v[96:99], v[160:163], 0
	ds_read_b128 v[128:131], v211 offset:32768
	ds_read_b128 v[132:135], v211 offset:40960
	ds_read_b128 v[136:139], v212 offset:32768
	v_exp_f32_e32 v140, v48
	v_exp_f32_e32 v141, v49
	v_exp_f32_e32 v142, v50
	v_exp_f32_e32 v143, v51
	ds_read_b128 v[48:51], v212 offset:40960
	v_mfma_f32_32x32x16_bf16 v[96:111], v[100:103], v[160:163], 0
	v_exp_f32_e32 v144, v52
	v_exp_f32_e32 v145, v53
	v_exp_f32_e32 v146, v54
	v_exp_f32_e32 v147, v55
	s_waitcnt lgkmcnt(0)
	v_mfma_f32_32x32x16_bf16 v[112:127], v[128:131], v[164:167], v[112:127]
	ds_read_b128 v[52:55], v213 offset:32768
	v_exp_f32_e32 v148, v56
	v_exp_f32_e32 v149, v57
	v_exp_f32_e32 v150, v58
	v_exp_f32_e32 v151, v59
	v_mfma_f32_32x32x16_bf16 v[96:111], v[132:135], v[164:167], v[96:111]
	ds_read_b128 v[56:59], v213 offset:40960
	v_exp_f32_e32 v128, v60
	v_exp_f32_e32 v129, v61
	v_exp_f32_e32 v130, v62
	v_exp_f32_e32 v131, v63
	v_mfma_f32_32x32x16_bf16 v[112:127], v[136:139], v[168:171], v[112:127]
	ds_read_b128 v[60:63], v206 offset:49152
	v_exp_f32_e32 v132, v32
	v_exp_f32_e32 v133, v33
	v_exp_f32_e32 v134, v34
	v_exp_f32_e32 v135, v35
	v_mfma_f32_32x32x16_bf16 v[96:111], v[48:51], v[168:171], v[96:111]
	ds_read_b128 v[32:35], v206 offset:53248
	v_exp_f32_e32 v136, v36
	v_exp_f32_e32 v137, v37
	v_exp_f32_e32 v138, v38
	v_exp_f32_e32 v139, v39
	s_waitcnt lgkmcnt(0)
	v_mfma_f32_32x32x16_bf16 v[112:127], v[52:55], v[172:175], v[112:127]
	ds_read_b128 v[36:39], v206 offset:57344
	v_exp_f32_e32 v152, v40
	v_exp_f32_e32 v153, v41
	v_exp_f32_e32 v154, v42
	v_exp_f32_e32 v155, v43
	v_mfma_f32_32x32x16_bf16 v[96:111], v[56:59], v[172:175], v[96:111]
	ds_read_b128 v[40:43], v206 offset:61440
	v_exp_f32_e32 v156, v44
	v_exp_f32_e32 v157, v45
	v_exp_f32_e32 v158, v46
	v_exp_f32_e32 v159, v47
	v_cvt_pk_bf16_f32 v44, v140, v141
	v_cvt_pk_bf16_f32 v45, v142, v143
	v_cvt_pk_bf16_f32 v46, v144, v145
	v_cvt_pk_bf16_f32 v47, v146, v147
	s_nop 1
	v_mfma_f32_32x32x16_bf16 v[80:95], v[60:63], v[44:47], v[80:95]
	ds_read_b128 v[48:51], v207 offset:49152
	v_cvt_pk_bf16_f32 v52, v148, v149
	v_cvt_pk_bf16_f32 v53, v150, v151
	v_cvt_pk_bf16_f32 v54, v128, v129
	v_cvt_pk_bf16_f32 v55, v130, v131
	v_mfma_f32_32x32x16_bf16 v[64:79], v[32:35], v[44:47], v[64:79]
	ds_read_b128 v[56:59], v207 offset:53248
	v_pk_add_f32 v[62:63], v[146:147], v[142:143]
	v_pk_add_f32 v[60:61], v[144:145], v[140:141]
	s_waitcnt lgkmcnt(0)
	v_mfma_f32_32x32x16_bf16 v[16:31], v[36:39], v[44:47], v[16:31]
	ds_read_b128 v[32:35], v207 offset:57344
	v_add_f32_e64 v62, v150, v62
	v_add_f32_e64 v63, v151, v63
	v_add_f32_e64 v60, v148, v60
	v_add_f32_e64 v61, v149, v61
	v_pk_add_f32 v[62:63], v[130:131], v[62:63]
	v_pk_add_f32 v[60:61], v[128:129], v[60:61]
	v_mfma_f32_32x32x16_bf16 v[0:15], v[40:43], v[44:47], v[0:15]
	ds_read_b128 v[36:39], v207 offset:61440
	v_mfma_f32_32x32x16_bf16 v[80:95], v[48:51], v[52:55], v[80:95]
	ds_read_b128 v[40:43], v208 offset:49152
	v_cvt_pk_bf16_f32 v44, v132, v133
	v_cvt_pk_bf16_f32 v45, v134, v135
	v_cvt_pk_bf16_f32 v46, v136, v137
	v_cvt_pk_bf16_f32 v47, v138, v139
	v_mfma_f32_32x32x16_bf16 v[64:79], v[56:59], v[52:55], v[64:79]
	ds_read_b128 v[48:51], v208 offset:53248
	v_add_f32_e64 v62, v134, v62
	v_add_f32_e64 v63, v135, v63
	v_add_f32_e64 v60, v132, v60
	v_add_f32_e64 v61, v133, v61
	v_pk_add_f32 v[62:63], v[138:139], v[62:63]
	v_pk_add_f32 v[60:61], v[136:137], v[60:61]
	s_waitcnt lgkmcnt(0)
	v_mfma_f32_32x32x16_bf16 v[16:31], v[32:35], v[52:55], v[16:31]
	ds_read_b128 v[56:59], v208 offset:57344
	v_add_f32_e64 v62, v154, v62
	v_add_f32_e64 v63, v155, v63
	v_add_f32_e64 v60, v152, v60
	v_add_f32_e64 v61, v153, v61
	v_pk_add_f32 v[130:131], v[158:159], v[62:63]
	v_pk_add_f32 v[128:129], v[156:157], v[60:61]
	v_mfma_f32_32x32x16_bf16 v[0:15], v[36:39], v[52:55], v[0:15]
	ds_read_b128 v[32:35], v208 offset:61440
	v_mfma_f32_32x32x16_bf16 v[80:95], v[40:43], v[44:47], v[80:95]
	ds_read_b128 v[36:39], v209 offset:49152
	v_cvt_pk_bf16_f32 v52, v152, v153
	v_cvt_pk_bf16_f32 v53, v154, v155
	v_cvt_pk_bf16_f32 v54, v156, v157
	v_cvt_pk_bf16_f32 v55, v158, v159
	v_mfma_f32_32x32x16_bf16 v[64:79], v[48:51], v[44:47], v[64:79]
	ds_read_b128 v[40:43], v209 offset:53248
	s_waitcnt lgkmcnt(0)
	v_mfma_f32_32x32x16_bf16 v[16:31], v[56:59], v[44:47], v[16:31]
	ds_read_b128 v[48:51], v209 offset:57344
	v_mfma_f32_32x32x16_bf16 v[0:15], v[32:35], v[44:47], v[0:15]
	ds_read_b128 v[56:59], v209 offset:61440
	v_mfma_f32_32x32x16_bf16 v[80:95], v[36:39], v[52:55], v[80:95]
	v_mfma_f32_32x32x16_bf16 v[64:79], v[40:43], v[52:55], v[64:79]
	s_waitcnt lgkmcnt(0)
	v_mfma_f32_32x32x16_bf16 v[16:31], v[48:51], v[52:55], v[16:31]
	v_mfma_f32_32x32x16_bf16 v[0:15], v[56:59], v[52:55], v[0:15]
	s_waitcnt vmcnt(4) lgkmcnt(0)
	s_barrier
	s_add_u32 s68, s98, 0x18000
	s_addc_u32 s69, s99, 0
	s_add_i32 m0, s57, 0x8000
	s_add_u32 s44, s100, 0x80
	global_load_lds_dwordx4 v198, s[68:69]
	s_addc_u32 s45, s101, 0
	s_add_i32 m0, s57, 0x8400
	s_nop 0
	global_load_lds_dwordx4 v194, s[68:69]
	s_add_i32 m0, s58, 0x18000
	s_nop 0
	global_load_lds_dwordx4 v196, s[44:45]
	s_add_i32 m0, s58, 0x18400
	s_nop 0
	global_load_lds_dwordx4 v192, s[44:45]
	v_exp_f32_e32 v144, v112
	ds_read_b128 v[32:35], v205
	ds_read_b128 v[36:39], v205 offset:8192
	s_waitcnt lgkmcnt(0)
	v_mfma_f32_32x32x16_bf16 v[48:63], v[32:35], v[160:163], 0
	ds_read_b128 v[132:135], v211
	ds_read_b128 v[136:139], v211 offset:8192
	ds_read_b128 v[140:143], v212
	v_exp_f32_e32 v145, v113
	v_exp_f32_e32 v146, v114
	v_exp_f32_e32 v147, v115
	ds_read_b128 v[112:115], v212 offset:8192
	v_mfma_f32_32x32x16_bf16 v[32:47], v[36:39], v[160:163], 0
	v_exp_f32_e32 v148, v116
	v_exp_f32_e32 v149, v117
	v_exp_f32_e32 v150, v118
	v_exp_f32_e32 v151, v119
	s_waitcnt lgkmcnt(0)
	v_mfma_f32_32x32x16_bf16 v[48:63], v[132:135], v[164:167], v[48:63]
	ds_read_b128 v[116:119], v213
	v_exp_f32_e32 v152, v120
	v_exp_f32_e32 v153, v121
	v_exp_f32_e32 v154, v122
	v_exp_f32_e32 v155, v123
	v_mfma_f32_32x32x16_bf16 v[32:47], v[136:139], v[164:167], v[32:47]
	ds_read_b128 v[120:123], v213 offset:8192
	v_exp_f32_e32 v156, v124
	v_exp_f32_e32 v157, v125
	v_exp_f32_e32 v158, v126
	v_exp_f32_e32 v159, v127
	v_mfma_f32_32x32x16_bf16 v[48:63], v[140:143], v[168:171], v[48:63]
	ds_read_b128 v[124:127], v236
	v_exp_f32_e32 v136, v96
	v_exp_f32_e32 v137, v97
	v_exp_f32_e32 v138, v98
	v_exp_f32_e32 v139, v99
	v_mfma_f32_32x32x16_bf16 v[32:47], v[112:115], v[168:171], v[32:47]
	ds_read_b128 v[96:99], v236 offset:4096
	v_exp_f32_e32 v140, v100
	v_exp_f32_e32 v141, v101
	v_exp_f32_e32 v142, v102
	v_exp_f32_e32 v143, v103
	s_waitcnt lgkmcnt(0)
	v_mfma_f32_32x32x16_bf16 v[48:63], v[116:119], v[172:175], v[48:63]
	ds_read_b128 v[100:103], v236 offset:8192
	v_exp_f32_e32 v178, v104
	v_exp_f32_e32 v179, v105
	v_exp_f32_e32 v180, v106
	v_exp_f32_e32 v181, v107
	v_mfma_f32_32x32x16_bf16 v[32:47], v[120:123], v[172:175], v[32:47]
	ds_read_b128 v[104:107], v236 offset:12288
	v_exp_f32_e32 v182, v108
	v_exp_f32_e32 v183, v109
	v_exp_f32_e32 v184, v110
	v_exp_f32_e32 v185, v111
	v_cvt_pk_bf16_f32 v108, v144, v145
	v_cvt_pk_bf16_f32 v109, v146, v147
	v_cvt_pk_bf16_f32 v110, v148, v149
	v_cvt_pk_bf16_f32 v111, v150, v151
	s_nop 1
	v_mfma_f32_32x32x16_bf16 v[80:95], v[124:127], v[108:111], v[80:95]
	ds_read_b128 v[112:115], v237
	v_cvt_pk_bf16_f32 v116, v152, v153
	v_cvt_pk_bf16_f32 v117, v154, v155
	v_cvt_pk_bf16_f32 v118, v156, v157
	v_cvt_pk_bf16_f32 v119, v158, v159
	v_mfma_f32_32x32x16_bf16 v[64:79], v[96:99], v[108:111], v[64:79]
	ds_read_b128 v[120:123], v237 offset:4096
	v_pk_add_f32 v[126:127], v[150:151], v[146:147]
	v_pk_add_f32 v[124:125], v[148:149], v[144:145]
	s_waitcnt lgkmcnt(0)
	v_mfma_f32_32x32x16_bf16 v[16:31], v[100:103], v[108:111], v[16:31]
	ds_read_b128 v[132:135], v237 offset:8192
	v_add_f32_e64 v98, v154, v126
	v_add_f32_e64 v99, v155, v127
	v_add_f32_e64 v96, v152, v124
	v_add_f32_e64 v97, v153, v125
	v_pk_add_f32 v[98:99], v[158:159], v[98:99]
	v_pk_add_f32 v[96:97], v[156:157], v[96:97]
	v_mfma_f32_32x32x16_bf16 v[0:15], v[104:107], v[108:111], v[0:15]
	ds_read_b128 v[100:103], v237 offset:12288
	v_mfma_f32_32x32x16_bf16 v[80:95], v[112:115], v[116:119], v[80:95]
	ds_read_b128 v[104:107], v238
	v_cvt_pk_bf16_f32 v108, v136, v137
	v_cvt_pk_bf16_f32 v109, v138, v139
	v_cvt_pk_bf16_f32 v110, v140, v141
	v_cvt_pk_bf16_f32 v111, v142, v143
	v_mfma_f32_32x32x16_bf16 v[64:79], v[120:123], v[116:119], v[64:79]
	ds_read_b128 v[112:115], v238 offset:4096
	v_add_f32_e64 v98, v138, v98
	v_add_f32_e64 v99, v139, v99
	v_add_f32_e64 v96, v136, v96
	v_add_f32_e64 v97, v137, v97
	v_pk_add_f32 v[98:99], v[142:143], v[98:99]
	v_pk_add_f32 v[96:97], v[140:141], v[96:97]
	s_waitcnt lgkmcnt(0)
	v_mfma_f32_32x32x16_bf16 v[16:31], v[132:135], v[116:119], v[16:31]
	ds_read_b128 v[120:123], v238 offset:8192
	v_add_f32_e64 v98, v180, v98
	v_add_f32_e64 v99, v181, v99
	v_add_f32_e64 v96, v178, v96
	v_add_f32_e64 v97, v179, v97
	v_pk_add_f32 v[98:99], v[184:185], v[98:99]
	v_pk_add_f32 v[96:97], v[182:183], v[96:97]
	v_mfma_f32_32x32x16_bf16 v[0:15], v[100:103], v[116:119], v[0:15]
	ds_read_b128 v[124:127], v238 offset:12288
	v_mfma_f32_32x32x16_bf16 v[80:95], v[104:107], v[108:111], v[80:95]
	ds_read_b128 v[100:103], v239
	v_cvt_pk_bf16_f32 v116, v178, v179
	v_cvt_pk_bf16_f32 v117, v180, v181
	v_cvt_pk_bf16_f32 v118, v182, v183
	v_cvt_pk_bf16_f32 v119, v184, v185
	v_mfma_f32_32x32x16_bf16 v[64:79], v[112:115], v[108:111], v[64:79]
	ds_read_b128 v[104:107], v239 offset:4096
	s_waitcnt lgkmcnt(0)
	v_mfma_f32_32x32x16_bf16 v[16:31], v[120:123], v[108:111], v[16:31]
	ds_read_b128 v[112:115], v239 offset:8192
	v_mfma_f32_32x32x16_bf16 v[0:15], v[124:127], v[108:111], v[0:15]
	ds_read_b128 v[120:123], v239 offset:12288
	v_mfma_f32_32x32x16_bf16 v[80:95], v[100:103], v[116:119], v[80:95]
	v_mfma_f32_32x32x16_bf16 v[64:79], v[104:107], v[116:119], v[64:79]
	s_waitcnt lgkmcnt(0)
	v_mfma_f32_32x32x16_bf16 v[16:31], v[112:115], v[116:119], v[16:31]
	v_mfma_f32_32x32x16_bf16 v[0:15], v[120:123], v[116:119], v[0:15]
	s_waitcnt vmcnt(4) lgkmcnt(0)
	v_add_f32_e32 v100, v128, v129
	v_add_f32_e32 v101, v130, v131
	v_add_f32_e32 v100, v100, v101
	v_add_f32_e32 v96, v96, v97
	v_add_f32_e32 v97, v98, v99
	s_barrier
	s_add_u32 s98, s98, 0x30000
	s_addc_u32 s99, s99, 0
	s_mov_b32 m0, s58
	s_add_u32 s100, s100, 0x100
	global_load_lds_dwordx4 v198, s[98:99]
	s_addc_u32 s101, s101, 0
	s_add_i32 m0, s58, 0x400
	v_add_f32_e32 v100, v177, v100
	global_load_lds_dwordx4 v194, s[98:99]
	s_add_i32 m0, s58, 0xc000
	v_add_f32_e32 v96, v96, v97
	global_load_lds_dwordx4 v196, s[100:101]
	s_add_i32 m0, s58, 0xc400
	v_add_f32_e32 v177, v100, v96
	global_load_lds_dwordx4 v192, s[100:101]
	ds_read_b128 v[96:99], v205 offset:16384
	ds_read_b128 v[100:103], v205 offset:24576
	s_waitcnt lgkmcnt(0)
	v_mfma_f32_32x32x16_bf16 v[112:127], v[96:99], v[160:163], 0
	ds_read_b128 v[128:131], v211 offset:16384
	ds_read_b128 v[132:135], v211 offset:24576
	ds_read_b128 v[136:139], v212 offset:16384
	v_exp_f32_e32 v140, v48
	v_exp_f32_e32 v141, v49
	v_exp_f32_e32 v142, v50
	v_exp_f32_e32 v143, v51
	ds_read_b128 v[48:51], v212 offset:24576
	v_mfma_f32_32x32x16_bf16 v[96:111], v[100:103], v[160:163], 0
	v_exp_f32_e32 v144, v52
	v_exp_f32_e32 v145, v53
	v_exp_f32_e32 v146, v54
	v_exp_f32_e32 v147, v55
	s_waitcnt lgkmcnt(0)
	v_mfma_f32_32x32x16_bf16 v[112:127], v[128:131], v[164:167], v[112:127]
	ds_read_b128 v[52:55], v213 offset:16384
	v_exp_f32_e32 v148, v56
	v_exp_f32_e32 v149, v57
	v_exp_f32_e32 v150, v58
	v_exp_f32_e32 v151, v59
	v_mfma_f32_32x32x16_bf16 v[96:111], v[132:135], v[164:167], v[96:111]
	ds_read_b128 v[56:59], v213 offset:24576
	v_exp_f32_e32 v128, v60
	v_exp_f32_e32 v129, v61
	v_exp_f32_e32 v130, v62
	v_exp_f32_e32 v131, v63
	v_mfma_f32_32x32x16_bf16 v[112:127], v[136:139], v[168:171], v[112:127]
	ds_read_b128 v[60:63], v236 offset:16384
	v_exp_f32_e32 v132, v32
	v_exp_f32_e32 v133, v33
	v_exp_f32_e32 v134, v34
	v_exp_f32_e32 v135, v35
	v_mfma_f32_32x32x16_bf16 v[96:111], v[48:51], v[168:171], v[96:111]
	ds_read_b128 v[32:35], v236 offset:20480
	v_exp_f32_e32 v136, v36
	v_exp_f32_e32 v137, v37
	v_exp_f32_e32 v138, v38
	v_exp_f32_e32 v139, v39
	s_waitcnt lgkmcnt(0)
	v_mfma_f32_32x32x16_bf16 v[112:127], v[52:55], v[172:175], v[112:127]
	ds_read_b128 v[36:39], v236 offset:24576
	v_exp_f32_e32 v152, v40
	v_exp_f32_e32 v153, v41
	v_exp_f32_e32 v154, v42
	v_exp_f32_e32 v155, v43
	v_mfma_f32_32x32x16_bf16 v[96:111], v[56:59], v[172:175], v[96:111]
	ds_read_b128 v[40:43], v236 offset:28672
	v_exp_f32_e32 v156, v44
	v_exp_f32_e32 v157, v45
	v_exp_f32_e32 v158, v46
	v_exp_f32_e32 v159, v47
	v_cvt_pk_bf16_f32 v44, v140, v141
	v_cvt_pk_bf16_f32 v45, v142, v143
	v_cvt_pk_bf16_f32 v46, v144, v145
	v_cvt_pk_bf16_f32 v47, v146, v147
	s_nop 1
	v_mfma_f32_32x32x16_bf16 v[80:95], v[60:63], v[44:47], v[80:95]
	ds_read_b128 v[48:51], v237 offset:16384
	v_cvt_pk_bf16_f32 v52, v148, v149
	v_cvt_pk_bf16_f32 v53, v150, v151
	v_cvt_pk_bf16_f32 v54, v128, v129
	v_cvt_pk_bf16_f32 v55, v130, v131
	v_mfma_f32_32x32x16_bf16 v[64:79], v[32:35], v[44:47], v[64:79]
	ds_read_b128 v[56:59], v237 offset:20480
	v_pk_add_f32 v[62:63], v[146:147], v[142:143]
	v_pk_add_f32 v[60:61], v[144:145], v[140:141]
	s_waitcnt lgkmcnt(0)
	v_mfma_f32_32x32x16_bf16 v[16:31], v[36:39], v[44:47], v[16:31]
	ds_read_b128 v[32:35], v237 offset:24576
	v_add_f32_e64 v62, v150, v62
	v_add_f32_e64 v63, v151, v63
	v_add_f32_e64 v60, v148, v60
	v_add_f32_e64 v61, v149, v61
	v_pk_add_f32 v[62:63], v[130:131], v[62:63]
	v_pk_add_f32 v[60:61], v[128:129], v[60:61]
	v_mfma_f32_32x32x16_bf16 v[0:15], v[40:43], v[44:47], v[0:15]
	ds_read_b128 v[36:39], v237 offset:28672
	v_mfma_f32_32x32x16_bf16 v[80:95], v[48:51], v[52:55], v[80:95]
	ds_read_b128 v[40:43], v238 offset:16384
	v_cvt_pk_bf16_f32 v44, v132, v133
	v_cvt_pk_bf16_f32 v45, v134, v135
	v_cvt_pk_bf16_f32 v46, v136, v137
	v_cvt_pk_bf16_f32 v47, v138, v139
	v_mfma_f32_32x32x16_bf16 v[64:79], v[56:59], v[52:55], v[64:79]
	ds_read_b128 v[48:51], v238 offset:20480
	v_add_f32_e64 v62, v134, v62
	v_add_f32_e64 v63, v135, v63
	v_add_f32_e64 v60, v132, v60
	v_add_f32_e64 v61, v133, v61
	v_pk_add_f32 v[62:63], v[138:139], v[62:63]
	v_pk_add_f32 v[60:61], v[136:137], v[60:61]
	s_waitcnt lgkmcnt(0)
	v_mfma_f32_32x32x16_bf16 v[16:31], v[32:35], v[52:55], v[16:31]
	ds_read_b128 v[56:59], v238 offset:24576
	v_add_f32_e64 v62, v154, v62
	v_add_f32_e64 v63, v155, v63
	v_add_f32_e64 v60, v152, v60
	v_add_f32_e64 v61, v153, v61
	v_pk_add_f32 v[130:131], v[158:159], v[62:63]
	v_pk_add_f32 v[128:129], v[156:157], v[60:61]
	v_mfma_f32_32x32x16_bf16 v[0:15], v[36:39], v[52:55], v[0:15]
	ds_read_b128 v[32:35], v238 offset:28672
	v_mfma_f32_32x32x16_bf16 v[80:95], v[40:43], v[44:47], v[80:95]
	ds_read_b128 v[36:39], v239 offset:16384
	v_cvt_pk_bf16_f32 v52, v152, v153
	v_cvt_pk_bf16_f32 v53, v154, v155
	v_cvt_pk_bf16_f32 v54, v156, v157
	v_cvt_pk_bf16_f32 v55, v158, v159
	v_mfma_f32_32x32x16_bf16 v[64:79], v[48:51], v[44:47], v[64:79]
	ds_read_b128 v[40:43], v239 offset:20480
	s_waitcnt lgkmcnt(0)
	v_mfma_f32_32x32x16_bf16 v[16:31], v[56:59], v[44:47], v[16:31]
	ds_read_b128 v[48:51], v239 offset:24576
	v_mfma_f32_32x32x16_bf16 v[0:15], v[32:35], v[44:47], v[0:15]
	ds_read_b128 v[56:59], v239 offset:28672
	v_mfma_f32_32x32x16_bf16 v[80:95], v[36:39], v[52:55], v[80:95]
	v_mfma_f32_32x32x16_bf16 v[64:79], v[40:43], v[52:55], v[64:79]
	s_waitcnt lgkmcnt(0)
	v_mfma_f32_32x32x16_bf16 v[16:31], v[48:51], v[52:55], v[16:31]
	v_mfma_f32_32x32x16_bf16 v[0:15], v[56:59], v[52:55], v[0:15]
	s_waitcnt vmcnt(4) lgkmcnt(0)
	s_barrier
	s_add_u32 s68, s98, 0x18000
	s_addc_u32 s69, s99, 0
	s_add_i32 m0, s57, 0x4000
	s_add_u32 s44, s100, 0x80
	global_load_lds_dwordx4 v198, s[68:69]
	s_addc_u32 s45, s101, 0
	s_add_i32 m0, s57, 0x4400
	s_nop 0
	global_load_lds_dwordx4 v194, s[68:69]
	s_add_i32 m0, s58, 0x10000
	s_nop 0
	global_load_lds_dwordx4 v196, s[44:45]
	s_add_i32 m0, s58, 0x10400
	s_nop 0
	global_load_lds_dwordx4 v192, s[44:45]
	v_exp_f32_e32 v144, v112
	ds_read_b128 v[32:35], v205 offset:32768
	ds_read_b128 v[36:39], v205 offset:40960
	s_waitcnt lgkmcnt(0)
	v_mfma_f32_32x32x16_bf16 v[48:63], v[32:35], v[160:163], 0
	ds_read_b128 v[132:135], v211 offset:32768
	ds_read_b128 v[136:139], v211 offset:40960
	ds_read_b128 v[140:143], v212 offset:32768
	v_exp_f32_e32 v145, v113
	v_exp_f32_e32 v146, v114
	v_exp_f32_e32 v147, v115
	ds_read_b128 v[112:115], v212 offset:40960
	v_mfma_f32_32x32x16_bf16 v[32:47], v[36:39], v[160:163], 0
	v_exp_f32_e32 v148, v116
	v_exp_f32_e32 v149, v117
	v_exp_f32_e32 v150, v118
	v_exp_f32_e32 v151, v119
	s_waitcnt lgkmcnt(0)
	v_mfma_f32_32x32x16_bf16 v[48:63], v[132:135], v[164:167], v[48:63]
	ds_read_b128 v[116:119], v213 offset:32768
	v_exp_f32_e32 v152, v120
	v_exp_f32_e32 v153, v121
	v_exp_f32_e32 v154, v122
	v_exp_f32_e32 v155, v123
	v_mfma_f32_32x32x16_bf16 v[32:47], v[136:139], v[164:167], v[32:47]
	ds_read_b128 v[120:123], v213 offset:40960
	v_exp_f32_e32 v156, v124
	v_exp_f32_e32 v157, v125
	v_exp_f32_e32 v158, v126
	v_exp_f32_e32 v159, v127
	v_mfma_f32_32x32x16_bf16 v[48:63], v[140:143], v[168:171], v[48:63]
	ds_read_b128 v[124:127], v236 offset:32768
	v_exp_f32_e32 v136, v96
	v_exp_f32_e32 v137, v97
	v_exp_f32_e32 v138, v98
	v_exp_f32_e32 v139, v99
	v_mfma_f32_32x32x16_bf16 v[32:47], v[112:115], v[168:171], v[32:47]
	ds_read_b128 v[96:99], v236 offset:36864
	v_exp_f32_e32 v140, v100
	v_exp_f32_e32 v141, v101
	v_exp_f32_e32 v142, v102
	v_exp_f32_e32 v143, v103
	s_waitcnt lgkmcnt(0)
	v_mfma_f32_32x32x16_bf16 v[48:63], v[116:119], v[172:175], v[48:63]
	ds_read_b128 v[100:103], v236 offset:40960
	v_exp_f32_e32 v178, v104
	v_exp_f32_e32 v179, v105
	v_exp_f32_e32 v180, v106
	v_exp_f32_e32 v181, v107
	v_mfma_f32_32x32x16_bf16 v[32:47], v[120:123], v[172:175], v[32:47]
	ds_read_b128 v[104:107], v236 offset:45056
	v_exp_f32_e32 v182, v108
	v_exp_f32_e32 v183, v109
	v_exp_f32_e32 v184, v110
	v_exp_f32_e32 v185, v111
	v_cvt_pk_bf16_f32 v108, v144, v145
	v_cvt_pk_bf16_f32 v109, v146, v147
	v_cvt_pk_bf16_f32 v110, v148, v149
	v_cvt_pk_bf16_f32 v111, v150, v151
	s_nop 1
	v_mfma_f32_32x32x16_bf16 v[80:95], v[124:127], v[108:111], v[80:95]
	ds_read_b128 v[112:115], v237 offset:32768
	v_cvt_pk_bf16_f32 v116, v152, v153
	v_cvt_pk_bf16_f32 v117, v154, v155
	v_cvt_pk_bf16_f32 v118, v156, v157
	v_cvt_pk_bf16_f32 v119, v158, v159
	v_mfma_f32_32x32x16_bf16 v[64:79], v[96:99], v[108:111], v[64:79]
	ds_read_b128 v[120:123], v237 offset:36864
	v_pk_add_f32 v[126:127], v[150:151], v[146:147]
	v_pk_add_f32 v[124:125], v[148:149], v[144:145]
	s_waitcnt lgkmcnt(0)
	v_mfma_f32_32x32x16_bf16 v[16:31], v[100:103], v[108:111], v[16:31]
	ds_read_b128 v[132:135], v237 offset:40960
	v_add_f32_e64 v98, v154, v126
	v_add_f32_e64 v99, v155, v127
	v_add_f32_e64 v96, v152, v124
	v_add_f32_e64 v97, v153, v125
	v_pk_add_f32 v[98:99], v[158:159], v[98:99]
	v_pk_add_f32 v[96:97], v[156:157], v[96:97]
	v_mfma_f32_32x32x16_bf16 v[0:15], v[104:107], v[108:111], v[0:15]
	ds_read_b128 v[100:103], v237 offset:45056
	v_mfma_f32_32x32x16_bf16 v[80:95], v[112:115], v[116:119], v[80:95]
	ds_read_b128 v[104:107], v238 offset:32768
	v_cvt_pk_bf16_f32 v108, v136, v137
	v_cvt_pk_bf16_f32 v109, v138, v139
	v_cvt_pk_bf16_f32 v110, v140, v141
	v_cvt_pk_bf16_f32 v111, v142, v143
	v_mfma_f32_32x32x16_bf16 v[64:79], v[120:123], v[116:119], v[64:79]
	ds_read_b128 v[112:115], v238 offset:36864
	v_add_f32_e64 v98, v138, v98
	v_add_f32_e64 v99, v139, v99
	v_add_f32_e64 v96, v136, v96
	v_add_f32_e64 v97, v137, v97
	v_pk_add_f32 v[98:99], v[142:143], v[98:99]
	v_pk_add_f32 v[96:97], v[140:141], v[96:97]
	s_waitcnt lgkmcnt(0)
	v_mfma_f32_32x32x16_bf16 v[16:31], v[132:135], v[116:119], v[16:31]
	ds_read_b128 v[120:123], v238 offset:40960
	v_add_f32_e64 v98, v180, v98
	v_add_f32_e64 v99, v181, v99
	v_add_f32_e64 v96, v178, v96
	v_add_f32_e64 v97, v179, v97
	v_pk_add_f32 v[98:99], v[184:185], v[98:99]
	v_pk_add_f32 v[96:97], v[182:183], v[96:97]
	v_mfma_f32_32x32x16_bf16 v[0:15], v[100:103], v[116:119], v[0:15]
	ds_read_b128 v[124:127], v238 offset:45056
	v_mfma_f32_32x32x16_bf16 v[80:95], v[104:107], v[108:111], v[80:95]
	ds_read_b128 v[100:103], v239 offset:32768
	v_cvt_pk_bf16_f32 v116, v178, v179
	v_cvt_pk_bf16_f32 v117, v180, v181
	v_cvt_pk_bf16_f32 v118, v182, v183
	v_cvt_pk_bf16_f32 v119, v184, v185
	v_mfma_f32_32x32x16_bf16 v[64:79], v[112:115], v[108:111], v[64:79]
	ds_read_b128 v[104:107], v239 offset:36864
	s_waitcnt lgkmcnt(0)
	v_mfma_f32_32x32x16_bf16 v[16:31], v[120:123], v[108:111], v[16:31]
	ds_read_b128 v[112:115], v239 offset:40960
	v_mfma_f32_32x32x16_bf16 v[0:15], v[124:127], v[108:111], v[0:15]
	ds_read_b128 v[120:123], v239 offset:45056
	v_mfma_f32_32x32x16_bf16 v[80:95], v[100:103], v[116:119], v[80:95]
	v_mfma_f32_32x32x16_bf16 v[64:79], v[104:107], v[116:119], v[64:79]
	s_waitcnt lgkmcnt(0)
	v_mfma_f32_32x32x16_bf16 v[16:31], v[112:115], v[116:119], v[16:31]
	v_mfma_f32_32x32x16_bf16 v[0:15], v[120:123], v[116:119], v[0:15]
	s_waitcnt vmcnt(4) lgkmcnt(0)
	v_add_f32_e32 v100, v128, v129
	v_add_f32_e32 v101, v130, v131
	v_add_f32_e32 v100, v100, v101
	v_add_f32_e32 v96, v96, v97
	v_add_f32_e32 v97, v98, v99
	s_barrier
	s_add_u32 s98, s98, 0x30000
	s_addc_u32 s99, s99, 0
	s_add_i32 m0, s58, 0x8000
	s_add_u32 s100, s100, 0x100
	global_load_lds_dwordx4 v198, s[98:99]
	s_addc_u32 s101, s101, 0
	s_add_i32 m0, s58, 0x8400
	v_add_f32_e32 v100, v177, v100
	global_load_lds_dwordx4 v194, s[98:99]
	s_add_i32 m0, s58, 0x14000
	v_add_f32_e32 v96, v96, v97
	global_load_lds_dwordx4 v196, s[100:101]
	s_add_i32 m0, s58, 0x14400
	v_add_f32_e32 v177, v100, v96
	global_load_lds_dwordx4 v192, s[100:101]
	ds_read_b128 v[96:99], v205
	ds_read_b128 v[100:103], v205 offset:8192
	s_waitcnt lgkmcnt(0)
	v_mfma_f32_32x32x16_bf16 v[112:127], v[96:99], v[160:163], 0
	ds_read_b128 v[128:131], v211
	ds_read_b128 v[132:135], v211 offset:8192
	ds_read_b128 v[136:139], v212
	v_exp_f32_e32 v140, v48
	v_exp_f32_e32 v141, v49
	v_exp_f32_e32 v142, v50
	v_exp_f32_e32 v143, v51
	ds_read_b128 v[48:51], v212 offset:8192
	v_mfma_f32_32x32x16_bf16 v[96:111], v[100:103], v[160:163], 0
	v_exp_f32_e32 v144, v52
	v_exp_f32_e32 v145, v53
	v_exp_f32_e32 v146, v54
	v_exp_f32_e32 v147, v55
	s_waitcnt lgkmcnt(0)
	v_mfma_f32_32x32x16_bf16 v[112:127], v[128:131], v[164:167], v[112:127]
	ds_read_b128 v[52:55], v213
	v_exp_f32_e32 v148, v56
	v_exp_f32_e32 v149, v57
	v_exp_f32_e32 v150, v58
	v_exp_f32_e32 v151, v59
	v_mfma_f32_32x32x16_bf16 v[96:111], v[132:135], v[164:167], v[96:111]
	ds_read_b128 v[56:59], v213 offset:8192
	v_exp_f32_e32 v128, v60
	v_exp_f32_e32 v129, v61
	v_exp_f32_e32 v130, v62
	v_exp_f32_e32 v131, v63
	v_mfma_f32_32x32x16_bf16 v[112:127], v[136:139], v[168:171], v[112:127]
	ds_read_b128 v[60:63], v206 offset:49152
	v_exp_f32_e32 v132, v32
	v_exp_f32_e32 v133, v33
	v_exp_f32_e32 v134, v34
	v_exp_f32_e32 v135, v35
	v_mfma_f32_32x32x16_bf16 v[96:111], v[48:51], v[168:171], v[96:111]
	ds_read_b128 v[32:35], v206 offset:53248
	v_exp_f32_e32 v136, v36
	v_exp_f32_e32 v137, v37
	v_exp_f32_e32 v138, v38
	v_exp_f32_e32 v139, v39
	s_waitcnt lgkmcnt(0)
	v_mfma_f32_32x32x16_bf16 v[112:127], v[52:55], v[172:175], v[112:127]
	ds_read_b128 v[36:39], v206 offset:57344
	v_exp_f32_e32 v152, v40
	v_exp_f32_e32 v153, v41
	v_exp_f32_e32 v154, v42
	v_exp_f32_e32 v155, v43
	v_mfma_f32_32x32x16_bf16 v[96:111], v[56:59], v[172:175], v[96:111]
	ds_read_b128 v[40:43], v206 offset:61440
	v_exp_f32_e32 v156, v44
	v_exp_f32_e32 v157, v45
	v_exp_f32_e32 v158, v46
	v_exp_f32_e32 v159, v47
	v_cvt_pk_bf16_f32 v44, v140, v141
	v_cvt_pk_bf16_f32 v45, v142, v143
	v_cvt_pk_bf16_f32 v46, v144, v145
	v_cvt_pk_bf16_f32 v47, v146, v147
	s_nop 1
	v_mfma_f32_32x32x16_bf16 v[80:95], v[60:63], v[44:47], v[80:95]
	ds_read_b128 v[48:51], v207 offset:49152
	v_cvt_pk_bf16_f32 v52, v148, v149
	v_cvt_pk_bf16_f32 v53, v150, v151
	v_cvt_pk_bf16_f32 v54, v128, v129
	v_cvt_pk_bf16_f32 v55, v130, v131
	v_mfma_f32_32x32x16_bf16 v[64:79], v[32:35], v[44:47], v[64:79]
	ds_read_b128 v[56:59], v207 offset:53248
	v_pk_add_f32 v[62:63], v[146:147], v[142:143]
	v_pk_add_f32 v[60:61], v[144:145], v[140:141]
	s_waitcnt lgkmcnt(0)
	v_mfma_f32_32x32x16_bf16 v[16:31], v[36:39], v[44:47], v[16:31]
	ds_read_b128 v[32:35], v207 offset:57344
	v_add_f32_e64 v62, v150, v62
	v_add_f32_e64 v63, v151, v63
	v_add_f32_e64 v60, v148, v60
	v_add_f32_e64 v61, v149, v61
	v_pk_add_f32 v[62:63], v[130:131], v[62:63]
	v_pk_add_f32 v[60:61], v[128:129], v[60:61]
	v_mfma_f32_32x32x16_bf16 v[0:15], v[40:43], v[44:47], v[0:15]
	ds_read_b128 v[36:39], v207 offset:61440
	v_mfma_f32_32x32x16_bf16 v[80:95], v[48:51], v[52:55], v[80:95]
	ds_read_b128 v[40:43], v208 offset:49152
	v_cvt_pk_bf16_f32 v44, v132, v133
	v_cvt_pk_bf16_f32 v45, v134, v135
	v_cvt_pk_bf16_f32 v46, v136, v137
	v_cvt_pk_bf16_f32 v47, v138, v139
	v_mfma_f32_32x32x16_bf16 v[64:79], v[56:59], v[52:55], v[64:79]
	ds_read_b128 v[48:51], v208 offset:53248
	v_add_f32_e64 v62, v134, v62
	v_add_f32_e64 v63, v135, v63
	v_add_f32_e64 v60, v132, v60
	v_add_f32_e64 v61, v133, v61
	v_pk_add_f32 v[62:63], v[138:139], v[62:63]
	v_pk_add_f32 v[60:61], v[136:137], v[60:61]
	s_waitcnt lgkmcnt(0)
	v_mfma_f32_32x32x16_bf16 v[16:31], v[32:35], v[52:55], v[16:31]
	ds_read_b128 v[56:59], v208 offset:57344
	v_add_f32_e64 v62, v154, v62
	v_add_f32_e64 v63, v155, v63
	v_add_f32_e64 v60, v152, v60
	v_add_f32_e64 v61, v153, v61
	v_pk_add_f32 v[130:131], v[158:159], v[62:63]
	v_pk_add_f32 v[128:129], v[156:157], v[60:61]
	v_mfma_f32_32x32x16_bf16 v[0:15], v[36:39], v[52:55], v[0:15]
	ds_read_b128 v[32:35], v208 offset:61440
	v_mfma_f32_32x32x16_bf16 v[80:95], v[40:43], v[44:47], v[80:95]
	ds_read_b128 v[36:39], v209 offset:49152
	v_cvt_pk_bf16_f32 v52, v152, v153
	v_cvt_pk_bf16_f32 v53, v154, v155
	v_cvt_pk_bf16_f32 v54, v156, v157
	v_cvt_pk_bf16_f32 v55, v158, v159
	v_mfma_f32_32x32x16_bf16 v[64:79], v[48:51], v[44:47], v[64:79]
	ds_read_b128 v[40:43], v209 offset:53248
	s_waitcnt lgkmcnt(0)
	v_mfma_f32_32x32x16_bf16 v[16:31], v[56:59], v[44:47], v[16:31]
	ds_read_b128 v[48:51], v209 offset:57344
	v_mfma_f32_32x32x16_bf16 v[0:15], v[32:35], v[44:47], v[0:15]
	ds_read_b128 v[56:59], v209 offset:61440
	v_mfma_f32_32x32x16_bf16 v[80:95], v[36:39], v[52:55], v[80:95]
	v_mfma_f32_32x32x16_bf16 v[64:79], v[40:43], v[52:55], v[64:79]
	s_waitcnt lgkmcnt(0)
	v_mfma_f32_32x32x16_bf16 v[16:31], v[48:51], v[52:55], v[16:31]
	v_mfma_f32_32x32x16_bf16 v[0:15], v[56:59], v[52:55], v[0:15]
	s_waitcnt vmcnt(4) lgkmcnt(0)
	s_barrier
	s_add_u32 s68, s98, 0x18000
	s_addc_u32 s69, s99, 0
	s_mov_b32 m0, s57
	s_add_u32 s44, s100, 0x80
	global_load_lds_dwordx4 v198, s[68:69]
	s_addc_u32 s45, s101, 0
	s_add_i32 m0, s57, 0x400
	s_nop 0
	global_load_lds_dwordx4 v194, s[68:69]
	s_add_i32 m0, s58, 0x18000
	s_nop 0
	global_load_lds_dwordx4 v196, s[44:45]
	s_add_i32 m0, s58, 0x18400
	s_nop 0
	global_load_lds_dwordx4 v192, s[44:45]
	v_exp_f32_e32 v144, v112
	ds_read_b128 v[32:35], v205 offset:16384
	ds_read_b128 v[36:39], v205 offset:24576
	s_waitcnt lgkmcnt(0)
	v_mfma_f32_32x32x16_bf16 v[48:63], v[32:35], v[160:163], 0
	ds_read_b128 v[132:135], v211 offset:16384
	ds_read_b128 v[136:139], v211 offset:24576
	ds_read_b128 v[140:143], v212 offset:16384
	v_exp_f32_e32 v145, v113
	v_exp_f32_e32 v146, v114
	v_exp_f32_e32 v147, v115
	ds_read_b128 v[112:115], v212 offset:24576
	v_mfma_f32_32x32x16_bf16 v[32:47], v[36:39], v[160:163], 0
	v_exp_f32_e32 v148, v116
	v_exp_f32_e32 v149, v117
	v_exp_f32_e32 v150, v118
	v_exp_f32_e32 v151, v119
	s_waitcnt lgkmcnt(0)
	v_mfma_f32_32x32x16_bf16 v[48:63], v[132:135], v[164:167], v[48:63]
	ds_read_b128 v[116:119], v213 offset:16384
	v_exp_f32_e32 v152, v120
	v_exp_f32_e32 v153, v121
	v_exp_f32_e32 v154, v122
	v_exp_f32_e32 v155, v123
	v_mfma_f32_32x32x16_bf16 v[32:47], v[136:139], v[164:167], v[32:47]
	ds_read_b128 v[120:123], v213 offset:24576
	v_exp_f32_e32 v156, v124
	v_exp_f32_e32 v157, v125
	v_exp_f32_e32 v158, v126
	v_exp_f32_e32 v159, v127
	v_mfma_f32_32x32x16_bf16 v[48:63], v[140:143], v[168:171], v[48:63]
	ds_read_b128 v[124:127], v236
	v_exp_f32_e32 v136, v96
	v_exp_f32_e32 v137, v97
	v_exp_f32_e32 v138, v98
	v_exp_f32_e32 v139, v99
	v_mfma_f32_32x32x16_bf16 v[32:47], v[112:115], v[168:171], v[32:47]
	ds_read_b128 v[96:99], v236 offset:4096
	v_exp_f32_e32 v140, v100
	v_exp_f32_e32 v141, v101
	v_exp_f32_e32 v142, v102
	v_exp_f32_e32 v143, v103
	s_waitcnt lgkmcnt(0)
	v_mfma_f32_32x32x16_bf16 v[48:63], v[116:119], v[172:175], v[48:63]
	ds_read_b128 v[100:103], v236 offset:8192
	v_exp_f32_e32 v178, v104
	v_exp_f32_e32 v179, v105
	v_exp_f32_e32 v180, v106
	v_exp_f32_e32 v181, v107
	v_mfma_f32_32x32x16_bf16 v[32:47], v[120:123], v[172:175], v[32:47]
	ds_read_b128 v[104:107], v236 offset:12288
	v_exp_f32_e32 v182, v108
	v_exp_f32_e32 v183, v109
	v_exp_f32_e32 v184, v110
	v_exp_f32_e32 v185, v111
	v_cvt_pk_bf16_f32 v108, v144, v145
	v_cvt_pk_bf16_f32 v109, v146, v147
	v_cvt_pk_bf16_f32 v110, v148, v149
	v_cvt_pk_bf16_f32 v111, v150, v151
	s_nop 1
	v_mfma_f32_32x32x16_bf16 v[80:95], v[124:127], v[108:111], v[80:95]
	ds_read_b128 v[112:115], v237
	v_cvt_pk_bf16_f32 v116, v152, v153
	v_cvt_pk_bf16_f32 v117, v154, v155
	v_cvt_pk_bf16_f32 v118, v156, v157
	v_cvt_pk_bf16_f32 v119, v158, v159
	v_mfma_f32_32x32x16_bf16 v[64:79], v[96:99], v[108:111], v[64:79]
	ds_read_b128 v[120:123], v237 offset:4096
	v_pk_add_f32 v[126:127], v[150:151], v[146:147]
	v_pk_add_f32 v[124:125], v[148:149], v[144:145]
	s_waitcnt lgkmcnt(0)
	v_mfma_f32_32x32x16_bf16 v[16:31], v[100:103], v[108:111], v[16:31]
	ds_read_b128 v[132:135], v237 offset:8192
	v_add_f32_e64 v98, v154, v126
	v_add_f32_e64 v99, v155, v127
	v_add_f32_e64 v96, v152, v124
	v_add_f32_e64 v97, v153, v125
	v_pk_add_f32 v[98:99], v[158:159], v[98:99]
	v_pk_add_f32 v[96:97], v[156:157], v[96:97]
	v_mfma_f32_32x32x16_bf16 v[0:15], v[104:107], v[108:111], v[0:15]
	ds_read_b128 v[100:103], v237 offset:12288
	v_mfma_f32_32x32x16_bf16 v[80:95], v[112:115], v[116:119], v[80:95]
	ds_read_b128 v[104:107], v238
	v_cvt_pk_bf16_f32 v108, v136, v137
	v_cvt_pk_bf16_f32 v109, v138, v139
	v_cvt_pk_bf16_f32 v110, v140, v141
	v_cvt_pk_bf16_f32 v111, v142, v143
	v_mfma_f32_32x32x16_bf16 v[64:79], v[120:123], v[116:119], v[64:79]
	ds_read_b128 v[112:115], v238 offset:4096
	v_add_f32_e64 v98, v138, v98
	v_add_f32_e64 v99, v139, v99
	v_add_f32_e64 v96, v136, v96
	v_add_f32_e64 v97, v137, v97
	v_pk_add_f32 v[98:99], v[142:143], v[98:99]
	v_pk_add_f32 v[96:97], v[140:141], v[96:97]
	s_waitcnt lgkmcnt(0)
	v_mfma_f32_32x32x16_bf16 v[16:31], v[132:135], v[116:119], v[16:31]
	ds_read_b128 v[120:123], v238 offset:8192
	v_add_f32_e64 v98, v180, v98
	v_add_f32_e64 v99, v181, v99
	v_add_f32_e64 v96, v178, v96
	v_add_f32_e64 v97, v179, v97
	v_pk_add_f32 v[98:99], v[184:185], v[98:99]
	v_pk_add_f32 v[96:97], v[182:183], v[96:97]
	v_mfma_f32_32x32x16_bf16 v[0:15], v[100:103], v[116:119], v[0:15]
	ds_read_b128 v[124:127], v238 offset:12288
	v_mfma_f32_32x32x16_bf16 v[80:95], v[104:107], v[108:111], v[80:95]
	ds_read_b128 v[100:103], v239
	v_cvt_pk_bf16_f32 v116, v178, v179
	v_cvt_pk_bf16_f32 v117, v180, v181
	v_cvt_pk_bf16_f32 v118, v182, v183
	v_cvt_pk_bf16_f32 v119, v184, v185
	v_mfma_f32_32x32x16_bf16 v[64:79], v[112:115], v[108:111], v[64:79]
	ds_read_b128 v[104:107], v239 offset:4096
	s_waitcnt lgkmcnt(0)
	v_mfma_f32_32x32x16_bf16 v[16:31], v[120:123], v[108:111], v[16:31]
	ds_read_b128 v[112:115], v239 offset:8192
	v_mfma_f32_32x32x16_bf16 v[0:15], v[124:127], v[108:111], v[0:15]
	ds_read_b128 v[120:123], v239 offset:12288
	v_mfma_f32_32x32x16_bf16 v[80:95], v[100:103], v[116:119], v[80:95]
	v_mfma_f32_32x32x16_bf16 v[64:79], v[104:107], v[116:119], v[64:79]
	s_waitcnt lgkmcnt(0)
	v_mfma_f32_32x32x16_bf16 v[16:31], v[112:115], v[116:119], v[16:31]
	v_mfma_f32_32x32x16_bf16 v[0:15], v[120:123], v[116:119], v[0:15]
	s_waitcnt vmcnt(4) lgkmcnt(0)
	v_add_f32_e32 v100, v128, v129
	v_add_f32_e32 v101, v130, v131
	v_add_f32_e32 v100, v100, v101
	v_add_f32_e32 v96, v96, v97
	v_add_f32_e32 v97, v98, v99
	s_barrier
	s_add_u32 s98, s98, 0x30000
	s_addc_u32 s99, s99, 0
	s_add_i32 m0, s58, 0x4000
	s_add_u32 s100, s100, 0x100
	global_load_lds_dwordx4 v198, s[98:99]
	s_addc_u32 s101, s101, 0
	s_add_i32 m0, s58, 0x4400
	v_add_f32_e32 v100, v177, v100
	global_load_lds_dwordx4 v194, s[98:99]
	s_add_i32 m0, s58, 0xc000
	v_add_f32_e32 v96, v96, v97
	global_load_lds_dwordx4 v196, s[100:101]
	s_add_i32 m0, s58, 0xc400
	v_add_f32_e32 v177, v100, v96
	global_load_lds_dwordx4 v192, s[100:101]
	ds_read_b128 v[96:99], v205 offset:32768
	ds_read_b128 v[100:103], v205 offset:40960
	s_waitcnt lgkmcnt(0)
	v_mfma_f32_32x32x16_bf16 v[112:127], v[96:99], v[160:163], 0
	ds_read_b128 v[128:131], v211 offset:32768
	ds_read_b128 v[132:135], v211 offset:40960
	ds_read_b128 v[136:139], v212 offset:32768
	v_exp_f32_e32 v140, v48
	v_exp_f32_e32 v141, v49
	v_exp_f32_e32 v142, v50
	v_exp_f32_e32 v143, v51
	ds_read_b128 v[48:51], v212 offset:40960
	v_mfma_f32_32x32x16_bf16 v[96:111], v[100:103], v[160:163], 0
	v_exp_f32_e32 v144, v52
	v_exp_f32_e32 v145, v53
	v_exp_f32_e32 v146, v54
	v_exp_f32_e32 v147, v55
	s_waitcnt lgkmcnt(0)
	v_mfma_f32_32x32x16_bf16 v[112:127], v[128:131], v[164:167], v[112:127]
	ds_read_b128 v[52:55], v213 offset:32768
	v_exp_f32_e32 v148, v56
	v_exp_f32_e32 v149, v57
	v_exp_f32_e32 v150, v58
	v_exp_f32_e32 v151, v59
	v_mfma_f32_32x32x16_bf16 v[96:111], v[132:135], v[164:167], v[96:111]
	ds_read_b128 v[56:59], v213 offset:40960
	v_exp_f32_e32 v128, v60
	v_exp_f32_e32 v129, v61
	v_exp_f32_e32 v130, v62
	v_exp_f32_e32 v131, v63
	v_mfma_f32_32x32x16_bf16 v[112:127], v[136:139], v[168:171], v[112:127]
	ds_read_b128 v[60:63], v236 offset:16384
	v_exp_f32_e32 v132, v32
	v_exp_f32_e32 v133, v33
	v_exp_f32_e32 v134, v34
	v_exp_f32_e32 v135, v35
	v_mfma_f32_32x32x16_bf16 v[96:111], v[48:51], v[168:171], v[96:111]
	ds_read_b128 v[32:35], v236 offset:20480
	v_exp_f32_e32 v136, v36
	v_exp_f32_e32 v137, v37
	v_exp_f32_e32 v138, v38
	v_exp_f32_e32 v139, v39
	s_waitcnt lgkmcnt(0)
	v_mfma_f32_32x32x16_bf16 v[112:127], v[52:55], v[172:175], v[112:127]
	ds_read_b128 v[36:39], v236 offset:24576
	v_exp_f32_e32 v152, v40
	v_exp_f32_e32 v153, v41
	v_exp_f32_e32 v154, v42
	v_exp_f32_e32 v155, v43
	v_mfma_f32_32x32x16_bf16 v[96:111], v[56:59], v[172:175], v[96:111]
	ds_read_b128 v[40:43], v236 offset:28672
	v_exp_f32_e32 v156, v44
	v_exp_f32_e32 v157, v45
	v_exp_f32_e32 v158, v46
	v_exp_f32_e32 v159, v47
	v_cvt_pk_bf16_f32 v44, v140, v141
	v_cvt_pk_bf16_f32 v45, v142, v143
	v_cvt_pk_bf16_f32 v46, v144, v145
	v_cvt_pk_bf16_f32 v47, v146, v147
	s_nop 1
	v_mfma_f32_32x32x16_bf16 v[80:95], v[60:63], v[44:47], v[80:95]
	ds_read_b128 v[48:51], v237 offset:16384
	v_cvt_pk_bf16_f32 v52, v148, v149
	v_cvt_pk_bf16_f32 v53, v150, v151
	v_cvt_pk_bf16_f32 v54, v128, v129
	v_cvt_pk_bf16_f32 v55, v130, v131
	v_mfma_f32_32x32x16_bf16 v[64:79], v[32:35], v[44:47], v[64:79]
	ds_read_b128 v[56:59], v237 offset:20480
	v_pk_add_f32 v[62:63], v[146:147], v[142:143]
	v_pk_add_f32 v[60:61], v[144:145], v[140:141]
	s_waitcnt lgkmcnt(0)
	v_mfma_f32_32x32x16_bf16 v[16:31], v[36:39], v[44:47], v[16:31]
	ds_read_b128 v[32:35], v237 offset:24576
	v_add_f32_e64 v62, v150, v62
	v_add_f32_e64 v63, v151, v63
	v_add_f32_e64 v60, v148, v60
	v_add_f32_e64 v61, v149, v61
	v_pk_add_f32 v[62:63], v[130:131], v[62:63]
	v_pk_add_f32 v[60:61], v[128:129], v[60:61]
	v_mfma_f32_32x32x16_bf16 v[0:15], v[40:43], v[44:47], v[0:15]
	ds_read_b128 v[36:39], v237 offset:28672
	v_mfma_f32_32x32x16_bf16 v[80:95], v[48:51], v[52:55], v[80:95]
	ds_read_b128 v[40:43], v238 offset:16384
	v_cvt_pk_bf16_f32 v44, v132, v133
	v_cvt_pk_bf16_f32 v45, v134, v135
	v_cvt_pk_bf16_f32 v46, v136, v137
	v_cvt_pk_bf16_f32 v47, v138, v139
	v_mfma_f32_32x32x16_bf16 v[64:79], v[56:59], v[52:55], v[64:79]
	ds_read_b128 v[48:51], v238 offset:20480
	v_add_f32_e64 v62, v134, v62
	v_add_f32_e64 v63, v135, v63
	v_add_f32_e64 v60, v132, v60
	v_add_f32_e64 v61, v133, v61
	v_pk_add_f32 v[62:63], v[138:139], v[62:63]
	v_pk_add_f32 v[60:61], v[136:137], v[60:61]
	s_waitcnt lgkmcnt(0)
	v_mfma_f32_32x32x16_bf16 v[16:31], v[32:35], v[52:55], v[16:31]
	ds_read_b128 v[56:59], v238 offset:24576
	v_add_f32_e64 v62, v154, v62
	v_add_f32_e64 v63, v155, v63
	v_add_f32_e64 v60, v152, v60
	v_add_f32_e64 v61, v153, v61
	v_pk_add_f32 v[130:131], v[158:159], v[62:63]
	v_pk_add_f32 v[128:129], v[156:157], v[60:61]
	v_mfma_f32_32x32x16_bf16 v[0:15], v[36:39], v[52:55], v[0:15]
	ds_read_b128 v[32:35], v238 offset:28672
	v_mfma_f32_32x32x16_bf16 v[80:95], v[40:43], v[44:47], v[80:95]
	ds_read_b128 v[36:39], v239 offset:16384
	v_cvt_pk_bf16_f32 v52, v152, v153
	v_cvt_pk_bf16_f32 v53, v154, v155
	v_cvt_pk_bf16_f32 v54, v156, v157
	v_cvt_pk_bf16_f32 v55, v158, v159
	v_mfma_f32_32x32x16_bf16 v[64:79], v[48:51], v[44:47], v[64:79]
	ds_read_b128 v[40:43], v239 offset:20480
	s_waitcnt lgkmcnt(0)
	v_mfma_f32_32x32x16_bf16 v[16:31], v[56:59], v[44:47], v[16:31]
	ds_read_b128 v[48:51], v239 offset:24576
	v_mfma_f32_32x32x16_bf16 v[0:15], v[32:35], v[44:47], v[0:15]
	ds_read_b128 v[56:59], v239 offset:28672
	v_mfma_f32_32x32x16_bf16 v[80:95], v[36:39], v[52:55], v[80:95]
	v_mfma_f32_32x32x16_bf16 v[64:79], v[40:43], v[52:55], v[64:79]
	s_waitcnt lgkmcnt(0)
	v_mfma_f32_32x32x16_bf16 v[16:31], v[48:51], v[52:55], v[16:31]
	v_mfma_f32_32x32x16_bf16 v[0:15], v[56:59], v[52:55], v[0:15]
	s_waitcnt vmcnt(4) lgkmcnt(0)
	s_barrier
	s_add_u32 s68, s98, 0x18000
	s_addc_u32 s69, s99, 0
	s_add_i32 m0, s57, 0x8000
	s_add_u32 s44, s100, 0x80
	global_load_lds_dwordx4 v198, s[68:69]
	s_addc_u32 s45, s101, 0
	s_add_i32 m0, s57, 0x8400
	s_nop 0
	global_load_lds_dwordx4 v194, s[68:69]
	s_add_i32 m0, s58, 0x10000
	s_nop 0
	global_load_lds_dwordx4 v196, s[44:45]
	s_add_i32 m0, s58, 0x10400
	s_nop 0
	global_load_lds_dwordx4 v192, s[44:45]
	v_exp_f32_e32 v144, v112
	ds_read_b128 v[32:35], v205
	ds_read_b128 v[36:39], v205 offset:8192
	s_waitcnt lgkmcnt(0)
	v_mfma_f32_32x32x16_bf16 v[48:63], v[32:35], v[160:163], 0
	ds_read_b128 v[132:135], v211
	ds_read_b128 v[136:139], v211 offset:8192
	ds_read_b128 v[140:143], v212
	v_exp_f32_e32 v145, v113
	v_exp_f32_e32 v146, v114
	v_exp_f32_e32 v147, v115
	ds_read_b128 v[112:115], v212 offset:8192
	v_mfma_f32_32x32x16_bf16 v[32:47], v[36:39], v[160:163], 0
	v_exp_f32_e32 v148, v116
	v_exp_f32_e32 v149, v117
	v_exp_f32_e32 v150, v118
	v_exp_f32_e32 v151, v119
	s_waitcnt lgkmcnt(0)
	v_mfma_f32_32x32x16_bf16 v[48:63], v[132:135], v[164:167], v[48:63]
	ds_read_b128 v[116:119], v213
	v_exp_f32_e32 v152, v120
	v_exp_f32_e32 v153, v121
	v_exp_f32_e32 v154, v122
	v_exp_f32_e32 v155, v123
	v_mfma_f32_32x32x16_bf16 v[32:47], v[136:139], v[164:167], v[32:47]
	ds_read_b128 v[120:123], v213 offset:8192
	v_exp_f32_e32 v156, v124
	v_exp_f32_e32 v157, v125
	v_exp_f32_e32 v158, v126
	v_exp_f32_e32 v159, v127
	v_mfma_f32_32x32x16_bf16 v[48:63], v[140:143], v[168:171], v[48:63]
	ds_read_b128 v[124:127], v236 offset:32768
	v_exp_f32_e32 v136, v96
	v_exp_f32_e32 v137, v97
	v_exp_f32_e32 v138, v98
	v_exp_f32_e32 v139, v99
	v_mfma_f32_32x32x16_bf16 v[32:47], v[112:115], v[168:171], v[32:47]
	ds_read_b128 v[96:99], v236 offset:36864
	v_exp_f32_e32 v140, v100
	v_exp_f32_e32 v141, v101
	v_exp_f32_e32 v142, v102
	v_exp_f32_e32 v143, v103
	s_waitcnt lgkmcnt(0)
	v_mfma_f32_32x32x16_bf16 v[48:63], v[116:119], v[172:175], v[48:63]
	ds_read_b128 v[100:103], v236 offset:40960
	v_exp_f32_e32 v178, v104
	v_exp_f32_e32 v179, v105
	v_exp_f32_e32 v180, v106
	v_exp_f32_e32 v181, v107
	v_mfma_f32_32x32x16_bf16 v[32:47], v[120:123], v[172:175], v[32:47]
	ds_read_b128 v[104:107], v236 offset:45056
	v_exp_f32_e32 v182, v108
	v_exp_f32_e32 v183, v109
	v_exp_f32_e32 v184, v110
	v_exp_f32_e32 v185, v111
	v_cvt_pk_bf16_f32 v108, v144, v145
	v_cvt_pk_bf16_f32 v109, v146, v147
	v_cvt_pk_bf16_f32 v110, v148, v149
	v_cvt_pk_bf16_f32 v111, v150, v151
	s_nop 1
	v_mfma_f32_32x32x16_bf16 v[80:95], v[124:127], v[108:111], v[80:95]
	ds_read_b128 v[112:115], v237 offset:32768
	v_cvt_pk_bf16_f32 v116, v152, v153
	v_cvt_pk_bf16_f32 v117, v154, v155
	v_cvt_pk_bf16_f32 v118, v156, v157
	v_cvt_pk_bf16_f32 v119, v158, v159
	v_mfma_f32_32x32x16_bf16 v[64:79], v[96:99], v[108:111], v[64:79]
	ds_read_b128 v[120:123], v237 offset:36864
	v_pk_add_f32 v[126:127], v[150:151], v[146:147]
	v_pk_add_f32 v[124:125], v[148:149], v[144:145]
	s_waitcnt lgkmcnt(0)
	v_mfma_f32_32x32x16_bf16 v[16:31], v[100:103], v[108:111], v[16:31]
	ds_read_b128 v[132:135], v237 offset:40960
	v_add_f32_e64 v98, v154, v126
	v_add_f32_e64 v99, v155, v127
	v_add_f32_e64 v96, v152, v124
	v_add_f32_e64 v97, v153, v125
	v_pk_add_f32 v[98:99], v[158:159], v[98:99]
	v_pk_add_f32 v[96:97], v[156:157], v[96:97]
	v_mfma_f32_32x32x16_bf16 v[0:15], v[104:107], v[108:111], v[0:15]
	ds_read_b128 v[100:103], v237 offset:45056
	v_mfma_f32_32x32x16_bf16 v[80:95], v[112:115], v[116:119], v[80:95]
	ds_read_b128 v[104:107], v238 offset:32768
	v_cvt_pk_bf16_f32 v108, v136, v137
	v_cvt_pk_bf16_f32 v109, v138, v139
	v_cvt_pk_bf16_f32 v110, v140, v141
	v_cvt_pk_bf16_f32 v111, v142, v143
	v_mfma_f32_32x32x16_bf16 v[64:79], v[120:123], v[116:119], v[64:79]
	ds_read_b128 v[112:115], v238 offset:36864
	v_add_f32_e64 v98, v138, v98
	v_add_f32_e64 v99, v139, v99
	v_add_f32_e64 v96, v136, v96
	v_add_f32_e64 v97, v137, v97
	v_pk_add_f32 v[98:99], v[142:143], v[98:99]
	v_pk_add_f32 v[96:97], v[140:141], v[96:97]
	s_waitcnt lgkmcnt(0)
	v_mfma_f32_32x32x16_bf16 v[16:31], v[132:135], v[116:119], v[16:31]
	ds_read_b128 v[120:123], v238 offset:40960
	v_add_f32_e64 v98, v180, v98
	v_add_f32_e64 v99, v181, v99
	v_add_f32_e64 v96, v178, v96
	v_add_f32_e64 v97, v179, v97
	v_pk_add_f32 v[98:99], v[184:185], v[98:99]
	v_pk_add_f32 v[96:97], v[182:183], v[96:97]
	v_mfma_f32_32x32x16_bf16 v[0:15], v[100:103], v[116:119], v[0:15]
	ds_read_b128 v[124:127], v238 offset:45056
	v_mfma_f32_32x32x16_bf16 v[80:95], v[104:107], v[108:111], v[80:95]
	ds_read_b128 v[100:103], v239 offset:32768
	v_cvt_pk_bf16_f32 v116, v178, v179
	v_cvt_pk_bf16_f32 v117, v180, v181
	v_cvt_pk_bf16_f32 v118, v182, v183
	v_cvt_pk_bf16_f32 v119, v184, v185
	v_mfma_f32_32x32x16_bf16 v[64:79], v[112:115], v[108:111], v[64:79]
	ds_read_b128 v[104:107], v239 offset:36864
	s_waitcnt lgkmcnt(0)
	v_mfma_f32_32x32x16_bf16 v[16:31], v[120:123], v[108:111], v[16:31]
	ds_read_b128 v[112:115], v239 offset:40960
	v_mfma_f32_32x32x16_bf16 v[0:15], v[124:127], v[108:111], v[0:15]
	ds_read_b128 v[120:123], v239 offset:45056
	v_mfma_f32_32x32x16_bf16 v[80:95], v[100:103], v[116:119], v[80:95]
	v_mfma_f32_32x32x16_bf16 v[64:79], v[104:107], v[116:119], v[64:79]
	s_waitcnt lgkmcnt(0)
	v_mfma_f32_32x32x16_bf16 v[16:31], v[112:115], v[116:119], v[16:31]
	v_mfma_f32_32x32x16_bf16 v[0:15], v[120:123], v[116:119], v[0:15]
	s_waitcnt vmcnt(4) lgkmcnt(0)
	v_add_f32_e32 v100, v128, v129
	v_add_f32_e32 v101, v130, v131
	v_add_f32_e32 v100, v100, v101
	v_add_f32_e32 v96, v96, v97
	v_add_f32_e32 v97, v98, v99
	s_barrier
	v_add_f32_e32 v100, v177, v100
	v_add_f32_e32 v96, v96, v97
	v_add_f32_e32 v177, v100, v96
	s_add_u32 s98, s98, 0x30000
	s_addc_u32 s99, s99, 0
	s_add_u32 s100, s100, 0x100
	s_addc_u32 s101, s101, 0
	s_add_i32 s21, s21, 12
	s_addk_i32 s15, 0x300
	s_add_i32 s20, s20, 0x30000
	s_cmp_lt_u32 s21, 50
	s_cbranch_scc1 .Lst0_u6_loop
	s_cmp_lt_u32 s21, 60
	s_cbranch_scc1 .Lst0_single

.Lst1_u6_loop:
	s_add_i32 m0, s58, 0x4000
	ds_read_b128 v[140:143], v206 offset:49152
	global_load_lds_dwordx4 v198, s[98:99]
	s_add_i32 m0, s58, 0x4400
	ds_read_b128 v[148:151], v206 offset:53248
	global_load_lds_dwordx4 v194, s[98:99]
	s_add_i32 m0, s58, 0x18000
	ds_read_b128 v[152:155], v206 offset:57344
	global_load_lds_dwordx4 v196, s[100:101]
	s_add_i32 m0, s58, 0x18400
	ds_read_b128 v[156:159], v206 offset:61440
	global_load_lds_dwordx4 v192, s[100:101]
	s_waitcnt lgkmcnt(0)
	v_mfma_f32_32x32x16_bf16 v[80:95], v[140:143], v[144:147], v[80:95]
	ds_read_b128 v[140:143], v207 offset:49152
	v_mfma_f32_32x32x16_bf16 v[64:79], v[148:151], v[144:147], v[64:79]
	ds_read_b128 v[148:151], v207 offset:53248
	v_mfma_f32_32x32x16_bf16 v[16:31], v[152:155], v[144:147], v[16:31]
	ds_read_b128 v[152:155], v207 offset:57344
	v_mfma_f32_32x32x16_bf16 v[0:15], v[156:159], v[144:147], v[0:15]
	ds_read_b128 v[144:147], v207 offset:61440
	s_waitcnt lgkmcnt(0)
	v_mfma_f32_32x32x16_bf16 v[80:95], v[140:143], v[128:131], v[80:95]
	ds_read_b128 v[140:143], v208 offset:49152
	v_mfma_f32_32x32x16_bf16 v[64:79], v[148:151], v[128:131], v[64:79]
	ds_read_b128 v[148:151], v208 offset:53248
	v_mfma_f32_32x32x16_bf16 v[16:31], v[152:155], v[128:131], v[16:31]
	ds_read_b128 v[152:155], v208 offset:57344
	v_mfma_f32_32x32x16_bf16 v[0:15], v[144:147], v[128:131], v[0:15]
	ds_read_b128 v[128:131], v208 offset:61440
	s_waitcnt lgkmcnt(0)
	v_mfma_f32_32x32x16_bf16 v[80:95], v[140:143], v[132:135], v[80:95]
	ds_read_b128 v[140:143], v209 offset:49152
	v_mfma_f32_32x32x16_bf16 v[64:79], v[148:151], v[132:135], v[64:79]
	ds_read_b128 v[144:147], v209 offset:53248
	v_mfma_f32_32x32x16_bf16 v[16:31], v[152:155], v[132:135], v[16:31]
	ds_read_b128 v[148:151], v209 offset:57344
	v_mfma_f32_32x32x16_bf16 v[0:15], v[128:131], v[132:135], v[0:15]
	ds_read_b128 v[128:131], v209 offset:61440
	s_waitcnt lgkmcnt(0)
	v_mfma_f32_32x32x16_bf16 v[80:95], v[140:143], v[136:139], v[80:95]
	ds_read_b128 v[132:135], v205 offset:32768
	v_mfma_f32_32x32x16_bf16 v[64:79], v[144:147], v[136:139], v[64:79]
	ds_read_b128 v[140:143], v205 offset:40960
	v_mfma_f32_32x32x16_bf16 v[16:31], v[148:151], v[136:139], v[16:31]
	ds_read_b128 v[176:179], v211 offset:32768
	v_mfma_f32_32x32x16_bf16 v[0:15], v[128:131], v[136:139], v[0:15]
	ds_read_b128 v[182:185], v211 offset:40960
	s_waitcnt lgkmcnt(0)
	v_mfma_f32_32x32x16_bf16 v[144:159], v[132:135], v[160:163], 0
	ds_read_b128 v[186:189], v212 offset:32768
	v_exp_f32_e32 v220, v112
	v_exp_f32_e32 v221, v113
	v_exp_f32_e32 v222, v114
	v_exp_f32_e32 v223, v115
	v_mfma_f32_32x32x16_bf16 v[128:143], v[140:143], v[160:163], 0
	ds_read_b128 v[216:219], v212 offset:40960
	v_exp_f32_e32 v224, v116
	v_exp_f32_e32 v225, v117
	v_exp_f32_e32 v226, v118
	v_exp_f32_e32 v227, v119
	v_mfma_f32_32x32x16_bf16 v[144:159], v[176:179], v[164:167], v[144:159]
	ds_read_b128 v[116:119], v213 offset:32768
	v_exp_f32_e32 v228, v120
	v_exp_f32_e32 v229, v121
	v_exp_f32_e32 v230, v122
	v_exp_f32_e32 v231, v123
	v_cvt_pk_bf16_f32 v112, v220, v221
	v_cvt_pk_bf16_f32 v113, v222, v223
	v_cvt_pk_bf16_f32 v114, v224, v225
	v_cvt_pk_bf16_f32 v115, v226, v227
	v_pk_add_f32 v[122:123], v[226:227], v[222:223]
	v_pk_add_f32 v[120:121], v[224:225], v[220:221]
	v_mfma_f32_32x32x16_bf16 v[128:143], v[182:185], v[164:167], v[128:143]
	ds_read_b128 v[176:179], v213 offset:40960
	v_exp_f32_e32 v124, v124
	v_exp_f32_e32 v125, v125
	v_exp_f32_e32 v126, v126
	v_exp_f32_e32 v127, v127
	s_waitcnt lgkmcnt(0)
	v_mfma_f32_32x32x16_bf16 v[144:159], v[186:189], v[168:171], v[144:159]
	v_add_f32_e64 v122, v230, v122
	v_add_f32_e64 v123, v231, v123
	v_add_f32_e64 v120, v228, v120
	v_add_f32_e64 v121, v229, v121
	v_exp_f32_e32 v182, v96
	v_exp_f32_e32 v183, v97
	v_exp_f32_e32 v184, v98
	v_exp_f32_e32 v185, v99
	v_cvt_pk_bf16_f32 v96, v228, v229
	v_cvt_pk_bf16_f32 v97, v230, v231
	v_cvt_pk_bf16_f32 v98, v124, v125
	v_cvt_pk_bf16_f32 v99, v126, v127
	v_pk_add_f32 v[122:123], v[126:127], v[122:123]
	v_pk_add_f32 v[120:121], v[124:125], v[120:121]
	v_mfma_f32_32x32x16_bf16 v[128:143], v[216:219], v[168:171], v[128:143]
	v_exp_f32_e32 v124, v100
	v_exp_f32_e32 v125, v101
	v_exp_f32_e32 v126, v102
	v_exp_f32_e32 v127, v103
	v_mfma_f32_32x32x16_bf16 v[144:159], v[116:119], v[172:175], v[144:159]
	v_exp_f32_e32 v186, v104
	v_exp_f32_e32 v187, v105
	v_exp_f32_e32 v188, v106
	v_exp_f32_e32 v189, v107
	v_pk_add_f32 v[106:107], v[184:185], v[122:123]
	v_pk_add_f32 v[104:105], v[182:183], v[120:121]
	v_cvt_pk_bf16_f32 v100, v182, v183
	v_cvt_pk_bf16_f32 v101, v184, v185
	v_cvt_pk_bf16_f32 v102, v124, v125
	v_cvt_pk_bf16_f32 v103, v126, v127
	v_pk_add_f32 v[118:119], v[126:127], v[106:107]
	v_pk_add_f32 v[116:117], v[124:125], v[104:105]
	v_mfma_f32_32x32x16_bf16 v[128:143], v[176:179], v[172:175], v[128:143]
	v_exp_f32_e32 v120, v108
	v_exp_f32_e32 v121, v109
	v_exp_f32_e32 v122, v110
	v_exp_f32_e32 v123, v111
	v_pk_add_f32 v[110:111], v[188:189], v[118:119]
	v_pk_add_f32 v[108:109], v[186:187], v[116:117]
	v_cvt_pk_bf16_f32 v104, v186, v187
	v_cvt_pk_bf16_f32 v105, v188, v189
	v_cvt_pk_bf16_f32 v106, v120, v121
	v_cvt_pk_bf16_f32 v107, v122, v123
	v_pk_add_f32 v[178:179], v[122:123], v[110:111]
	v_pk_add_f32 v[176:177], v[120:121], v[108:109]
	s_waitcnt vmcnt(4) lgkmcnt(0)
	s_barrier
	s_add_u32 s70, s98, 0x18000
	s_addc_u32 s71, s99, 0
	s_add_i32 m0, s57, 0x8000
	s_add_u32 s2, s100, 0x80
	global_load_lds_dwordx4 v198, s[70:71]
	s_addc_u32 s3, s101, 0
	s_add_i32 m0, s57, 0x8400
	ds_read_b128 v[108:111], v236
	global_load_lds_dwordx4 v194, s[70:71]
	s_add_i32 m0, s58, 0xc000
	ds_read_b128 v[116:119], v236 offset:4096
	global_load_lds_dwordx4 v196, s[2:3]
	s_add_i32 m0, s58, 0xc400
	ds_read_b128 v[120:123], v236 offset:8192
	global_load_lds_dwordx4 v192, s[2:3]
	ds_read_b128 v[124:127], v236 offset:12288
	s_waitcnt lgkmcnt(0)
	v_mfma_f32_32x32x16_bf16 v[80:95], v[108:111], v[112:115], v[80:95]
	ds_read_b128 v[108:111], v237
	v_mfma_f32_32x32x16_bf16 v[64:79], v[116:119], v[112:115], v[64:79]
	ds_read_b128 v[116:119], v237 offset:4096
	v_mfma_f32_32x32x16_bf16 v[16:31], v[120:123], v[112:115], v[16:31]
	ds_read_b128 v[120:123], v237 offset:8192
	v_mfma_f32_32x32x16_bf16 v[0:15], v[124:127], v[112:115], v[0:15]
	ds_read_b128 v[112:115], v237 offset:12288
	s_waitcnt lgkmcnt(0)
	v_mfma_f32_32x32x16_bf16 v[80:95], v[108:111], v[96:99], v[80:95]
	ds_read_b128 v[108:111], v238
	v_mfma_f32_32x32x16_bf16 v[64:79], v[116:119], v[96:99], v[64:79]
	ds_read_b128 v[116:119], v238 offset:4096
	v_mfma_f32_32x32x16_bf16 v[16:31], v[120:123], v[96:99], v[16:31]
	ds_read_b128 v[120:123], v238 offset:8192
	v_mfma_f32_32x32x16_bf16 v[0:15], v[112:115], v[96:99], v[0:15]
	ds_read_b128 v[96:99], v238 offset:12288
	s_waitcnt lgkmcnt(0)
	v_mfma_f32_32x32x16_bf16 v[80:95], v[108:111], v[100:103], v[80:95]
	ds_read_b128 v[108:111], v239
	v_mfma_f32_32x32x16_bf16 v[64:79], v[116:119], v[100:103], v[64:79]
	ds_read_b128 v[112:115], v239 offset:4096
	v_mfma_f32_32x32x16_bf16 v[16:31], v[120:123], v[100:103], v[16:31]
	ds_read_b128 v[116:119], v239 offset:8192
	v_mfma_f32_32x32x16_bf16 v[0:15], v[96:99], v[100:103], v[0:15]
	ds_read_b128 v[120:123], v239 offset:12288
	s_waitcnt lgkmcnt(0)
	v_mfma_f32_32x32x16_bf16 v[80:95], v[108:111], v[104:107], v[80:95]
	ds_read_b128 v[96:99], v205
	v_mfma_f32_32x32x16_bf16 v[64:79], v[112:115], v[104:107], v[64:79]
	ds_read_b128 v[100:103], v205 offset:8192
	v_mfma_f32_32x32x16_bf16 v[16:31], v[116:119], v[104:107], v[16:31]
	ds_read_b128 v[182:185], v211
	v_mfma_f32_32x32x16_bf16 v[0:15], v[120:123], v[104:107], v[0:15]
	ds_read_b128 v[186:189], v211 offset:8192
	s_waitcnt lgkmcnt(0)
	v_mfma_f32_32x32x16_bf16 v[112:127], v[96:99], v[160:163], 0
	ds_read_b128 v[216:219], v212
	v_exp_f32_e32 v224, v144
	v_exp_f32_e32 v225, v145
	v_exp_f32_e32 v226, v146
	v_exp_f32_e32 v227, v147
	ds_read_b128 v[220:223], v212 offset:8192
	v_mfma_f32_32x32x16_bf16 v[96:111], v[100:103], v[160:163], 0
	v_exp_f32_e32 v228, v148
	v_exp_f32_e32 v229, v149
	v_exp_f32_e32 v230, v150
	v_exp_f32_e32 v231, v151
	v_mfma_f32_32x32x16_bf16 v[112:127], v[182:185], v[164:167], v[112:127]
	ds_read_b128 v[148:151], v213
	v_exp_f32_e32 v232, v152
	v_exp_f32_e32 v233, v153
	v_exp_f32_e32 v234, v154
	v_exp_f32_e32 v235, v155
	v_cvt_pk_bf16_f32 v144, v224, v225
	v_cvt_pk_bf16_f32 v145, v226, v227
	v_cvt_pk_bf16_f32 v146, v228, v229
	v_cvt_pk_bf16_f32 v147, v230, v231
	v_pk_add_f32 v[154:155], v[230:231], v[226:227]
	v_pk_add_f32 v[152:153], v[228:229], v[224:225]
	v_mfma_f32_32x32x16_bf16 v[96:111], v[186:189], v[164:167], v[96:111]
	ds_read_b128 v[182:185], v213 offset:8192
	v_exp_f32_e32 v156, v156
	v_exp_f32_e32 v157, v157
	v_exp_f32_e32 v158, v158
	v_exp_f32_e32 v159, v159
	s_waitcnt lgkmcnt(0)
	v_mfma_f32_32x32x16_bf16 v[112:127], v[216:219], v[168:171], v[112:127]
	v_add_f32_e64 v154, v234, v154
	v_add_f32_e64 v155, v235, v155
	v_add_f32_e64 v152, v232, v152
	v_add_f32_e64 v153, v233, v153
	v_exp_f32_e32 v186, v128
	v_exp_f32_e32 v187, v129
	v_exp_f32_e32 v188, v130
	v_exp_f32_e32 v189, v131
	v_cvt_pk_bf16_f32 v128, v232, v233
	v_cvt_pk_bf16_f32 v129, v234, v235
	v_cvt_pk_bf16_f32 v130, v156, v157
	v_cvt_pk_bf16_f32 v131, v158, v159
	v_pk_add_f32 v[154:155], v[158:159], v[154:155]
	v_pk_add_f32 v[152:153], v[156:157], v[152:153]
	v_mfma_f32_32x32x16_bf16 v[96:111], v[220:223], v[168:171], v[96:111]
	v_exp_f32_e32 v156, v132
	v_exp_f32_e32 v157, v133
	v_exp_f32_e32 v158, v134
	v_exp_f32_e32 v159, v135
	v_mfma_f32_32x32x16_bf16 v[112:127], v[148:151], v[172:175], v[112:127]
	v_exp_f32_e32 v216, v136
	v_exp_f32_e32 v217, v137
	v_exp_f32_e32 v218, v138
	v_exp_f32_e32 v219, v139
	v_pk_add_f32 v[138:139], v[188:189], v[154:155]
	v_pk_add_f32 v[136:137], v[186:187], v[152:153]
	v_cvt_pk_bf16_f32 v132, v186, v187
	v_cvt_pk_bf16_f32 v133, v188, v189
	v_cvt_pk_bf16_f32 v134, v156, v157
	v_cvt_pk_bf16_f32 v135, v158, v159
	v_pk_add_f32 v[150:151], v[158:159], v[138:139]
	v_pk_add_f32 v[148:149], v[156:157], v[136:137]
	v_mfma_f32_32x32x16_bf16 v[96:111], v[182:185], v[172:175], v[96:111]
	v_exp_f32_e32 v152, v140
	v_exp_f32_e32 v153, v141
	v_exp_f32_e32 v154, v142
	v_exp_f32_e32 v155, v143
	v_pk_add_f32 v[142:143], v[218:219], v[150:151]
	v_pk_add_f32 v[140:141], v[216:217], v[148:149]
	v_cvt_pk_bf16_f32 v136, v216, v217
	v_cvt_pk_bf16_f32 v137, v218, v219
	v_cvt_pk_bf16_f32 v138, v152, v153
	v_cvt_pk_bf16_f32 v139, v154, v155
	v_pk_add_f32 v[142:143], v[154:155], v[142:143]
	v_pk_add_f32 v[140:141], v[152:153], v[140:141]
	s_waitcnt vmcnt(4) lgkmcnt(0)
	v_add_f32_e32 v148, v176, v177
	v_add_f32_e32 v149, v178, v179
	v_add_f32_e32 v148, v148, v149
	v_add_f32_e32 v140, v140, v141
	v_add_f32_e32 v141, v142, v143
	s_barrier
	s_add_u32 s98, s98, 0x30000
	s_addc_u32 s99, s99, 0
	s_mov_b32 m0, s58
	s_add_u32 s100, s100, 0x100
	global_load_lds_dwordx4 v198, s[98:99]
	s_addc_u32 s101, s101, 0
	s_add_i32 m0, s58, 0x400
	v_add_f32_e32 v148, v180, v148
	global_load_lds_dwordx4 v194, s[98:99]
	s_add_i32 m0, s58, 0x10000
	v_add_f32_e32 v140, v140, v141
	global_load_lds_dwordx4 v196, s[100:101]
	s_add_i32 m0, s58, 0x10400
	v_add_f32_e32 v180, v148, v140
	global_load_lds_dwordx4 v192, s[100:101]
	ds_read_b128 v[140:143], v236 offset:16384
	ds_read_b128 v[148:151], v236 offset:20480
	ds_read_b128 v[152:155], v236 offset:24576
	ds_read_b128 v[156:159], v236 offset:28672
	s_waitcnt lgkmcnt(0)
	v_mfma_f32_32x32x16_bf16 v[80:95], v[140:143], v[144:147], v[80:95]
	ds_read_b128 v[140:143], v237 offset:16384
	v_mfma_f32_32x32x16_bf16 v[64:79], v[148:151], v[144:147], v[64:79]
	ds_read_b128 v[148:151], v237 offset:20480
	v_mfma_f32_32x32x16_bf16 v[16:31], v[152:155], v[144:147], v[16:31]
	ds_read_b128 v[152:155], v237 offset:24576
	v_mfma_f32_32x32x16_bf16 v[0:15], v[156:159], v[144:147], v[0:15]
	ds_read_b128 v[144:147], v237 offset:28672
	s_waitcnt lgkmcnt(0)
	v_mfma_f32_32x32x16_bf16 v[80:95], v[140:143], v[128:131], v[80:95]
	ds_read_b128 v[140:143], v238 offset:16384
	v_mfma_f32_32x32x16_bf16 v[64:79], v[148:151], v[128:131], v[64:79]
	ds_read_b128 v[148:151], v238 offset:20480
	v_mfma_f32_32x32x16_bf16 v[16:31], v[152:155], v[128:131], v[16:31]
	ds_read_b128 v[152:155], v238 offset:24576
	v_mfma_f32_32x32x16_bf16 v[0:15], v[144:147], v[128:131], v[0:15]
	ds_read_b128 v[128:131], v238 offset:28672
	s_waitcnt lgkmcnt(0)
	v_mfma_f32_32x32x16_bf16 v[80:95], v[140:143], v[132:135], v[80:95]
	ds_read_b128 v[140:143], v239 offset:16384
	v_mfma_f32_32x32x16_bf16 v[64:79], v[148:151], v[132:135], v[64:79]
	ds_read_b128 v[144:147], v239 offset:20480
	v_mfma_f32_32x32x16_bf16 v[16:31], v[152:155], v[132:135], v[16:31]
	ds_read_b128 v[148:151], v239 offset:24576
	v_mfma_f32_32x32x16_bf16 v[0:15], v[128:131], v[132:135], v[0:15]
	ds_read_b128 v[128:131], v239 offset:28672
	s_waitcnt lgkmcnt(0)
	v_mfma_f32_32x32x16_bf16 v[80:95], v[140:143], v[136:139], v[80:95]
	ds_read_b128 v[132:135], v205 offset:16384
	v_mfma_f32_32x32x16_bf16 v[64:79], v[144:147], v[136:139], v[64:79]
	ds_read_b128 v[140:143], v205 offset:24576
	v_mfma_f32_32x32x16_bf16 v[16:31], v[148:151], v[136:139], v[16:31]
	ds_read_b128 v[176:179], v211 offset:16384
	v_mfma_f32_32x32x16_bf16 v[0:15], v[128:131], v[136:139], v[0:15]
	ds_read_b128 v[182:185], v211 offset:24576
	s_waitcnt lgkmcnt(0)
	v_mfma_f32_32x32x16_bf16 v[144:159], v[132:135], v[160:163], 0
	ds_read_b128 v[186:189], v212 offset:16384
	v_exp_f32_e32 v220, v112
	v_exp_f32_e32 v221, v113
	v_exp_f32_e32 v222, v114
	v_exp_f32_e32 v223, v115
	v_mfma_f32_32x32x16_bf16 v[128:143], v[140:143], v[160:163], 0
	ds_read_b128 v[216:219], v212 offset:24576
	v_exp_f32_e32 v224, v116
	v_exp_f32_e32 v225, v117
	v_exp_f32_e32 v226, v118
	v_exp_f32_e32 v227, v119
	v_mfma_f32_32x32x16_bf16 v[144:159], v[176:179], v[164:167], v[144:159]
	ds_read_b128 v[116:119], v213 offset:16384
	v_exp_f32_e32 v228, v120
	v_exp_f32_e32 v229, v121
	v_exp_f32_e32 v230, v122
	v_exp_f32_e32 v231, v123
	v_cvt_pk_bf16_f32 v112, v220, v221
	v_cvt_pk_bf16_f32 v113, v222, v223
	v_cvt_pk_bf16_f32 v114, v224, v225
	v_cvt_pk_bf16_f32 v115, v226, v227
	v_pk_add_f32 v[122:123], v[226:227], v[222:223]
	v_pk_add_f32 v[120:121], v[224:225], v[220:221]
	v_mfma_f32_32x32x16_bf16 v[128:143], v[182:185], v[164:167], v[128:143]
	ds_read_b128 v[176:179], v213 offset:24576
	v_exp_f32_e32 v124, v124
	v_exp_f32_e32 v125, v125
	v_exp_f32_e32 v126, v126
	v_exp_f32_e32 v127, v127
	s_waitcnt lgkmcnt(0)
	v_mfma_f32_32x32x16_bf16 v[144:159], v[186:189], v[168:171], v[144:159]
	v_add_f32_e64 v122, v230, v122
	v_add_f32_e64 v123, v231, v123
	v_add_f32_e64 v120, v228, v120
	v_add_f32_e64 v121, v229, v121
	v_exp_f32_e32 v182, v96
	v_exp_f32_e32 v183, v97
	v_exp_f32_e32 v184, v98
	v_exp_f32_e32 v185, v99
	v_cvt_pk_bf16_f32 v96, v228, v229
	v_cvt_pk_bf16_f32 v97, v230, v231
	v_cvt_pk_bf16_f32 v98, v124, v125
	v_cvt_pk_bf16_f32 v99, v126, v127
	v_pk_add_f32 v[122:123], v[126:127], v[122:123]
	v_pk_add_f32 v[120:121], v[124:125], v[120:121]
	v_mfma_f32_32x32x16_bf16 v[128:143], v[216:219], v[168:171], v[128:143]
	v_exp_f32_e32 v124, v100
	v_exp_f32_e32 v125, v101
	v_exp_f32_e32 v126, v102
	v_exp_f32_e32 v127, v103
	v_mfma_f32_32x32x16_bf16 v[144:159], v[116:119], v[172:175], v[144:159]
	v_exp_f32_e32 v186, v104
	v_exp_f32_e32 v187, v105
	v_exp_f32_e32 v188, v106
	v_exp_f32_e32 v189, v107
	v_pk_add_f32 v[106:107], v[184:185], v[122:123]
	v_pk_add_f32 v[104:105], v[182:183], v[120:121]
	v_cvt_pk_bf16_f32 v100, v182, v183
	v_cvt_pk_bf16_f32 v101, v184, v185
	v_cvt_pk_bf16_f32 v102, v124, v125
	v_cvt_pk_bf16_f32 v103, v126, v127
	v_pk_add_f32 v[118:119], v[126:127], v[106:107]
	v_pk_add_f32 v[116:117], v[124:125], v[104:105]
	v_mfma_f32_32x32x16_bf16 v[128:143], v[176:179], v[172:175], v[128:143]
	v_exp_f32_e32 v120, v108
	v_exp_f32_e32 v121, v109
	v_exp_f32_e32 v122, v110
	v_exp_f32_e32 v123, v111
	v_pk_add_f32 v[110:111], v[188:189], v[118:119]
	v_pk_add_f32 v[108:109], v[186:187], v[116:117]
	v_cvt_pk_bf16_f32 v104, v186, v187
	v_cvt_pk_bf16_f32 v105, v188, v189
	v_cvt_pk_bf16_f32 v106, v120, v121
	v_cvt_pk_bf16_f32 v107, v122, v123
	v_pk_add_f32 v[178:179], v[122:123], v[110:111]
	v_pk_add_f32 v[176:177], v[120:121], v[108:109]
	s_waitcnt vmcnt(4) lgkmcnt(0)
	s_barrier
	s_add_u32 s70, s98, 0x18000
	s_addc_u32 s71, s99, 0
	s_add_i32 m0, s57, 0x4000
	s_add_u32 s2, s100, 0x80
	global_load_lds_dwordx4 v198, s[70:71]
	s_addc_u32 s3, s101, 0
	s_add_i32 m0, s57, 0x4400
	ds_read_b128 v[108:111], v236 offset:32768
	global_load_lds_dwordx4 v194, s[70:71]
	s_add_i32 m0, s58, 0x14000
	ds_read_b128 v[116:119], v236 offset:36864
	global_load_lds_dwordx4 v196, s[2:3]
	s_add_i32 m0, s58, 0x14400
	ds_read_b128 v[120:123], v236 offset:40960
	global_load_lds_dwordx4 v192, s[2:3]
	ds_read_b128 v[124:127], v236 offset:45056
	s_waitcnt lgkmcnt(0)
	v_mfma_f32_32x32x16_bf16 v[80:95], v[108:111], v[112:115], v[80:95]
	ds_read_b128 v[108:111], v237 offset:32768
	v_mfma_f32_32x32x16_bf16 v[64:79], v[116:119], v[112:115], v[64:79]
	ds_read_b128 v[116:119], v237 offset:36864
	v_mfma_f32_32x32x16_bf16 v[16:31], v[120:123], v[112:115], v[16:31]
	ds_read_b128 v[120:123], v237 offset:40960
	v_mfma_f32_32x32x16_bf16 v[0:15], v[124:127], v[112:115], v[0:15]
	ds_read_b128 v[112:115], v237 offset:45056
	s_waitcnt lgkmcnt(0)
	v_mfma_f32_32x32x16_bf16 v[80:95], v[108:111], v[96:99], v[80:95]
	ds_read_b128 v[108:111], v238 offset:32768
	v_mfma_f32_32x32x16_bf16 v[64:79], v[116:119], v[96:99], v[64:79]
	ds_read_b128 v[116:119], v238 offset:36864
	v_mfma_f32_32x32x16_bf16 v[16:31], v[120:123], v[96:99], v[16:31]
	ds_read_b128 v[120:123], v238 offset:40960
	v_mfma_f32_32x32x16_bf16 v[0:15], v[112:115], v[96:99], v[0:15]
	ds_read_b128 v[96:99], v238 offset:45056
	s_waitcnt lgkmcnt(0)
	v_mfma_f32_32x32x16_bf16 v[80:95], v[108:111], v[100:103], v[80:95]
	ds_read_b128 v[108:111], v239 offset:32768
	v_mfma_f32_32x32x16_bf16 v[64:79], v[116:119], v[100:103], v[64:79]
	ds_read_b128 v[112:115], v239 offset:36864
	v_mfma_f32_32x32x16_bf16 v[16:31], v[120:123], v[100:103], v[16:31]
	ds_read_b128 v[116:119], v239 offset:40960
	v_mfma_f32_32x32x16_bf16 v[0:15], v[96:99], v[100:103], v[0:15]
	ds_read_b128 v[120:123], v239 offset:45056
	s_waitcnt lgkmcnt(0)
	v_mfma_f32_32x32x16_bf16 v[80:95], v[108:111], v[104:107], v[80:95]
	ds_read_b128 v[96:99], v205 offset:32768
	v_mfma_f32_32x32x16_bf16 v[64:79], v[112:115], v[104:107], v[64:79]
	ds_read_b128 v[100:103], v205 offset:40960
	v_mfma_f32_32x32x16_bf16 v[16:31], v[116:119], v[104:107], v[16:31]
	ds_read_b128 v[182:185], v211 offset:32768
	v_mfma_f32_32x32x16_bf16 v[0:15], v[120:123], v[104:107], v[0:15]
	ds_read_b128 v[186:189], v211 offset:40960
	s_waitcnt lgkmcnt(0)
	v_mfma_f32_32x32x16_bf16 v[112:127], v[96:99], v[160:163], 0
	ds_read_b128 v[216:219], v212 offset:32768
	v_exp_f32_e32 v224, v144
	v_exp_f32_e32 v225, v145
	v_exp_f32_e32 v226, v146
	v_exp_f32_e32 v227, v147
	ds_read_b128 v[220:223], v212 offset:40960
	v_mfma_f32_32x32x16_bf16 v[96:111], v[100:103], v[160:163], 0
	v_exp_f32_e32 v228, v148
	v_exp_f32_e32 v229, v149
	v_exp_f32_e32 v230, v150
	v_exp_f32_e32 v231, v151
	v_mfma_f32_32x32x16_bf16 v[112:127], v[182:185], v[164:167], v[112:127]
	ds_read_b128 v[148:151], v213 offset:32768
	v_exp_f32_e32 v232, v152
	v_exp_f32_e32 v233, v153
	v_exp_f32_e32 v234, v154
	v_exp_f32_e32 v235, v155
	v_cvt_pk_bf16_f32 v144, v224, v225
	v_cvt_pk_bf16_f32 v145, v226, v227
	v_cvt_pk_bf16_f32 v146, v228, v229
	v_cvt_pk_bf16_f32 v147, v230, v231
	v_pk_add_f32 v[154:155], v[230:231], v[226:227]
	v_pk_add_f32 v[152:153], v[228:229], v[224:225]
	v_mfma_f32_32x32x16_bf16 v[96:111], v[186:189], v[164:167], v[96:111]
	ds_read_b128 v[182:185], v213 offset:40960
	v_exp_f32_e32 v156, v156
	v_exp_f32_e32 v157, v157
	v_exp_f32_e32 v158, v158
	v_exp_f32_e32 v159, v159
	s_waitcnt lgkmcnt(0)
	v_mfma_f32_32x32x16_bf16 v[112:127], v[216:219], v[168:171], v[112:127]
	v_add_f32_e64 v154, v234, v154
	v_add_f32_e64 v155, v235, v155
	v_add_f32_e64 v152, v232, v152
	v_add_f32_e64 v153, v233, v153
	v_exp_f32_e32 v186, v128
	v_exp_f32_e32 v187, v129
	v_exp_f32_e32 v188, v130
	v_exp_f32_e32 v189, v131
	v_cvt_pk_bf16_f32 v128, v232, v233
	v_cvt_pk_bf16_f32 v129, v234, v235
	v_cvt_pk_bf16_f32 v130, v156, v157
	v_cvt_pk_bf16_f32 v131, v158, v159
	v_pk_add_f32 v[154:155], v[158:159], v[154:155]
	v_pk_add_f32 v[152:153], v[156:157], v[152:153]
	v_mfma_f32_32x32x16_bf16 v[96:111], v[220:223], v[168:171], v[96:111]
	v_exp_f32_e32 v156, v132
	v_exp_f32_e32 v157, v133
	v_exp_f32_e32 v158, v134
	v_exp_f32_e32 v159, v135
	v_mfma_f32_32x32x16_bf16 v[112:127], v[148:151], v[172:175], v[112:127]
	v_exp_f32_e32 v216, v136
	v_exp_f32_e32 v217, v137
	v_exp_f32_e32 v218, v138
	v_exp_f32_e32 v219, v139
	v_pk_add_f32 v[138:139], v[188:189], v[154:155]
	v_pk_add_f32 v[136:137], v[186:187], v[152:153]
	v_cvt_pk_bf16_f32 v132, v186, v187
	v_cvt_pk_bf16_f32 v133, v188, v189
	v_cvt_pk_bf16_f32 v134, v156, v157
	v_cvt_pk_bf16_f32 v135, v158, v159
	v_pk_add_f32 v[150:151], v[158:159], v[138:139]
	v_pk_add_f32 v[148:149], v[156:157], v[136:137]
	v_mfma_f32_32x32x16_bf16 v[96:111], v[182:185], v[172:175], v[96:111]
	v_exp_f32_e32 v152, v140
	v_exp_f32_e32 v153, v141
	v_exp_f32_e32 v154, v142
	v_exp_f32_e32 v155, v143
	v_pk_add_f32 v[142:143], v[218:219], v[150:151]
	v_pk_add_f32 v[140:141], v[216:217], v[148:149]
	v_cvt_pk_bf16_f32 v136, v216, v217
	v_cvt_pk_bf16_f32 v137, v218, v219
	v_cvt_pk_bf16_f32 v138, v152, v153
	v_cvt_pk_bf16_f32 v139, v154, v155
	v_pk_add_f32 v[142:143], v[154:155], v[142:143]
	v_pk_add_f32 v[140:141], v[152:153], v[140:141]
	s_waitcnt vmcnt(4) lgkmcnt(0)
	v_add_f32_e32 v148, v176, v177
	v_add_f32_e32 v149, v178, v179
	v_add_f32_e32 v148, v148, v149
	v_add_f32_e32 v140, v140, v141
	v_add_f32_e32 v141, v142, v143
	s_barrier
	s_add_u32 s98, s98, 0x30000
	s_addc_u32 s99, s99, 0
	s_add_i32 m0, s58, 0x8000
	s_add_u32 s100, s100, 0x100
	global_load_lds_dwordx4 v198, s[98:99]
	s_addc_u32 s101, s101, 0
	s_add_i32 m0, s58, 0x8400
	v_add_f32_e32 v148, v180, v148
	global_load_lds_dwordx4 v194, s[98:99]
	s_add_i32 m0, s58, 0x18000
	v_add_f32_e32 v140, v140, v141
	global_load_lds_dwordx4 v196, s[100:101]
	s_add_i32 m0, s58, 0x18400
	v_add_f32_e32 v180, v148, v140
	global_load_lds_dwordx4 v192, s[100:101]
	ds_read_b128 v[140:143], v206 offset:49152
	ds_read_b128 v[148:151], v206 offset:53248
	ds_read_b128 v[152:155], v206 offset:57344
	ds_read_b128 v[156:159], v206 offset:61440
	s_waitcnt lgkmcnt(0)
	v_mfma_f32_32x32x16_bf16 v[80:95], v[140:143], v[144:147], v[80:95]
	ds_read_b128 v[140:143], v207 offset:49152
	v_mfma_f32_32x32x16_bf16 v[64:79], v[148:151], v[144:147], v[64:79]
	ds_read_b128 v[148:151], v207 offset:53248
	v_mfma_f32_32x32x16_bf16 v[16:31], v[152:155], v[144:147], v[16:31]
	ds_read_b128 v[152:155], v207 offset:57344
	v_mfma_f32_32x32x16_bf16 v[0:15], v[156:159], v[144:147], v[0:15]
	ds_read_b128 v[144:147], v207 offset:61440
	s_waitcnt lgkmcnt(0)
	v_mfma_f32_32x32x16_bf16 v[80:95], v[140:143], v[128:131], v[80:95]
	ds_read_b128 v[140:143], v208 offset:49152
	v_mfma_f32_32x32x16_bf16 v[64:79], v[148:151], v[128:131], v[64:79]
	ds_read_b128 v[148:151], v208 offset:53248
	v_mfma_f32_32x32x16_bf16 v[16:31], v[152:155], v[128:131], v[16:31]
	ds_read_b128 v[152:155], v208 offset:57344
	v_mfma_f32_32x32x16_bf16 v[0:15], v[144:147], v[128:131], v[0:15]
	ds_read_b128 v[128:131], v208 offset:61440
	s_waitcnt lgkmcnt(0)
	v_mfma_f32_32x32x16_bf16 v[80:95], v[140:143], v[132:135], v[80:95]
	ds_read_b128 v[140:143], v209 offset:49152
	v_mfma_f32_32x32x16_bf16 v[64:79], v[148:151], v[132:135], v[64:79]
	ds_read_b128 v[144:147], v209 offset:53248
	v_mfma_f32_32x32x16_bf16 v[16:31], v[152:155], v[132:135], v[16:31]
	ds_read_b128 v[148:151], v209 offset:57344
	v_mfma_f32_32x32x16_bf16 v[0:15], v[128:131], v[132:135], v[0:15]
	ds_read_b128 v[128:131], v209 offset:61440
	s_waitcnt lgkmcnt(0)
	v_mfma_f32_32x32x16_bf16 v[80:95], v[140:143], v[136:139], v[80:95]
	ds_read_b128 v[132:135], v205
	v_mfma_f32_32x32x16_bf16 v[64:79], v[144:147], v[136:139], v[64:79]
	ds_read_b128 v[140:143], v205 offset:8192
	v_mfma_f32_32x32x16_bf16 v[16:31], v[148:151], v[136:139], v[16:31]
	ds_read_b128 v[176:179], v211
	v_mfma_f32_32x32x16_bf16 v[0:15], v[128:131], v[136:139], v[0:15]
	ds_read_b128 v[182:185], v211 offset:8192
	s_waitcnt lgkmcnt(0)
	v_mfma_f32_32x32x16_bf16 v[144:159], v[132:135], v[160:163], 0
	ds_read_b128 v[186:189], v212
	v_exp_f32_e32 v220, v112
	v_exp_f32_e32 v221, v113
	v_exp_f32_e32 v222, v114
	v_exp_f32_e32 v223, v115
	v_mfma_f32_32x32x16_bf16 v[128:143], v[140:143], v[160:163], 0
	ds_read_b128 v[216:219], v212 offset:8192
	v_exp_f32_e32 v224, v116
	v_exp_f32_e32 v225, v117
	v_exp_f32_e32 v226, v118
	v_exp_f32_e32 v227, v119
	v_mfma_f32_32x32x16_bf16 v[144:159], v[176:179], v[164:167], v[144:159]
	ds_read_b128 v[116:119], v213
	v_exp_f32_e32 v228, v120
	v_exp_f32_e32 v229, v121
	v_exp_f32_e32 v230, v122
	v_exp_f32_e32 v231, v123
	v_cvt_pk_bf16_f32 v112, v220, v221
	v_cvt_pk_bf16_f32 v113, v222, v223
	v_cvt_pk_bf16_f32 v114, v224, v225
	v_cvt_pk_bf16_f32 v115, v226, v227
	v_pk_add_f32 v[122:123], v[226:227], v[222:223]
	v_pk_add_f32 v[120:121], v[224:225], v[220:221]
	v_mfma_f32_32x32x16_bf16 v[128:143], v[182:185], v[164:167], v[128:143]
	ds_read_b128 v[176:179], v213 offset:8192
	v_exp_f32_e32 v124, v124
	v_exp_f32_e32 v125, v125
	v_exp_f32_e32 v126, v126
	v_exp_f32_e32 v127, v127
	s_waitcnt lgkmcnt(0)
	v_mfma_f32_32x32x16_bf16 v[144:159], v[186:189], v[168:171], v[144:159]
	v_add_f32_e64 v122, v230, v122
	v_add_f32_e64 v123, v231, v123
	v_add_f32_e64 v120, v228, v120
	v_add_f32_e64 v121, v229, v121
	v_exp_f32_e32 v182, v96
	v_exp_f32_e32 v183, v97
	v_exp_f32_e32 v184, v98
	v_exp_f32_e32 v185, v99
	v_cvt_pk_bf16_f32 v96, v228, v229
	v_cvt_pk_bf16_f32 v97, v230, v231
	v_cvt_pk_bf16_f32 v98, v124, v125
	v_cvt_pk_bf16_f32 v99, v126, v127
	v_pk_add_f32 v[122:123], v[126:127], v[122:123]
	v_pk_add_f32 v[120:121], v[124:125], v[120:121]
	v_mfma_f32_32x32x16_bf16 v[128:143], v[216:219], v[168:171], v[128:143]
	v_exp_f32_e32 v124, v100
	v_exp_f32_e32 v125, v101
	v_exp_f32_e32 v126, v102
	v_exp_f32_e32 v127, v103
	v_mfma_f32_32x32x16_bf16 v[144:159], v[116:119], v[172:175], v[144:159]
	v_exp_f32_e32 v186, v104
	v_exp_f32_e32 v187, v105
	v_exp_f32_e32 v188, v106
	v_exp_f32_e32 v189, v107
	v_pk_add_f32 v[106:107], v[184:185], v[122:123]
	v_pk_add_f32 v[104:105], v[182:183], v[120:121]
	v_cvt_pk_bf16_f32 v100, v182, v183
	v_cvt_pk_bf16_f32 v101, v184, v185
	v_cvt_pk_bf16_f32 v102, v124, v125
	v_cvt_pk_bf16_f32 v103, v126, v127
	v_pk_add_f32 v[118:119], v[126:127], v[106:107]
	v_pk_add_f32 v[116:117], v[124:125], v[104:105]
	v_mfma_f32_32x32x16_bf16 v[128:143], v[176:179], v[172:175], v[128:143]
	v_exp_f32_e32 v120, v108
	v_exp_f32_e32 v121, v109
	v_exp_f32_e32 v122, v110
	v_exp_f32_e32 v123, v111
	v_pk_add_f32 v[110:111], v[188:189], v[118:119]
	v_pk_add_f32 v[108:109], v[186:187], v[116:117]
	v_cvt_pk_bf16_f32 v104, v186, v187
	v_cvt_pk_bf16_f32 v105, v188, v189
	v_cvt_pk_bf16_f32 v106, v120, v121
	v_cvt_pk_bf16_f32 v107, v122, v123
	v_pk_add_f32 v[178:179], v[122:123], v[110:111]
	v_pk_add_f32 v[176:177], v[120:121], v[108:109]
	s_waitcnt vmcnt(4) lgkmcnt(0)
	s_barrier
	s_add_u32 s70, s98, 0x18000
	s_addc_u32 s71, s99, 0
	s_mov_b32 m0, s57
	s_add_u32 s2, s100, 0x80
	global_load_lds_dwordx4 v198, s[70:71]
	s_addc_u32 s3, s101, 0
	s_add_i32 m0, s57, 0x400
	ds_read_b128 v[108:111], v236
	global_load_lds_dwordx4 v194, s[70:71]
	s_add_i32 m0, s58, 0xc000
	ds_read_b128 v[116:119], v236 offset:4096
	global_load_lds_dwordx4 v196, s[2:3]
	s_add_i32 m0, s58, 0xc400
	ds_read_b128 v[120:123], v236 offset:8192
	global_load_lds_dwordx4 v192, s[2:3]
	ds_read_b128 v[124:127], v236 offset:12288
	s_waitcnt lgkmcnt(0)
	v_mfma_f32_32x32x16_bf16 v[80:95], v[108:111], v[112:115], v[80:95]
	ds_read_b128 v[108:111], v237
	v_mfma_f32_32x32x16_bf16 v[64:79], v[116:119], v[112:115], v[64:79]
	ds_read_b128 v[116:119], v237 offset:4096
	v_mfma_f32_32x32x16_bf16 v[16:31], v[120:123], v[112:115], v[16:31]
	ds_read_b128 v[120:123], v237 offset:8192
	v_mfma_f32_32x32x16_bf16 v[0:15], v[124:127], v[112:115], v[0:15]
	ds_read_b128 v[112:115], v237 offset:12288
	s_waitcnt lgkmcnt(0)
	v_mfma_f32_32x32x16_bf16 v[80:95], v[108:111], v[96:99], v[80:95]
	ds_read_b128 v[108:111], v238
	v_mfma_f32_32x32x16_bf16 v[64:79], v[116:119], v[96:99], v[64:79]
	ds_read_b128 v[116:119], v238 offset:4096
	v_mfma_f32_32x32x16_bf16 v[16:31], v[120:123], v[96:99], v[16:31]
	ds_read_b128 v[120:123], v238 offset:8192
	v_mfma_f32_32x32x16_bf16 v[0:15], v[112:115], v[96:99], v[0:15]
	ds_read_b128 v[96:99], v238 offset:12288
	s_waitcnt lgkmcnt(0)
	v_mfma_f32_32x32x16_bf16 v[80:95], v[108:111], v[100:103], v[80:95]
	ds_read_b128 v[108:111], v239
	v_mfma_f32_32x32x16_bf16 v[64:79], v[116:119], v[100:103], v[64:79]
	ds_read_b128 v[112:115], v239 offset:4096
	v_mfma_f32_32x32x16_bf16 v[16:31], v[120:123], v[100:103], v[16:31]
	ds_read_b128 v[116:119], v239 offset:8192
	v_mfma_f32_32x32x16_bf16 v[0:15], v[96:99], v[100:103], v[0:15]
	ds_read_b128 v[120:123], v239 offset:12288
	s_waitcnt lgkmcnt(0)
	v_mfma_f32_32x32x16_bf16 v[80:95], v[108:111], v[104:107], v[80:95]
	ds_read_b128 v[96:99], v205 offset:16384
	v_mfma_f32_32x32x16_bf16 v[64:79], v[112:115], v[104:107], v[64:79]
	ds_read_b128 v[100:103], v205 offset:24576
	v_mfma_f32_32x32x16_bf16 v[16:31], v[116:119], v[104:107], v[16:31]
	ds_read_b128 v[182:185], v211 offset:16384
	v_mfma_f32_32x32x16_bf16 v[0:15], v[120:123], v[104:107], v[0:15]
	ds_read_b128 v[186:189], v211 offset:24576
	s_waitcnt lgkmcnt(0)
	v_mfma_f32_32x32x16_bf16 v[112:127], v[96:99], v[160:163], 0
	ds_read_b128 v[216:219], v212 offset:16384
	v_exp_f32_e32 v224, v144
	v_exp_f32_e32 v225, v145
	v_exp_f32_e32 v226, v146
	v_exp_f32_e32 v227, v147
	ds_read_b128 v[220:223], v212 offset:24576
	v_mfma_f32_32x32x16_bf16 v[96:111], v[100:103], v[160:163], 0
	v_exp_f32_e32 v228, v148
	v_exp_f32_e32 v229, v149
	v_exp_f32_e32 v230, v150
	v_exp_f32_e32 v231, v151
	v_mfma_f32_32x32x16_bf16 v[112:127], v[182:185], v[164:167], v[112:127]
	ds_read_b128 v[148:151], v213 offset:16384
	v_exp_f32_e32 v232, v152
	v_exp_f32_e32 v233, v153
	v_exp_f32_e32 v234, v154
	v_exp_f32_e32 v235, v155
	v_cvt_pk_bf16_f32 v144, v224, v225
	v_cvt_pk_bf16_f32 v145, v226, v227
	v_cvt_pk_bf16_f32 v146, v228, v229
	v_cvt_pk_bf16_f32 v147, v230, v231
	v_pk_add_f32 v[154:155], v[230:231], v[226:227]
	v_pk_add_f32 v[152:153], v[228:229], v[224:225]
	v_mfma_f32_32x32x16_bf16 v[96:111], v[186:189], v[164:167], v[96:111]
	ds_read_b128 v[182:185], v213 offset:24576
	v_exp_f32_e32 v156, v156
	v_exp_f32_e32 v157, v157
	v_exp_f32_e32 v158, v158
	v_exp_f32_e32 v159, v159
	s_waitcnt lgkmcnt(0)
	v_mfma_f32_32x32x16_bf16 v[112:127], v[216:219], v[168:171], v[112:127]
	v_add_f32_e64 v154, v234, v154
	v_add_f32_e64 v155, v235, v155
	v_add_f32_e64 v152, v232, v152
	v_add_f32_e64 v153, v233, v153
	v_exp_f32_e32 v186, v128
	v_exp_f32_e32 v187, v129
	v_exp_f32_e32 v188, v130
	v_exp_f32_e32 v189, v131
	v_cvt_pk_bf16_f32 v128, v232, v233
	v_cvt_pk_bf16_f32 v129, v234, v235
	v_cvt_pk_bf16_f32 v130, v156, v157
	v_cvt_pk_bf16_f32 v131, v158, v159
	v_pk_add_f32 v[154:155], v[158:159], v[154:155]
	v_pk_add_f32 v[152:153], v[156:157], v[152:153]
	v_mfma_f32_32x32x16_bf16 v[96:111], v[220:223], v[168:171], v[96:111]
	v_exp_f32_e32 v156, v132
	v_exp_f32_e32 v157, v133
	v_exp_f32_e32 v158, v134
	v_exp_f32_e32 v159, v135
	v_mfma_f32_32x32x16_bf16 v[112:127], v[148:151], v[172:175], v[112:127]
	v_exp_f32_e32 v216, v136
	v_exp_f32_e32 v217, v137
	v_exp_f32_e32 v218, v138
	v_exp_f32_e32 v219, v139
	v_pk_add_f32 v[138:139], v[188:189], v[154:155]
	v_pk_add_f32 v[136:137], v[186:187], v[152:153]
	v_cvt_pk_bf16_f32 v132, v186, v187
	v_cvt_pk_bf16_f32 v133, v188, v189
	v_cvt_pk_bf16_f32 v134, v156, v157
	v_cvt_pk_bf16_f32 v135, v158, v159
	v_pk_add_f32 v[150:151], v[158:159], v[138:139]
	v_pk_add_f32 v[148:149], v[156:157], v[136:137]
	v_mfma_f32_32x32x16_bf16 v[96:111], v[182:185], v[172:175], v[96:111]
	v_exp_f32_e32 v152, v140
	v_exp_f32_e32 v153, v141
	v_exp_f32_e32 v154, v142
	v_exp_f32_e32 v155, v143
	v_pk_add_f32 v[142:143], v[218:219], v[150:151]
	v_pk_add_f32 v[140:141], v[216:217], v[148:149]
	v_cvt_pk_bf16_f32 v136, v216, v217
	v_cvt_pk_bf16_f32 v137, v218, v219
	v_cvt_pk_bf16_f32 v138, v152, v153
	v_cvt_pk_bf16_f32 v139, v154, v155
	v_pk_add_f32 v[142:143], v[154:155], v[142:143]
	v_pk_add_f32 v[140:141], v[152:153], v[140:141]
	s_waitcnt vmcnt(4) lgkmcnt(0)
	v_add_f32_e32 v148, v176, v177
	v_add_f32_e32 v149, v178, v179
	v_add_f32_e32 v148, v148, v149
	v_add_f32_e32 v140, v140, v141
	v_add_f32_e32 v141, v142, v143
	s_barrier
	s_add_u32 s98, s98, 0x30000
	s_addc_u32 s99, s99, 0
	s_add_i32 m0, s58, 0x4000
	s_add_u32 s100, s100, 0x100
	global_load_lds_dwordx4 v198, s[98:99]
	s_addc_u32 s101, s101, 0
	s_add_i32 m0, s58, 0x4400
	v_add_f32_e32 v148, v180, v148
	global_load_lds_dwordx4 v194, s[98:99]
	s_add_i32 m0, s58, 0x10000
	v_add_f32_e32 v140, v140, v141
	global_load_lds_dwordx4 v196, s[100:101]
	s_add_i32 m0, s58, 0x10400
	v_add_f32_e32 v180, v148, v140
	global_load_lds_dwordx4 v192, s[100:101]
	ds_read_b128 v[140:143], v236 offset:16384
	ds_read_b128 v[148:151], v236 offset:20480
	ds_read_b128 v[152:155], v236 offset:24576
	ds_read_b128 v[156:159], v236 offset:28672
	s_waitcnt lgkmcnt(0)
	v_mfma_f32_32x32x16_bf16 v[80:95], v[140:143], v[144:147], v[80:95]
	ds_read_b128 v[140:143], v237 offset:16384
	v_mfma_f32_32x32x16_bf16 v[64:79], v[148:151], v[144:147], v[64:79]
	ds_read_b128 v[148:151], v237 offset:20480
	v_mfma_f32_32x32x16_bf16 v[16:31], v[152:155], v[144:147], v[16:31]
	ds_read_b128 v[152:155], v237 offset:24576
	v_mfma_f32_32x32x16_bf16 v[0:15], v[156:159], v[144:147], v[0:15]
	ds_read_b128 v[144:147], v237 offset:28672
	s_waitcnt lgkmcnt(0)
	v_mfma_f32_32x32x16_bf16 v[80:95], v[140:143], v[128:131], v[80:95]
	ds_read_b128 v[140:143], v238 offset:16384
	v_mfma_f32_32x32x16_bf16 v[64:79], v[148:151], v[128:131], v[64:79]
	ds_read_b128 v[148:151], v238 offset:20480
	v_mfma_f32_32x32x16_bf16 v[16:31], v[152:155], v[128:131], v[16:31]
	ds_read_b128 v[152:155], v238 offset:24576
	v_mfma_f32_32x32x16_bf16 v[0:15], v[144:147], v[128:131], v[0:15]
	ds_read_b128 v[128:131], v238 offset:28672
	s_waitcnt lgkmcnt(0)
	v_mfma_f32_32x32x16_bf16 v[80:95], v[140:143], v[132:135], v[80:95]
	ds_read_b128 v[140:143], v239 offset:16384
	v_mfma_f32_32x32x16_bf16 v[64:79], v[148:151], v[132:135], v[64:79]
	ds_read_b128 v[144:147], v239 offset:20480
	v_mfma_f32_32x32x16_bf16 v[16:31], v[152:155], v[132:135], v[16:31]
	ds_read_b128 v[148:151], v239 offset:24576
	v_mfma_f32_32x32x16_bf16 v[0:15], v[128:131], v[132:135], v[0:15]
	ds_read_b128 v[128:131], v239 offset:28672
	s_waitcnt lgkmcnt(0)
	v_mfma_f32_32x32x16_bf16 v[80:95], v[140:143], v[136:139], v[80:95]
	ds_read_b128 v[132:135], v205 offset:32768
	v_mfma_f32_32x32x16_bf16 v[64:79], v[144:147], v[136:139], v[64:79]
	ds_read_b128 v[140:143], v205 offset:40960
	v_mfma_f32_32x32x16_bf16 v[16:31], v[148:151], v[136:139], v[16:31]
	ds_read_b128 v[176:179], v211 offset:32768
	v_mfma_f32_32x32x16_bf16 v[0:15], v[128:131], v[136:139], v[0:15]
	ds_read_b128 v[182:185], v211 offset:40960
	s_waitcnt lgkmcnt(0)
	v_mfma_f32_32x32x16_bf16 v[144:159], v[132:135], v[160:163], 0
	ds_read_b128 v[186:189], v212 offset:32768
	v_exp_f32_e32 v220, v112
	v_exp_f32_e32 v221, v113
	v_exp_f32_e32 v222, v114
	v_exp_f32_e32 v223, v115
	v_mfma_f32_32x32x16_bf16 v[128:143], v[140:143], v[160:163], 0
	ds_read_b128 v[216:219], v212 offset:40960
	v_exp_f32_e32 v224, v116
	v_exp_f32_e32 v225, v117
	v_exp_f32_e32 v226, v118
	v_exp_f32_e32 v227, v119
	v_mfma_f32_32x32x16_bf16 v[144:159], v[176:179], v[164:167], v[144:159]
	ds_read_b128 v[116:119], v213 offset:32768
	v_exp_f32_e32 v228, v120
	v_exp_f32_e32 v229, v121
	v_exp_f32_e32 v230, v122
	v_exp_f32_e32 v231, v123
	v_cvt_pk_bf16_f32 v112, v220, v221
	v_cvt_pk_bf16_f32 v113, v222, v223
	v_cvt_pk_bf16_f32 v114, v224, v225
	v_cvt_pk_bf16_f32 v115, v226, v227
	v_pk_add_f32 v[122:123], v[226:227], v[222:223]
	v_pk_add_f32 v[120:121], v[224:225], v[220:221]
	v_mfma_f32_32x32x16_bf16 v[128:143], v[182:185], v[164:167], v[128:143]
	ds_read_b128 v[176:179], v213 offset:40960
	v_exp_f32_e32 v124, v124
	v_exp_f32_e32 v125, v125
	v_exp_f32_e32 v126, v126
	v_exp_f32_e32 v127, v127
	s_waitcnt lgkmcnt(0)
	v_mfma_f32_32x32x16_bf16 v[144:159], v[186:189], v[168:171], v[144:159]
	v_add_f32_e64 v122, v230, v122
	v_add_f32_e64 v123, v231, v123
	v_add_f32_e64 v120, v228, v120
	v_add_f32_e64 v121, v229, v121
	v_exp_f32_e32 v182, v96
	v_exp_f32_e32 v183, v97
	v_exp_f32_e32 v184, v98
	v_exp_f32_e32 v185, v99
	v_cvt_pk_bf16_f32 v96, v228, v229
	v_cvt_pk_bf16_f32 v97, v230, v231
	v_cvt_pk_bf16_f32 v98, v124, v125
	v_cvt_pk_bf16_f32 v99, v126, v127
	v_pk_add_f32 v[122:123], v[126:127], v[122:123]
	v_pk_add_f32 v[120:121], v[124:125], v[120:121]
	v_mfma_f32_32x32x16_bf16 v[128:143], v[216:219], v[168:171], v[128:143]
	v_exp_f32_e32 v124, v100
	v_exp_f32_e32 v125, v101
	v_exp_f32_e32 v126, v102
	v_exp_f32_e32 v127, v103
	v_mfma_f32_32x32x16_bf16 v[144:159], v[116:119], v[172:175], v[144:159]
	v_exp_f32_e32 v186, v104
	v_exp_f32_e32 v187, v105
	v_exp_f32_e32 v188, v106
	v_exp_f32_e32 v189, v107
	v_pk_add_f32 v[106:107], v[184:185], v[122:123]
	v_pk_add_f32 v[104:105], v[182:183], v[120:121]
	v_cvt_pk_bf16_f32 v100, v182, v183
	v_cvt_pk_bf16_f32 v101, v184, v185
	v_cvt_pk_bf16_f32 v102, v124, v125
	v_cvt_pk_bf16_f32 v103, v126, v127
	v_pk_add_f32 v[118:119], v[126:127], v[106:107]
	v_pk_add_f32 v[116:117], v[124:125], v[104:105]
	v_mfma_f32_32x32x16_bf16 v[128:143], v[176:179], v[172:175], v[128:143]
	v_exp_f32_e32 v120, v108
	v_exp_f32_e32 v121, v109
	v_exp_f32_e32 v122, v110
	v_exp_f32_e32 v123, v111
	v_pk_add_f32 v[110:111], v[188:189], v[118:119]
	v_pk_add_f32 v[108:109], v[186:187], v[116:117]
	v_cvt_pk_bf16_f32 v104, v186, v187
	v_cvt_pk_bf16_f32 v105, v188, v189
	v_cvt_pk_bf16_f32 v106, v120, v121
	v_cvt_pk_bf16_f32 v107, v122, v123
	v_pk_add_f32 v[178:179], v[122:123], v[110:111]
	v_pk_add_f32 v[176:177], v[120:121], v[108:109]
	s_waitcnt vmcnt(4) lgkmcnt(0)
	s_barrier
	s_add_u32 s70, s98, 0x18000
	s_addc_u32 s71, s99, 0
	s_add_i32 m0, s57, 0x8000
	s_add_u32 s2, s100, 0x80
	global_load_lds_dwordx4 v198, s[70:71]
	s_addc_u32 s3, s101, 0
	s_add_i32 m0, s57, 0x8400
	ds_read_b128 v[108:111], v236 offset:32768
	global_load_lds_dwordx4 v194, s[70:71]
	s_add_i32 m0, s58, 0x14000
	ds_read_b128 v[116:119], v236 offset:36864
	global_load_lds_dwordx4 v196, s[2:3]
	s_add_i32 m0, s58, 0x14400
	ds_read_b128 v[120:123], v236 offset:40960
	global_load_lds_dwordx4 v192, s[2:3]
	ds_read_b128 v[124:127], v236 offset:45056
	s_waitcnt lgkmcnt(0)
	v_mfma_f32_32x32x16_bf16 v[80:95], v[108:111], v[112:115], v[80:95]
	ds_read_b128 v[108:111], v237 offset:32768
	v_mfma_f32_32x32x16_bf16 v[64:79], v[116:119], v[112:115], v[64:79]
	ds_read_b128 v[116:119], v237 offset:36864
	v_mfma_f32_32x32x16_bf16 v[16:31], v[120:123], v[112:115], v[16:31]
	ds_read_b128 v[120:123], v237 offset:40960
	v_mfma_f32_32x32x16_bf16 v[0:15], v[124:127], v[112:115], v[0:15]
	ds_read_b128 v[112:115], v237 offset:45056
	s_waitcnt lgkmcnt(0)
	v_mfma_f32_32x32x16_bf16 v[80:95], v[108:111], v[96:99], v[80:95]
	ds_read_b128 v[108:111], v238 offset:32768
	v_mfma_f32_32x32x16_bf16 v[64:79], v[116:119], v[96:99], v[64:79]
	ds_read_b128 v[116:119], v238 offset:36864
	v_mfma_f32_32x32x16_bf16 v[16:31], v[120:123], v[96:99], v[16:31]
	ds_read_b128 v[120:123], v238 offset:40960
	v_mfma_f32_32x32x16_bf16 v[0:15], v[112:115], v[96:99], v[0:15]
	ds_read_b128 v[96:99], v238 offset:45056
	s_waitcnt lgkmcnt(0)
	v_mfma_f32_32x32x16_bf16 v[80:95], v[108:111], v[100:103], v[80:95]
	ds_read_b128 v[108:111], v239 offset:32768
	v_mfma_f32_32x32x16_bf16 v[64:79], v[116:119], v[100:103], v[64:79]
	ds_read_b128 v[112:115], v239 offset:36864
	v_mfma_f32_32x32x16_bf16 v[16:31], v[120:123], v[100:103], v[16:31]
	ds_read_b128 v[116:119], v239 offset:40960
	v_mfma_f32_32x32x16_bf16 v[0:15], v[96:99], v[100:103], v[0:15]
	ds_read_b128 v[120:123], v239 offset:45056
	s_waitcnt lgkmcnt(0)
	v_mfma_f32_32x32x16_bf16 v[80:95], v[108:111], v[104:107], v[80:95]
	ds_read_b128 v[96:99], v205
	v_mfma_f32_32x32x16_bf16 v[64:79], v[112:115], v[104:107], v[64:79]
	ds_read_b128 v[100:103], v205 offset:8192
	v_mfma_f32_32x32x16_bf16 v[16:31], v[116:119], v[104:107], v[16:31]
	ds_read_b128 v[182:185], v211
	v_mfma_f32_32x32x16_bf16 v[0:15], v[120:123], v[104:107], v[0:15]
	ds_read_b128 v[186:189], v211 offset:8192
	s_waitcnt lgkmcnt(0)
	v_mfma_f32_32x32x16_bf16 v[112:127], v[96:99], v[160:163], 0
	ds_read_b128 v[216:219], v212
	v_exp_f32_e32 v224, v144
	v_exp_f32_e32 v225, v145
	v_exp_f32_e32 v226, v146
	v_exp_f32_e32 v227, v147
	ds_read_b128 v[220:223], v212 offset:8192
	v_mfma_f32_32x32x16_bf16 v[96:111], v[100:103], v[160:163], 0
	v_exp_f32_e32 v228, v148
	v_exp_f32_e32 v229, v149
	v_exp_f32_e32 v230, v150
	v_exp_f32_e32 v231, v151
	v_mfma_f32_32x32x16_bf16 v[112:127], v[182:185], v[164:167], v[112:127]
	ds_read_b128 v[148:151], v213
	v_exp_f32_e32 v232, v152
	v_exp_f32_e32 v233, v153
	v_exp_f32_e32 v234, v154
	v_exp_f32_e32 v235, v155
	v_cvt_pk_bf16_f32 v144, v224, v225
	v_cvt_pk_bf16_f32 v145, v226, v227
	v_cvt_pk_bf16_f32 v146, v228, v229
	v_cvt_pk_bf16_f32 v147, v230, v231
	v_pk_add_f32 v[154:155], v[230:231], v[226:227]
	v_pk_add_f32 v[152:153], v[228:229], v[224:225]
	v_mfma_f32_32x32x16_bf16 v[96:111], v[186:189], v[164:167], v[96:111]
	ds_read_b128 v[182:185], v213 offset:8192
	v_exp_f32_e32 v156, v156
	v_exp_f32_e32 v157, v157
	v_exp_f32_e32 v158, v158
	v_exp_f32_e32 v159, v159
	s_waitcnt lgkmcnt(0)
	v_mfma_f32_32x32x16_bf16 v[112:127], v[216:219], v[168:171], v[112:127]
	v_add_f32_e64 v154, v234, v154
	v_add_f32_e64 v155, v235, v155
	v_add_f32_e64 v152, v232, v152
	v_add_f32_e64 v153, v233, v153
	v_exp_f32_e32 v186, v128
	v_exp_f32_e32 v187, v129
	v_exp_f32_e32 v188, v130
	v_exp_f32_e32 v189, v131
	v_cvt_pk_bf16_f32 v128, v232, v233
	v_cvt_pk_bf16_f32 v129, v234, v235
	v_cvt_pk_bf16_f32 v130, v156, v157
	v_cvt_pk_bf16_f32 v131, v158, v159
	v_pk_add_f32 v[154:155], v[158:159], v[154:155]
	v_pk_add_f32 v[152:153], v[156:157], v[152:153]
	v_mfma_f32_32x32x16_bf16 v[96:111], v[220:223], v[168:171], v[96:111]
	v_exp_f32_e32 v156, v132
	v_exp_f32_e32 v157, v133
	v_exp_f32_e32 v158, v134
	v_exp_f32_e32 v159, v135
	v_mfma_f32_32x32x16_bf16 v[112:127], v[148:151], v[172:175], v[112:127]
	v_exp_f32_e32 v216, v136
	v_exp_f32_e32 v217, v137
	v_exp_f32_e32 v218, v138
	v_exp_f32_e32 v219, v139
	v_pk_add_f32 v[138:139], v[188:189], v[154:155]
	v_pk_add_f32 v[136:137], v[186:187], v[152:153]
	v_cvt_pk_bf16_f32 v132, v186, v187
	v_cvt_pk_bf16_f32 v133, v188, v189
	v_cvt_pk_bf16_f32 v134, v156, v157
	v_cvt_pk_bf16_f32 v135, v158, v159
	v_pk_add_f32 v[150:151], v[158:159], v[138:139]
	v_pk_add_f32 v[148:149], v[156:157], v[136:137]
	v_mfma_f32_32x32x16_bf16 v[96:111], v[182:185], v[172:175], v[96:111]
	v_exp_f32_e32 v152, v140
	v_exp_f32_e32 v153, v141
	v_exp_f32_e32 v154, v142
	v_exp_f32_e32 v155, v143
	v_pk_add_f32 v[142:143], v[218:219], v[150:151]
	v_pk_add_f32 v[140:141], v[216:217], v[148:149]
	v_cvt_pk_bf16_f32 v136, v216, v217
	v_cvt_pk_bf16_f32 v137, v218, v219
	v_cvt_pk_bf16_f32 v138, v152, v153
	v_cvt_pk_bf16_f32 v139, v154, v155
	v_pk_add_f32 v[142:143], v[154:155], v[142:143]
	v_pk_add_f32 v[140:141], v[152:153], v[140:141]
	s_waitcnt vmcnt(4) lgkmcnt(0)
	v_add_f32_e32 v148, v176, v177
	v_add_f32_e32 v149, v178, v179
	v_add_f32_e32 v148, v148, v149
	v_add_f32_e32 v140, v140, v141
	v_add_f32_e32 v141, v142, v143
	s_barrier
	s_add_u32 s98, s98, 0x30000
	s_addc_u32 s99, s99, 0
	s_mov_b32 m0, s58
	s_add_u32 s100, s100, 0x100
	global_load_lds_dwordx4 v198, s[98:99]
	s_addc_u32 s101, s101, 0
	s_add_i32 m0, s58, 0x400
	v_add_f32_e32 v148, v180, v148
	global_load_lds_dwordx4 v194, s[98:99]
	s_add_i32 m0, s58, 0x18000
	v_add_f32_e32 v140, v140, v141
	global_load_lds_dwordx4 v196, s[100:101]
	s_add_i32 m0, s58, 0x18400
	v_add_f32_e32 v180, v148, v140
	global_load_lds_dwordx4 v192, s[100:101]
	ds_read_b128 v[140:143], v206 offset:49152
	ds_read_b128 v[148:151], v206 offset:53248
	ds_read_b128 v[152:155], v206 offset:57344
	ds_read_b128 v[156:159], v206 offset:61440
	s_waitcnt lgkmcnt(0)
	v_mfma_f32_32x32x16_bf16 v[80:95], v[140:143], v[144:147], v[80:95]
	ds_read_b128 v[140:143], v207 offset:49152
	v_mfma_f32_32x32x16_bf16 v[64:79], v[148:151], v[144:147], v[64:79]
	ds_read_b128 v[148:151], v207 offset:53248
	v_mfma_f32_32x32x16_bf16 v[16:31], v[152:155], v[144:147], v[16:31]
	ds_read_b128 v[152:155], v207 offset:57344
	v_mfma_f32_32x32x16_bf16 v[0:15], v[156:159], v[144:147], v[0:15]
	ds_read_b128 v[144:147], v207 offset:61440
	s_waitcnt lgkmcnt(0)
	v_mfma_f32_32x32x16_bf16 v[80:95], v[140:143], v[128:131], v[80:95]
	ds_read_b128 v[140:143], v208 offset:49152
	v_mfma_f32_32x32x16_bf16 v[64:79], v[148:151], v[128:131], v[64:79]
	ds_read_b128 v[148:151], v208 offset:53248
	v_mfma_f32_32x32x16_bf16 v[16:31], v[152:155], v[128:131], v[16:31]
	ds_read_b128 v[152:155], v208 offset:57344
	v_mfma_f32_32x32x16_bf16 v[0:15], v[144:147], v[128:131], v[0:15]
	ds_read_b128 v[128:131], v208 offset:61440
	s_waitcnt lgkmcnt(0)
	v_mfma_f32_32x32x16_bf16 v[80:95], v[140:143], v[132:135], v[80:95]
	ds_read_b128 v[140:143], v209 offset:49152
	v_mfma_f32_32x32x16_bf16 v[64:79], v[148:151], v[132:135], v[64:79]
	ds_read_b128 v[144:147], v209 offset:53248
	v_mfma_f32_32x32x16_bf16 v[16:31], v[152:155], v[132:135], v[16:31]
	ds_read_b128 v[148:151], v209 offset:57344
	v_mfma_f32_32x32x16_bf16 v[0:15], v[128:131], v[132:135], v[0:15]
	ds_read_b128 v[128:131], v209 offset:61440
	s_waitcnt lgkmcnt(0)
	v_mfma_f32_32x32x16_bf16 v[80:95], v[140:143], v[136:139], v[80:95]
	ds_read_b128 v[132:135], v205 offset:16384
	v_mfma_f32_32x32x16_bf16 v[64:79], v[144:147], v[136:139], v[64:79]
	ds_read_b128 v[140:143], v205 offset:24576
	v_mfma_f32_32x32x16_bf16 v[16:31], v[148:151], v[136:139], v[16:31]
	ds_read_b128 v[176:179], v211 offset:16384
	v_mfma_f32_32x32x16_bf16 v[0:15], v[128:131], v[136:139], v[0:15]
	ds_read_b128 v[182:185], v211 offset:24576
	s_waitcnt lgkmcnt(0)
	v_mfma_f32_32x32x16_bf16 v[144:159], v[132:135], v[160:163], 0
	ds_read_b128 v[186:189], v212 offset:16384
	v_exp_f32_e32 v220, v112
	v_exp_f32_e32 v221, v113
	v_exp_f32_e32 v222, v114
	v_exp_f32_e32 v223, v115
	v_mfma_f32_32x32x16_bf16 v[128:143], v[140:143], v[160:163], 0
	ds_read_b128 v[216:219], v212 offset:24576
	v_exp_f32_e32 v224, v116
	v_exp_f32_e32 v225, v117
	v_exp_f32_e32 v226, v118
	v_exp_f32_e32 v227, v119
	v_mfma_f32_32x32x16_bf16 v[144:159], v[176:179], v[164:167], v[144:159]
	ds_read_b128 v[116:119], v213 offset:16384
	v_exp_f32_e32 v228, v120
	v_exp_f32_e32 v229, v121
	v_exp_f32_e32 v230, v122
	v_exp_f32_e32 v231, v123
	v_cvt_pk_bf16_f32 v112, v220, v221
	v_cvt_pk_bf16_f32 v113, v222, v223
	v_cvt_pk_bf16_f32 v114, v224, v225
	v_cvt_pk_bf16_f32 v115, v226, v227
	v_pk_add_f32 v[122:123], v[226:227], v[222:223]
	v_pk_add_f32 v[120:121], v[224:225], v[220:221]
	v_mfma_f32_32x32x16_bf16 v[128:143], v[182:185], v[164:167], v[128:143]
	ds_read_b128 v[176:179], v213 offset:24576
	v_exp_f32_e32 v124, v124
	v_exp_f32_e32 v125, v125
	v_exp_f32_e32 v126, v126
	v_exp_f32_e32 v127, v127
	s_waitcnt lgkmcnt(0)
	v_mfma_f32_32x32x16_bf16 v[144:159], v[186:189], v[168:171], v[144:159]
	v_add_f32_e64 v122, v230, v122
	v_add_f32_e64 v123, v231, v123
	v_add_f32_e64 v120, v228, v120
	v_add_f32_e64 v121, v229, v121
	v_exp_f32_e32 v182, v96
	v_exp_f32_e32 v183, v97
	v_exp_f32_e32 v184, v98
	v_exp_f32_e32 v185, v99
	v_cvt_pk_bf16_f32 v96, v228, v229
	v_cvt_pk_bf16_f32 v97, v230, v231
	v_cvt_pk_bf16_f32 v98, v124, v125
	v_cvt_pk_bf16_f32 v99, v126, v127
	v_pk_add_f32 v[122:123], v[126:127], v[122:123]
	v_pk_add_f32 v[120:121], v[124:125], v[120:121]
	v_mfma_f32_32x32x16_bf16 v[128:143], v[216:219], v[168:171], v[128:143]
	v_exp_f32_e32 v124, v100
	v_exp_f32_e32 v125, v101
	v_exp_f32_e32 v126, v102
	v_exp_f32_e32 v127, v103
	v_mfma_f32_32x32x16_bf16 v[144:159], v[116:119], v[172:175], v[144:159]
	v_exp_f32_e32 v186, v104
	v_exp_f32_e32 v187, v105
	v_exp_f32_e32 v188, v106
	v_exp_f32_e32 v189, v107
	v_pk_add_f32 v[106:107], v[184:185], v[122:123]
	v_pk_add_f32 v[104:105], v[182:183], v[120:121]
	v_cvt_pk_bf16_f32 v100, v182, v183
	v_cvt_pk_bf16_f32 v101, v184, v185
	v_cvt_pk_bf16_f32 v102, v124, v125
	v_cvt_pk_bf16_f32 v103, v126, v127
	v_pk_add_f32 v[118:119], v[126:127], v[106:107]
	v_pk_add_f32 v[116:117], v[124:125], v[104:105]
	v_mfma_f32_32x32x16_bf16 v[128:143], v[176:179], v[172:175], v[128:143]
	v_exp_f32_e32 v120, v108
	v_exp_f32_e32 v121, v109
	v_exp_f32_e32 v122, v110
	v_exp_f32_e32 v123, v111
	v_pk_add_f32 v[110:111], v[188:189], v[118:119]
	v_pk_add_f32 v[108:109], v[186:187], v[116:117]
	v_cvt_pk_bf16_f32 v104, v186, v187
	v_cvt_pk_bf16_f32 v105, v188, v189
	v_cvt_pk_bf16_f32 v106, v120, v121
	v_cvt_pk_bf16_f32 v107, v122, v123
	v_pk_add_f32 v[178:179], v[122:123], v[110:111]
	v_pk_add_f32 v[176:177], v[120:121], v[108:109]
	s_waitcnt vmcnt(4) lgkmcnt(0)
	s_barrier
	s_add_u32 s70, s98, 0x18000
	s_addc_u32 s71, s99, 0
	s_add_i32 m0, s57, 0x4000
	s_add_u32 s2, s100, 0x80
	global_load_lds_dwordx4 v198, s[70:71]
	s_addc_u32 s3, s101, 0
	s_add_i32 m0, s57, 0x4400
	ds_read_b128 v[108:111], v236
	global_load_lds_dwordx4 v194, s[70:71]
	s_add_i32 m0, s58, 0xc000
	ds_read_b128 v[116:119], v236 offset:4096
	global_load_lds_dwordx4 v196, s[2:3]
	s_add_i32 m0, s58, 0xc400
	ds_read_b128 v[120:123], v236 offset:8192
	global_load_lds_dwordx4 v192, s[2:3]
	ds_read_b128 v[124:127], v236 offset:12288
	s_waitcnt lgkmcnt(0)
	v_mfma_f32_32x32x16_bf16 v[80:95], v[108:111], v[112:115], v[80:95]
	ds_read_b128 v[108:111], v237
	v_mfma_f32_32x32x16_bf16 v[64:79], v[116:119], v[112:115], v[64:79]
	ds_read_b128 v[116:119], v237 offset:4096
	v_mfma_f32_32x32x16_bf16 v[16:31], v[120:123], v[112:115], v[16:31]
	ds_read_b128 v[120:123], v237 offset:8192
	v_mfma_f32_32x32x16_bf16 v[0:15], v[124:127], v[112:115], v[0:15]
	ds_read_b128 v[112:115], v237 offset:12288
	s_waitcnt lgkmcnt(0)
	v_mfma_f32_32x32x16_bf16 v[80:95], v[108:111], v[96:99], v[80:95]
	ds_read_b128 v[108:111], v238
	v_mfma_f32_32x32x16_bf16 v[64:79], v[116:119], v[96:99], v[64:79]
	ds_read_b128 v[116:119], v238 offset:4096
	v_mfma_f32_32x32x16_bf16 v[16:31], v[120:123], v[96:99], v[16:31]
	ds_read_b128 v[120:123], v238 offset:8192
	v_mfma_f32_32x32x16_bf16 v[0:15], v[112:115], v[96:99], v[0:15]
	ds_read_b128 v[96:99], v238 offset:12288
	s_waitcnt lgkmcnt(0)
	v_mfma_f32_32x32x16_bf16 v[80:95], v[108:111], v[100:103], v[80:95]
	ds_read_b128 v[108:111], v239
	v_mfma_f32_32x32x16_bf16 v[64:79], v[116:119], v[100:103], v[64:79]
	ds_read_b128 v[112:115], v239 offset:4096
	v_mfma_f32_32x32x16_bf16 v[16:31], v[120:123], v[100:103], v[16:31]
	ds_read_b128 v[116:119], v239 offset:8192
	v_mfma_f32_32x32x16_bf16 v[0:15], v[96:99], v[100:103], v[0:15]
	ds_read_b128 v[120:123], v239 offset:12288
	s_waitcnt lgkmcnt(0)
	v_mfma_f32_32x32x16_bf16 v[80:95], v[108:111], v[104:107], v[80:95]
	ds_read_b128 v[96:99], v205 offset:32768
	v_mfma_f32_32x32x16_bf16 v[64:79], v[112:115], v[104:107], v[64:79]
	ds_read_b128 v[100:103], v205 offset:40960
	v_mfma_f32_32x32x16_bf16 v[16:31], v[116:119], v[104:107], v[16:31]
	ds_read_b128 v[182:185], v211 offset:32768
	v_mfma_f32_32x32x16_bf16 v[0:15], v[120:123], v[104:107], v[0:15]
	ds_read_b128 v[186:189], v211 offset:40960
	s_waitcnt lgkmcnt(0)
	v_mfma_f32_32x32x16_bf16 v[112:127], v[96:99], v[160:163], 0
	ds_read_b128 v[216:219], v212 offset:32768
	v_exp_f32_e32 v224, v144
	v_exp_f32_e32 v225, v145
	v_exp_f32_e32 v226, v146
	v_exp_f32_e32 v227, v147
	ds_read_b128 v[220:223], v212 offset:40960
	v_mfma_f32_32x32x16_bf16 v[96:111], v[100:103], v[160:163], 0
	v_exp_f32_e32 v228, v148
	v_exp_f32_e32 v229, v149
	v_exp_f32_e32 v230, v150
	v_exp_f32_e32 v231, v151
	v_mfma_f32_32x32x16_bf16 v[112:127], v[182:185], v[164:167], v[112:127]
	ds_read_b128 v[148:151], v213 offset:32768
	v_exp_f32_e32 v232, v152
	v_exp_f32_e32 v233, v153
	v_exp_f32_e32 v234, v154
	v_exp_f32_e32 v235, v155
	v_cvt_pk_bf16_f32 v144, v224, v225
	v_cvt_pk_bf16_f32 v145, v226, v227
	v_cvt_pk_bf16_f32 v146, v228, v229
	v_cvt_pk_bf16_f32 v147, v230, v231
	v_pk_add_f32 v[154:155], v[230:231], v[226:227]
	v_pk_add_f32 v[152:153], v[228:229], v[224:225]
	v_mfma_f32_32x32x16_bf16 v[96:111], v[186:189], v[164:167], v[96:111]
	ds_read_b128 v[182:185], v213 offset:40960
	v_exp_f32_e32 v156, v156
	v_exp_f32_e32 v157, v157
	v_exp_f32_e32 v158, v158
	v_exp_f32_e32 v159, v159
	s_waitcnt lgkmcnt(0)
	v_mfma_f32_32x32x16_bf16 v[112:127], v[216:219], v[168:171], v[112:127]
	v_add_f32_e64 v154, v234, v154
	v_add_f32_e64 v155, v235, v155
	v_add_f32_e64 v152, v232, v152
	v_add_f32_e64 v153, v233, v153
	v_exp_f32_e32 v186, v128
	v_exp_f32_e32 v187, v129
	v_exp_f32_e32 v188, v130
	v_exp_f32_e32 v189, v131
	v_cvt_pk_bf16_f32 v128, v232, v233
	v_cvt_pk_bf16_f32 v129, v234, v235
	v_cvt_pk_bf16_f32 v130, v156, v157
	v_cvt_pk_bf16_f32 v131, v158, v159
	v_pk_add_f32 v[154:155], v[158:159], v[154:155]
	v_pk_add_f32 v[152:153], v[156:157], v[152:153]
	v_mfma_f32_32x32x16_bf16 v[96:111], v[220:223], v[168:171], v[96:111]
	v_exp_f32_e32 v156, v132
	v_exp_f32_e32 v157, v133
	v_exp_f32_e32 v158, v134
	v_exp_f32_e32 v159, v135
	v_mfma_f32_32x32x16_bf16 v[112:127], v[148:151], v[172:175], v[112:127]
	v_exp_f32_e32 v216, v136
	v_exp_f32_e32 v217, v137
	v_exp_f32_e32 v218, v138
	v_exp_f32_e32 v219, v139
	v_pk_add_f32 v[138:139], v[188:189], v[154:155]
	v_pk_add_f32 v[136:137], v[186:187], v[152:153]
	v_cvt_pk_bf16_f32 v132, v186, v187
	v_cvt_pk_bf16_f32 v133, v188, v189
	v_cvt_pk_bf16_f32 v134, v156, v157
	v_cvt_pk_bf16_f32 v135, v158, v159
	v_pk_add_f32 v[150:151], v[158:159], v[138:139]
	v_pk_add_f32 v[148:149], v[156:157], v[136:137]
	v_mfma_f32_32x32x16_bf16 v[96:111], v[182:185], v[172:175], v[96:111]
	v_exp_f32_e32 v152, v140
	v_exp_f32_e32 v153, v141
	v_exp_f32_e32 v154, v142
	v_exp_f32_e32 v155, v143
	v_pk_add_f32 v[142:143], v[218:219], v[150:151]
	v_pk_add_f32 v[140:141], v[216:217], v[148:149]
	v_cvt_pk_bf16_f32 v136, v216, v217
	v_cvt_pk_bf16_f32 v137, v218, v219
	v_cvt_pk_bf16_f32 v138, v152, v153
	v_cvt_pk_bf16_f32 v139, v154, v155
	v_pk_add_f32 v[142:143], v[154:155], v[142:143]
	v_pk_add_f32 v[140:141], v[152:153], v[140:141]
	s_waitcnt vmcnt(4) lgkmcnt(0)
	v_add_f32_e32 v148, v176, v177
	v_add_f32_e32 v149, v178, v179
	v_add_f32_e32 v148, v148, v149
	v_add_f32_e32 v140, v140, v141
	v_add_f32_e32 v141, v142, v143
	s_barrier
	s_add_u32 s98, s98, 0x30000
	s_addc_u32 s99, s99, 0
	s_add_i32 m0, s58, 0x8000
	s_add_u32 s100, s100, 0x100
	global_load_lds_dwordx4 v198, s[98:99]
	s_addc_u32 s101, s101, 0
	s_add_i32 m0, s58, 0x8400
	v_add_f32_e32 v148, v180, v148
	global_load_lds_dwordx4 v194, s[98:99]
	s_add_i32 m0, s58, 0x10000
	v_add_f32_e32 v140, v140, v141
	global_load_lds_dwordx4 v196, s[100:101]
	s_add_i32 m0, s58, 0x10400
	v_add_f32_e32 v180, v148, v140
	global_load_lds_dwordx4 v192, s[100:101]
	ds_read_b128 v[140:143], v236 offset:16384
	ds_read_b128 v[148:151], v236 offset:20480
	ds_read_b128 v[152:155], v236 offset:24576
	ds_read_b128 v[156:159], v236 offset:28672
	s_waitcnt lgkmcnt(0)
	v_mfma_f32_32x32x16_bf16 v[80:95], v[140:143], v[144:147], v[80:95]
	ds_read_b128 v[140:143], v237 offset:16384
	v_mfma_f32_32x32x16_bf16 v[64:79], v[148:151], v[144:147], v[64:79]
	ds_read_b128 v[148:151], v237 offset:20480
	v_mfma_f32_32x32x16_bf16 v[16:31], v[152:155], v[144:147], v[16:31]
	ds_read_b128 v[152:155], v237 offset:24576
	v_mfma_f32_32x32x16_bf16 v[0:15], v[156:159], v[144:147], v[0:15]
	ds_read_b128 v[144:147], v237 offset:28672
	s_waitcnt lgkmcnt(0)
	v_mfma_f32_32x32x16_bf16 v[80:95], v[140:143], v[128:131], v[80:95]
	ds_read_b128 v[140:143], v238 offset:16384
	v_mfma_f32_32x32x16_bf16 v[64:79], v[148:151], v[128:131], v[64:79]
	ds_read_b128 v[148:151], v238 offset:20480
	v_mfma_f32_32x32x16_bf16 v[16:31], v[152:155], v[128:131], v[16:31]
	ds_read_b128 v[152:155], v238 offset:24576
	v_mfma_f32_32x32x16_bf16 v[0:15], v[144:147], v[128:131], v[0:15]
	ds_read_b128 v[128:131], v238 offset:28672
	s_waitcnt lgkmcnt(0)
	v_mfma_f32_32x32x16_bf16 v[80:95], v[140:143], v[132:135], v[80:95]
	ds_read_b128 v[140:143], v239 offset:16384
	v_mfma_f32_32x32x16_bf16 v[64:79], v[148:151], v[132:135], v[64:79]
	ds_read_b128 v[144:147], v239 offset:20480
	v_mfma_f32_32x32x16_bf16 v[16:31], v[152:155], v[132:135], v[16:31]
	ds_read_b128 v[148:151], v239 offset:24576
	v_mfma_f32_32x32x16_bf16 v[0:15], v[128:131], v[132:135], v[0:15]
	ds_read_b128 v[128:131], v239 offset:28672
	s_waitcnt lgkmcnt(0)
	v_mfma_f32_32x32x16_bf16 v[80:95], v[140:143], v[136:139], v[80:95]
	ds_read_b128 v[132:135], v205
	v_mfma_f32_32x32x16_bf16 v[64:79], v[144:147], v[136:139], v[64:79]
	ds_read_b128 v[140:143], v205 offset:8192
	v_mfma_f32_32x32x16_bf16 v[16:31], v[148:151], v[136:139], v[16:31]
	ds_read_b128 v[176:179], v211
	v_mfma_f32_32x32x16_bf16 v[0:15], v[128:131], v[136:139], v[0:15]
	ds_read_b128 v[182:185], v211 offset:8192
	s_waitcnt lgkmcnt(0)
	v_mfma_f32_32x32x16_bf16 v[144:159], v[132:135], v[160:163], 0
	ds_read_b128 v[186:189], v212
	v_exp_f32_e32 v220, v112
	v_exp_f32_e32 v221, v113
	v_exp_f32_e32 v222, v114
	v_exp_f32_e32 v223, v115
	v_mfma_f32_32x32x16_bf16 v[128:143], v[140:143], v[160:163], 0
	ds_read_b128 v[216:219], v212 offset:8192
	v_exp_f32_e32 v224, v116
	v_exp_f32_e32 v225, v117
	v_exp_f32_e32 v226, v118
	v_exp_f32_e32 v227, v119
	v_mfma_f32_32x32x16_bf16 v[144:159], v[176:179], v[164:167], v[144:159]
	ds_read_b128 v[116:119], v213
	v_exp_f32_e32 v228, v120
	v_exp_f32_e32 v229, v121
	v_exp_f32_e32 v230, v122
	v_exp_f32_e32 v231, v123
	v_cvt_pk_bf16_f32 v112, v220, v221
	v_cvt_pk_bf16_f32 v113, v222, v223
	v_cvt_pk_bf16_f32 v114, v224, v225
	v_cvt_pk_bf16_f32 v115, v226, v227
	v_pk_add_f32 v[122:123], v[226:227], v[222:223]
	v_pk_add_f32 v[120:121], v[224:225], v[220:221]
	v_mfma_f32_32x32x16_bf16 v[128:143], v[182:185], v[164:167], v[128:143]
	ds_read_b128 v[176:179], v213 offset:8192
	v_exp_f32_e32 v124, v124
	v_exp_f32_e32 v125, v125
	v_exp_f32_e32 v126, v126
	v_exp_f32_e32 v127, v127
	s_waitcnt lgkmcnt(0)
	v_mfma_f32_32x32x16_bf16 v[144:159], v[186:189], v[168:171], v[144:159]
	v_add_f32_e64 v122, v230, v122
	v_add_f32_e64 v123, v231, v123
	v_add_f32_e64 v120, v228, v120
	v_add_f32_e64 v121, v229, v121
	v_exp_f32_e32 v182, v96
	v_exp_f32_e32 v183, v97
	v_exp_f32_e32 v184, v98
	v_exp_f32_e32 v185, v99
	v_cvt_pk_bf16_f32 v96, v228, v229
	v_cvt_pk_bf16_f32 v97, v230, v231
	v_cvt_pk_bf16_f32 v98, v124, v125
	v_cvt_pk_bf16_f32 v99, v126, v127
	v_pk_add_f32 v[122:123], v[126:127], v[122:123]
	v_pk_add_f32 v[120:121], v[124:125], v[120:121]
	v_mfma_f32_32x32x16_bf16 v[128:143], v[216:219], v[168:171], v[128:143]
	v_exp_f32_e32 v124, v100
	v_exp_f32_e32 v125, v101
	v_exp_f32_e32 v126, v102
	v_exp_f32_e32 v127, v103
	v_mfma_f32_32x32x16_bf16 v[144:159], v[116:119], v[172:175], v[144:159]
	v_exp_f32_e32 v186, v104
	v_exp_f32_e32 v187, v105
	v_exp_f32_e32 v188, v106
	v_exp_f32_e32 v189, v107
	v_pk_add_f32 v[106:107], v[184:185], v[122:123]
	v_pk_add_f32 v[104:105], v[182:183], v[120:121]
	v_cvt_pk_bf16_f32 v100, v182, v183
	v_cvt_pk_bf16_f32 v101, v184, v185
	v_cvt_pk_bf16_f32 v102, v124, v125
	v_cvt_pk_bf16_f32 v103, v126, v127
	v_pk_add_f32 v[118:119], v[126:127], v[106:107]
	v_pk_add_f32 v[116:117], v[124:125], v[104:105]
	v_mfma_f32_32x32x16_bf16 v[128:143], v[176:179], v[172:175], v[128:143]
	v_exp_f32_e32 v120, v108
	v_exp_f32_e32 v121, v109
	v_exp_f32_e32 v122, v110
	v_exp_f32_e32 v123, v111
	v_pk_add_f32 v[110:111], v[188:189], v[118:119]
	v_pk_add_f32 v[108:109], v[186:187], v[116:117]
	v_cvt_pk_bf16_f32 v104, v186, v187
	v_cvt_pk_bf16_f32 v105, v188, v189
	v_cvt_pk_bf16_f32 v106, v120, v121
	v_cvt_pk_bf16_f32 v107, v122, v123
	v_pk_add_f32 v[178:179], v[122:123], v[110:111]
	v_pk_add_f32 v[176:177], v[120:121], v[108:109]
	s_waitcnt vmcnt(4) lgkmcnt(0)
	s_barrier
	s_add_u32 s70, s98, 0x18000
	s_addc_u32 s71, s99, 0
	s_mov_b32 m0, s57
	s_add_u32 s2, s100, 0x80
	global_load_lds_dwordx4 v198, s[70:71]
	s_addc_u32 s3, s101, 0
	s_add_i32 m0, s57, 0x400
	ds_read_b128 v[108:111], v236 offset:32768
	global_load_lds_dwordx4 v194, s[70:71]
	s_add_i32 m0, s58, 0x14000
	ds_read_b128 v[116:119], v236 offset:36864
	global_load_lds_dwordx4 v196, s[2:3]
	s_add_i32 m0, s58, 0x14400
	ds_read_b128 v[120:123], v236 offset:40960
	global_load_lds_dwordx4 v192, s[2:3]
	ds_read_b128 v[124:127], v236 offset:45056
	s_waitcnt lgkmcnt(0)
	v_mfma_f32_32x32x16_bf16 v[80:95], v[108:111], v[112:115], v[80:95]
	ds_read_b128 v[108:111], v237 offset:32768
	v_mfma_f32_32x32x16_bf16 v[64:79], v[116:119], v[112:115], v[64:79]
	ds_read_b128 v[116:119], v237 offset:36864
	v_mfma_f32_32x32x16_bf16 v[16:31], v[120:123], v[112:115], v[16:31]
	ds_read_b128 v[120:123], v237 offset:40960
	v_mfma_f32_32x32x16_bf16 v[0:15], v[124:127], v[112:115], v[0:15]
	ds_read_b128 v[112:115], v237 offset:45056
	s_waitcnt lgkmcnt(0)
	v_mfma_f32_32x32x16_bf16 v[80:95], v[108:111], v[96:99], v[80:95]
	ds_read_b128 v[108:111], v238 offset:32768
	v_mfma_f32_32x32x16_bf16 v[64:79], v[116:119], v[96:99], v[64:79]
	ds_read_b128 v[116:119], v238 offset:36864
	v_mfma_f32_32x32x16_bf16 v[16:31], v[120:123], v[96:99], v[16:31]
	ds_read_b128 v[120:123], v238 offset:40960
	v_mfma_f32_32x32x16_bf16 v[0:15], v[112:115], v[96:99], v[0:15]
	ds_read_b128 v[96:99], v238 offset:45056
	s_waitcnt lgkmcnt(0)
	v_mfma_f32_32x32x16_bf16 v[80:95], v[108:111], v[100:103], v[80:95]
	ds_read_b128 v[108:111], v239 offset:32768
	v_mfma_f32_32x32x16_bf16 v[64:79], v[116:119], v[100:103], v[64:79]
	ds_read_b128 v[112:115], v239 offset:36864
	v_mfma_f32_32x32x16_bf16 v[16:31], v[120:123], v[100:103], v[16:31]
	ds_read_b128 v[116:119], v239 offset:40960
	v_mfma_f32_32x32x16_bf16 v[0:15], v[96:99], v[100:103], v[0:15]
	ds_read_b128 v[120:123], v239 offset:45056
	s_waitcnt lgkmcnt(0)
	v_mfma_f32_32x32x16_bf16 v[80:95], v[108:111], v[104:107], v[80:95]
	ds_read_b128 v[96:99], v205 offset:16384
	v_mfma_f32_32x32x16_bf16 v[64:79], v[112:115], v[104:107], v[64:79]
	ds_read_b128 v[100:103], v205 offset:24576
	v_mfma_f32_32x32x16_bf16 v[16:31], v[116:119], v[104:107], v[16:31]
	ds_read_b128 v[182:185], v211 offset:16384
	v_mfma_f32_32x32x16_bf16 v[0:15], v[120:123], v[104:107], v[0:15]
	ds_read_b128 v[186:189], v211 offset:24576
	s_waitcnt lgkmcnt(0)
	v_mfma_f32_32x32x16_bf16 v[112:127], v[96:99], v[160:163], 0
	ds_read_b128 v[216:219], v212 offset:16384
	v_exp_f32_e32 v224, v144
	v_exp_f32_e32 v225, v145
	v_exp_f32_e32 v226, v146
	v_exp_f32_e32 v227, v147
	ds_read_b128 v[220:223], v212 offset:24576
	v_mfma_f32_32x32x16_bf16 v[96:111], v[100:103], v[160:163], 0
	v_exp_f32_e32 v228, v148
	v_exp_f32_e32 v229, v149
	v_exp_f32_e32 v230, v150
	v_exp_f32_e32 v231, v151
	v_mfma_f32_32x32x16_bf16 v[112:127], v[182:185], v[164:167], v[112:127]
	ds_read_b128 v[148:151], v213 offset:16384
	v_exp_f32_e32 v232, v152
	v_exp_f32_e32 v233, v153
	v_exp_f32_e32 v234, v154
	v_exp_f32_e32 v235, v155
	v_cvt_pk_bf16_f32 v144, v224, v225
	v_cvt_pk_bf16_f32 v145, v226, v227
	v_cvt_pk_bf16_f32 v146, v228, v229
	v_cvt_pk_bf16_f32 v147, v230, v231
	v_pk_add_f32 v[154:155], v[230:231], v[226:227]
	v_pk_add_f32 v[152:153], v[228:229], v[224:225]
	v_mfma_f32_32x32x16_bf16 v[96:111], v[186:189], v[164:167], v[96:111]
	ds_read_b128 v[182:185], v213 offset:24576
	v_exp_f32_e32 v156, v156
	v_exp_f32_e32 v157, v157
	v_exp_f32_e32 v158, v158
	v_exp_f32_e32 v159, v159
	s_waitcnt lgkmcnt(0)
	v_mfma_f32_32x32x16_bf16 v[112:127], v[216:219], v[168:171], v[112:127]
	v_add_f32_e64 v154, v234, v154
	v_add_f32_e64 v155, v235, v155
	v_add_f32_e64 v152, v232, v152
	v_add_f32_e64 v153, v233, v153
	v_exp_f32_e32 v186, v128
	v_exp_f32_e32 v187, v129
	v_exp_f32_e32 v188, v130
	v_exp_f32_e32 v189, v131
	v_cvt_pk_bf16_f32 v128, v232, v233
	v_cvt_pk_bf16_f32 v129, v234, v235
	v_cvt_pk_bf16_f32 v130, v156, v157
	v_cvt_pk_bf16_f32 v131, v158, v159
	v_pk_add_f32 v[154:155], v[158:159], v[154:155]
	v_pk_add_f32 v[152:153], v[156:157], v[152:153]
	v_mfma_f32_32x32x16_bf16 v[96:111], v[220:223], v[168:171], v[96:111]
	v_exp_f32_e32 v156, v132
	v_exp_f32_e32 v157, v133
	v_exp_f32_e32 v158, v134
	v_exp_f32_e32 v159, v135
	v_mfma_f32_32x32x16_bf16 v[112:127], v[148:151], v[172:175], v[112:127]
	v_exp_f32_e32 v216, v136
	v_exp_f32_e32 v217, v137
	v_exp_f32_e32 v218, v138
	v_exp_f32_e32 v219, v139
	v_pk_add_f32 v[138:139], v[188:189], v[154:155]
	v_pk_add_f32 v[136:137], v[186:187], v[152:153]
	v_cvt_pk_bf16_f32 v132, v186, v187
	v_cvt_pk_bf16_f32 v133, v188, v189
	v_cvt_pk_bf16_f32 v134, v156, v157
	v_cvt_pk_bf16_f32 v135, v158, v159
	v_pk_add_f32 v[150:151], v[158:159], v[138:139]
	v_pk_add_f32 v[148:149], v[156:157], v[136:137]
	v_mfma_f32_32x32x16_bf16 v[96:111], v[182:185], v[172:175], v[96:111]
	v_exp_f32_e32 v152, v140
	v_exp_f32_e32 v153, v141
	v_exp_f32_e32 v154, v142
	v_exp_f32_e32 v155, v143
	v_pk_add_f32 v[142:143], v[218:219], v[150:151]
	v_pk_add_f32 v[140:141], v[216:217], v[148:149]
	v_cvt_pk_bf16_f32 v136, v216, v217
	v_cvt_pk_bf16_f32 v137, v218, v219
	v_cvt_pk_bf16_f32 v138, v152, v153
	v_cvt_pk_bf16_f32 v139, v154, v155
	v_pk_add_f32 v[142:143], v[154:155], v[142:143]
	v_pk_add_f32 v[140:141], v[152:153], v[140:141]
	s_waitcnt vmcnt(4) lgkmcnt(0)
	v_add_f32_e32 v148, v176, v177
	v_add_f32_e32 v149, v178, v179
	v_add_f32_e32 v148, v148, v149
	v_add_f32_e32 v140, v140, v141
	v_add_f32_e32 v141, v142, v143
	s_barrier
	v_add_f32_e32 v148, v180, v148
	v_add_f32_e32 v140, v140, v141
	v_add_f32_e32 v180, v148, v140
	s_add_u32 s98, s98, 0x30000
	s_addc_u32 s99, s99, 0
	s_add_u32 s100, s100, 0x100
	s_addc_u32 s101, s101, 0
	s_add_i32 s47, s47, 12
	s_addk_i32 s41, 0x300
	s_add_i32 s46, s46, 0x30000
	s_cmp_lt_u32 s47, 50
	s_cbranch_scc1 .Lst1_u6_loop
	s_cmp_lt_u32 s47, 60
	s_cbranch_scc1 .Lst1_single
